# peel
# speedup vs baseline: 1.0227x; 1.0048x over previous
; #define STAGE_A(P, br, kt) do { const char* _base = (const char*)(((kt) < G.ksplit ? G.A1 : A2m) + (long)(br) * G.lda + (long)(kt) * BK); \
;     __builtin_amdgcn_global_load_lds((const unsigned*)(_base + aoff0), (unsigned*)((char*)(P) + sb0), 16, 0, 0); \
;     __builtin_amdgcn_global_load_lds((const unsigned*)(_base + aoff1), (unsigned*)((char*)(P) + sb1), 16, 0, 0); } while (0)
; #define STAGE_B(P, br, kt) do { const char* _base = (const char*)(G.Bt + (long)(br) * G.ldb + (long)(kt) * BK); \
;     __builtin_amdgcn_global_load_lds((const unsigned*)(_base + boff0), (unsigned*)((char*)(P) + sb0), 16, 0, 0); \
;     __builtin_amdgcn_global_load_lds((const unsigned*)(_base + boff1), (unsigned*)((char*)(P) + sb1), 16, 0, 0); } while (0)
; #define LDA(dst, b, h) for (int m = 0; m < 4; ++m) for (int k = 0; k < 2; ++k) \
;     dst[m][k] = *reinterpret_cast<const bf16x8*>(a_rd + ((b) * 2 + (h)) * (HT * 2) + m * 2048 + k * 1024)
; #define BAR __builtin_amdgcn_s_barrier()
;     ...
;   const int sb0 = t1 * 16, sb1 = sb0 + 8192;
;   const int swz_ = lds_byte(fr, fq * 8);
;   const char* a_rd = shmc + wr * 8192 + swz_;
;   const char* b_rd = shmc + 4 * (HT * 2) + wc * 4096 + swz_;
;   int r0_, c0_, r1_, c1_; stage_rc(sb0, r0_, c0_); stage_rc(sb1, r1_, c1_);
;   const unsigned aoff0 = (unsigned)(r0_ * G.lda + c0_) * 2u, aoff1 = (unsigned)(r1_ * G.lda + c1_) * 2u;
;   const unsigned boff0 = (unsigned)(r0_ * G.ldb + c0_) * 2u, boff1 = (unsigned)(r1_ * G.ldb + c1_) * 2u;
;   f32x4 acc[2][2][4][2] = {};
;   bf16x8 At[4][2], B0[2][2], B1[2][2];
;   const int nt = K / BK;
;   if (EPI == EPI_RESID || first) {
;     STAGE_B(SB(0, 0), bcol, 0); STAGE_A(SA(0, 0), brow, 0);
;     STAGE_B(SB(0, 1), bcol + HALF, 0); STAGE_A(SA(0, 1), brow + HALF, 0);
;   }
;   if (wr == 1) BAR;
;   WAIT_V(0); BAR;
;   STAGE_B(SB(1, 0), bcol, 1); STAGE_A(SA(1, 0), brow, 1); STAGE_B(SB(1, 1), bcol + HALF, 1);
;   WAIT_V(6); BAR;
;   for (int t = 0; t < nt - 2; t += 2) {
;     LDB(B0, 0, 0); SCHED; LDA(At, 0, 0); STAGE_A(SA(1, 1), brow + HALF, t + 1);
;     WAIT_L(8); BAR; WAIT_L(0); MMA(0, 0, At, B0); BAR; SCHED;
;     LDB(B1, 0, 1); STAGE_B(SB(0, 0), bcol, t + 2);
;     BAR; WAIT_L(0); MMA(0, 1, At, B1); BAR;
;     LDA(At, 0, 1); STAGE_A(SA(0, 0), brow, t + 2);
;     BAR; WAIT_L(0); MMA(1, 0, At, B0); BAR; SCHED;
;     STAGE_B(SB(0, 1), bcol + HALF, t + 2);
;     WAIT_V(6); BAR; MMA(1, 1, At, B1); BAR;
.LBB0_745:
	s_or_b64 exec, exec, s[10:11]
	v_and_b32_e32 v150, 15, v144
	v_lshlrev_b32_e32 v10, 2, v144
	s_ashr_i32 s9, s8, 31
	v_and_b32_e32 v8, 48, v144
	v_lshlrev_b32_e32 v9, 6, v150
	v_and_b32_e32 v10, 32, v10
	s_add_i32 s10, 32, 0x10000
	s_lshl_b32 s36, s52, 8
	s_lshl_b64 s[44:45], s[8:9], 1
	v_bitop3_b32 v10, v9, v10, v8 bitop3:0x36
	v_lshlrev_b32_e32 v8, 6, v144
	s_add_u32 s46, s49, s44
	v_readlane_b32 s9, v253, 46
	v_and_b32_e32 v8, 0x3000, v8
	s_addc_u32 s47, s50, s45
	v_add_u32_e32 v152, s9, v146
	v_add_u32_e32 v12, s10, v8
	v_lshl_add_u64 v[8:9], s[46:47], 0, v[180:181]
	s_mov_b64 vcc, 0x80
	v_readfirstlane_b32 s9, v152
	v_lshl_add_u64 v[8:9], v[8:9], 0, vcc
	s_mov_b32 m0, s9
	v_mov_b32_e32 v129, v181
	v_add_u32_e32 v153, 0x2000, v152
	s_add_u32 s42, s12, s42
	s_waitcnt vmcnt(0)
	s_barrier
	global_load_lds_dwordx4 v[8:9], off
	v_lshl_add_u64 v[8:9], s[46:47], 0, v[128:129]
	v_readfirstlane_b32 s9, v153
	s_addc_u32 s43, s13, s37
	s_or_b32 s37, s36, 0x80
	v_lshl_add_u64 v[8:9], v[8:9], 0, vcc
	s_mov_b32 m0, s9
	v_add_u32_e32 v154, 0x8000, v149
	s_mul_i32 s46, s37, 0x840
	global_load_lds_dwordx4 v[8:9], off
	v_lshl_add_u64 v[8:9], s[42:43], 0, v[180:181]
	v_readfirstlane_b32 s9, v154
	v_add_u32_e32 v156, 0xa000, v149
	s_ashr_i32 s47, s46, 31
	v_lshl_add_u64 v[8:9], v[8:9], 0, vcc
	s_mov_b32 m0, s9
	v_readfirstlane_b32 s9, v156
	s_lshl_b64 s[46:47], s[46:47], 1
	global_load_lds_dwordx4 v[8:9], off
	v_lshl_add_u64 v[8:9], s[42:43], 0, v[128:129]
	s_mov_b32 m0, s9
	s_add_u32 s46, s49, s46
	v_readlane_b32 s9, v253, 47
	v_lshl_add_u64 v[8:9], v[8:9], 0, vcc
	s_addc_u32 s47, s50, s47
	v_add_u32_e32 v157, s9, v146
	global_load_lds_dwordx4 v[8:9], off
	v_lshl_add_u64 v[8:9], s[46:47], 0, v[180:181]
	v_readfirstlane_b32 s9, v157
	v_lshl_add_u64 v[8:9], v[8:9], 0, vcc
	s_mov_b32 m0, s9
	v_add_u32_e32 v158, 0x2000, v157
	global_load_lds_dwordx4 v[8:9], off
	v_lshl_add_u64 v[8:9], s[46:47], 0, v[128:129]
	v_readfirstlane_b32 s9, v158
	v_lshl_add_u64 v[8:9], v[8:9], 0, vcc
	s_mov_b32 m0, s9
	s_movk_i32 s9, 0x840
	global_load_lds_dwordx4 v[8:9], off
	v_lshrrev_b32_e32 v8, 1, v0
	v_mul_lo_u32 v0, v2, s9
	v_mad_u64_u32 v[8:9], s[46:47], v8, s84, v[0:1]
	s_add_u32 s44, s14, s44
	v_or_b32_e32 v0, v8, v3
	s_addc_u32 s45, s15, s45
	s_add_i32 s8, s8, 0x40000
	v_add_lshl_u32 v2, v0, v4, 1
	v_lshrrev_b32_e32 v1, 1, v1
	v_mul_lo_u32 v0, v5, s9
	s_ashr_i32 s9, s8, 31
	v_mad_u64_u32 v[0:1], s[46:47], v1, s84, v[0:1]
	s_lshl_b64 s[8:9], s[8:9], 1
	v_or_b32_e32 v0, v0, v6
	s_add_u32 s8, s14, s8
	s_waitcnt vmcnt(6)
	v_add_lshl_u32 v0, v0, v7, 1
	v_mov_b32_e32 v1, v181
	s_addc_u32 s9, s15, s9
	v_lshl_add_u32 v11, v148, 13, 32
	v_mov_b32_e32 v3, v181
	v_lshl_add_u64 v[132:133], s[44:45], 0, v[0:1]
	v_lshl_add_u64 v[136:137], s[42:43], 0, v[0:1]
	v_lshl_add_u64 v[140:141], s[8:9], 0, v[0:1]
	v_lshl_add_u64 v[130:131], s[44:45], 0, v[2:3]
	v_lshl_add_u64 v[134:135], s[42:43], 0, v[2:3]
	v_lshl_add_u64 v[138:139], s[8:9], 0, v[2:3]
	s_mov_b32 s11, -2
	s_mov_b64 s[8:9], 0
	v_add_u32_e32 v155, v12, v10
	v_add_u32_e32 v151, v11, v10
	s_waitcnt vmcnt(0)
	s_mov_b64 s[44:45], 0x84080
	s_mov_b64 s[46:47], 0x4360100
	s_mov_b64 vcc, 0x4364100
	s_mov_b64 s[64:65], 0x84100
	s_mov_b64 s[22:23], 0x4360180
	s_mov_b64 s[24:25], 0x4364180
	s_barrier
	ds_read_b128 v[164:167], v155
	ds_read_b128 v[168:171], v155 offset:1024
	ds_read_b128 v[172:175], v155 offset:2048
	ds_read_b128 v[176:179], v155 offset:3072
	v_add_u32_e32 v162, 0xc000, v149
	v_lshl_add_u64 v[222:223], v[134:135], 0, s[8:9]
	v_readfirstlane_b32 s42, v162
	v_add_u32_e32 v163, 0xe000, v149
	v_lshl_add_u64 v[160:161], v[222:223], 0, s[44:45]
	s_mov_b32 m0, s42
	v_lshl_add_u64 v[234:235], v[136:137], 0, s[8:9]
	v_readfirstlane_b32 s42, v163
	ds_read_b128 v[182:185], v151
	ds_read_b128 v[186:189], v151 offset:1024
	ds_read_b128 v[190:193], v151 offset:2048
	ds_read_b128 v[194:197], v151 offset:3072
	ds_read_b128 v[198:201], v151 offset:4096
	ds_read_b128 v[202:205], v151 offset:5120
	ds_read_b128 v[206:209], v151 offset:6144
	ds_read_b128 v[210:213], v151 offset:7168
	global_load_lds_dwordx4 v[160:161], off
	v_lshl_add_u64 v[160:161], v[234:235], 0, s[44:45]
	s_mov_b32 m0, s42
	s_nop 0
	global_load_lds_dwordx4 v[160:161], off
	ds_read_b128 v[214:217], v155 offset:16384
	ds_read_b128 v[218:221], v155 offset:17408
	ds_read_b128 v[230:233], v155 offset:18432
	ds_read_b128 v[238:241], v155 offset:19456
	s_waitcnt lgkmcnt(0)
	s_waitcnt vmcnt(8)
	s_barrier
	s_setprio 1
	v_mfma_f32_16x16x32_bf16 v[124:127], v[164:167], v[182:185], 0
	v_mfma_f32_16x16x32_bf16 v[120:123], v[172:175], v[182:185], 0
	v_mfma_f32_16x16x32_bf16 v[116:119], v[164:167], v[190:193], 0
	v_mfma_f32_16x16x32_bf16 v[112:115], v[172:175], v[190:193], 0
	v_mfma_f32_16x16x32_bf16 v[108:111], v[164:167], v[198:201], 0
	v_mfma_f32_16x16x32_bf16 v[104:107], v[172:175], v[198:201], 0
	v_mfma_f32_16x16x32_bf16 v[100:103], v[164:167], v[206:209], 0
	v_mfma_f32_16x16x32_bf16 v[96:99], v[172:175], v[206:209], 0
	v_mfma_f32_16x16x32_bf16 v[124:127], v[168:171], v[186:189], v[124:127]
	v_mfma_f32_16x16x32_bf16 v[120:123], v[176:179], v[186:189], v[120:123]
	v_mfma_f32_16x16x32_bf16 v[116:119], v[168:171], v[194:197], v[116:119]
	v_mfma_f32_16x16x32_bf16 v[112:115], v[176:179], v[194:197], v[112:115]
	v_mfma_f32_16x16x32_bf16 v[108:111], v[168:171], v[202:205], v[108:111]
	v_mfma_f32_16x16x32_bf16 v[104:107], v[176:179], v[202:205], v[104:107]
	v_mfma_f32_16x16x32_bf16 v[100:103], v[168:171], v[210:213], v[100:103]
	v_mfma_f32_16x16x32_bf16 v[96:99], v[176:179], v[210:213], v[96:99]
	v_mfma_f32_16x16x32_bf16 v[92:95], v[214:217], v[182:185], 0
	v_mfma_f32_16x16x32_bf16 v[88:91], v[230:233], v[182:185], 0
	v_mfma_f32_16x16x32_bf16 v[84:87], v[214:217], v[190:193], 0
	v_mfma_f32_16x16x32_bf16 v[80:83], v[230:233], v[190:193], 0
	v_mfma_f32_16x16x32_bf16 v[76:79], v[214:217], v[198:201], 0
	v_mfma_f32_16x16x32_bf16 v[72:75], v[230:233], v[198:201], 0
	v_mfma_f32_16x16x32_bf16 v[68:71], v[214:217], v[206:209], 0
	v_mfma_f32_16x16x32_bf16 v[64:67], v[230:233], v[206:209], 0
	v_mfma_f32_16x16x32_bf16 v[92:95], v[218:221], v[186:189], v[92:95]
	v_mfma_f32_16x16x32_bf16 v[88:91], v[238:241], v[186:189], v[88:91]
	v_mfma_f32_16x16x32_bf16 v[84:87], v[218:221], v[194:197], v[84:87]
	v_mfma_f32_16x16x32_bf16 v[80:83], v[238:241], v[194:197], v[80:83]
	v_mfma_f32_16x16x32_bf16 v[76:79], v[218:221], v[202:205], v[76:79]
	v_mfma_f32_16x16x32_bf16 v[72:75], v[238:241], v[202:205], v[72:75]
	s_setprio 2
	s_barrier
; #define STAGE_A(P, br, kt) do { const char* _base = (const char*)(((kt) < G.ksplit ? G.A1 : A2m) + (long)(br) * G.lda + (long)(kt) * BK); \
;     __builtin_amdgcn_global_load_lds((const unsigned*)(_base + aoff0), (unsigned*)((char*)(P) + sb0), 16, 0, 0); \
;     __builtin_amdgcn_global_load_lds((const unsigned*)(_base + aoff1), (unsigned*)((char*)(P) + sb1), 16, 0, 0); } while (0)
; #define STAGE_B(P, br, kt) do { const char* _base = (const char*)(G.Bt + (long)(br) * G.ldb + (long)(kt) * BK); \
;     __builtin_amdgcn_global_load_lds((const unsigned*)(_base + boff0), (unsigned*)((char*)(P) + sb0), 16, 0, 0); \
;     __builtin_amdgcn_global_load_lds((const unsigned*)(_base + boff1), (unsigned*)((char*)(P) + sb1), 16, 0, 0); } while (0)
; #define LDA(dst, b, h) for (int m = 0; m < 4; ++m) for (int k = 0; k < 2; ++k) \
;     dst[m][k] = *reinterpret_cast<const bf16x8*>(a_rd + ((b) * 2 + (h)) * (HT * 2) + m * 2048 + k * 1024)
; #define LDB(dst, b, h) for (int n = 0; n < 2; ++n) for (int k = 0; k < 2; ++k) \
;     dst[n][k] = *reinterpret_cast<const bf16x8*>(b_rd + ((b) * 2 + (h)) * (HT * 2) + n * 2048 + k * 1024)
; #define MMA(ai, bj, At_, Bt_) do { __builtin_amdgcn_s_setprio(1); \
;     for (int m = 0; m < 4; ++m) for (int n = 0; n < 2; ++n) for (int k = 0; k < 2; ++k) \
;       acc[ai][bj][m][n] = __builtin_amdgcn_mfma_f32_16x16x32_bf16(Bt_[n][k], At_[m][k], acc[ai][bj][m][n], 0, 0, 0); \
;     __builtin_amdgcn_s_setprio(0); } while (0)
; #define WAIT_V(n) asm volatile("s_waitcnt vmcnt(" #n ")" ::: "memory")
; #define WAIT_L(n) asm volatile("s_waitcnt lgkmcnt(" #n ")" ::: "memory")
; #define BAR __builtin_amdgcn_s_barrier()
; #define SCHED __builtin_amdgcn_sched_barrier(0)
;     ...
;     LDB(B0, 0, 0); SCHED; LDA(At, 0, 0); STAGE_A(SA(1, 1), brow + HALF, t + 1);
;     WAIT_L(8); BAR; WAIT_L(0); MMA(0, 0, At, B0); BAR; SCHED;
;     LDB(B1, 0, 1); STAGE_B(SB(0, 0), bcol, t + 2);
;     BAR; WAIT_L(0); MMA(0, 1, At, B1); BAR;
;     LDA(At, 0, 1); STAGE_A(SA(0, 0), brow, t + 2);
;     BAR; WAIT_L(0); MMA(1, 0, At, B0); BAR; SCHED;
;     STAGE_B(SB(0, 1), bcol + HALF, t + 2);
;     WAIT_V(6); BAR; MMA(1, 1, At, B1); BAR;
;     LDB(B0, 1, 0); SCHED; LDA(At, 1, 0); STAGE_A(SA(0, 1), brow + HALF, t + 2);
;     WAIT_L(8); BAR; WAIT_L(0); MMA(0, 0, At, B0); BAR; SCHED;
;     LDB(B1, 1, 1); STAGE_B(SB(1, 0), bcol, t + 3);
	v_mfma_f32_16x16x32_bf16 v[68:71], v[218:221], v[210:213], v[68:71]
	v_mfma_f32_16x16x32_bf16 v[64:67], v[238:241], v[210:213], v[64:67]
	s_setprio 0
	v_add_u32_e32 v159, s10, v146
	v_lshl_add_u64 v[236:237], v[130:131], 0, s[8:9]
	v_readfirstlane_b32 s42, v159
	v_lshl_add_u64 v[160:161], v[236:237], 0, s[46:47]
	s_mov_b32 m0, s42
	global_load_lds_dwordx4 v[160:161], off
	v_add_u32_e32 v160, 0x2000, v159
	v_lshl_add_u64 v[246:247], v[132:133], 0, s[8:9]
	v_readfirstlane_b32 s42, v160
	v_lshl_add_u64 v[248:249], v[246:247], 0, s[46:47]
	s_mov_b32 m0, s42
	s_nop 0
	global_load_lds_dwordx4 v[248:249], off
	v_readfirstlane_b32 s42, v149
	v_lshl_add_u64 v[248:249], v[222:223], 0, s[90:91]
	s_mov_b32 m0, s42
	v_readfirstlane_b32 s42, v147
	ds_read_b128 v[182:185], v151 offset:16384
	ds_read_b128 v[186:189], v151 offset:17408
	ds_read_b128 v[190:193], v151 offset:18432
	ds_read_b128 v[194:197], v151 offset:19456
	ds_read_b128 v[198:201], v151 offset:20480
	ds_read_b128 v[202:205], v151 offset:21504
	ds_read_b128 v[206:209], v151 offset:22528
	ds_read_b128 v[210:213], v151 offset:23552
	global_load_lds_dwordx4 v[248:249], off
	v_lshl_add_u64 v[248:249], v[234:235], 0, s[90:91]
	s_mov_b32 m0, s42
	s_nop 0
	global_load_lds_dwordx4 v[248:249], off
	v_lshl_add_u64 v[248:249], v[138:139], 0, s[8:9]
	v_readfirstlane_b32 s42, v145
	v_add_u32_e32 v161, 0x2000, v145
	v_lshl_add_u64 v[250:251], v[248:249], 0, vcc
	s_mov_b32 m0, s42
	v_lshl_add_u64 v[226:227], v[140:141], 0, s[8:9]
	v_readfirstlane_b32 s42, v161
	global_load_lds_dwordx4 v[250:251], off
	v_lshl_add_u64 v[250:251], v[226:227], 0, vcc
	s_mov_b32 m0, s42
	s_nop 0
	global_load_lds_dwordx4 v[250:251], off
	s_waitcnt lgkmcnt(0)
	s_waitcnt vmcnt(8)
	s_barrier
	s_setprio 1
	v_mfma_f32_16x16x32_bf16 v[60:63], v[164:167], v[182:185], 0
	v_mfma_f32_16x16x32_bf16 v[56:59], v[172:175], v[182:185], 0
	v_mfma_f32_16x16x32_bf16 v[52:55], v[164:167], v[190:193], 0
	v_mfma_f32_16x16x32_bf16 v[48:51], v[172:175], v[190:193], 0
	v_mfma_f32_16x16x32_bf16 v[44:47], v[164:167], v[198:201], 0
	v_mfma_f32_16x16x32_bf16 v[40:43], v[172:175], v[198:201], 0
	v_mfma_f32_16x16x32_bf16 v[36:39], v[164:167], v[206:209], 0
	v_mfma_f32_16x16x32_bf16 v[32:35], v[172:175], v[206:209], 0
	v_mfma_f32_16x16x32_bf16 v[60:63], v[168:171], v[186:189], v[60:63]
	v_mfma_f32_16x16x32_bf16 v[56:59], v[176:179], v[186:189], v[56:59]
	v_mfma_f32_16x16x32_bf16 v[52:55], v[168:171], v[194:197], v[52:55]
	v_mfma_f32_16x16x32_bf16 v[48:51], v[176:179], v[194:197], v[48:51]
	v_mfma_f32_16x16x32_bf16 v[44:47], v[168:171], v[202:205], v[44:47]
	v_mfma_f32_16x16x32_bf16 v[40:43], v[176:179], v[202:205], v[40:43]
	v_mfma_f32_16x16x32_bf16 v[36:39], v[168:171], v[210:213], v[36:39]
	v_mfma_f32_16x16x32_bf16 v[32:35], v[176:179], v[210:213], v[32:35]
	v_mfma_f32_16x16x32_bf16 v[28:31], v[214:217], v[182:185], 0
	v_mfma_f32_16x16x32_bf16 v[24:27], v[230:233], v[182:185], 0
	v_mfma_f32_16x16x32_bf16 v[20:23], v[214:217], v[190:193], 0
	v_mfma_f32_16x16x32_bf16 v[16:19], v[230:233], v[190:193], 0
	v_mfma_f32_16x16x32_bf16 v[12:15], v[214:217], v[198:201], 0
	v_mfma_f32_16x16x32_bf16 v[8:11], v[230:233], v[198:201], 0
	v_mfma_f32_16x16x32_bf16 v[4:7], v[214:217], v[206:209], 0
	v_mfma_f32_16x16x32_bf16 v[0:3], v[230:233], v[206:209], 0
	v_mfma_f32_16x16x32_bf16 v[28:31], v[218:221], v[186:189], v[28:31]
	v_mfma_f32_16x16x32_bf16 v[24:27], v[238:241], v[186:189], v[24:27]
	v_mfma_f32_16x16x32_bf16 v[20:23], v[218:221], v[194:197], v[20:23]
	v_mfma_f32_16x16x32_bf16 v[16:19], v[238:241], v[194:197], v[16:19]
	v_mfma_f32_16x16x32_bf16 v[12:15], v[218:221], v[202:205], v[12:15]
	v_mfma_f32_16x16x32_bf16 v[8:11], v[238:241], v[202:205], v[8:11]
	s_setprio 2
	s_barrier
	v_mfma_f32_16x16x32_bf16 v[4:7], v[218:221], v[210:213], v[4:7]
	v_mfma_f32_16x16x32_bf16 v[0:3], v[238:241], v[210:213], v[0:3]
	s_setprio 0
	ds_read_b128 v[164:167], v155 offset:32768
	ds_read_b128 v[168:171], v155 offset:33792
	ds_read_b128 v[172:175], v155 offset:34816
	ds_read_b128 v[176:179], v155 offset:35840
	v_readfirstlane_b32 s42, v143
	v_lshl_add_u64 v[214:215], v[222:223], 0, s[64:65]
	s_mov_b32 m0, s42
	v_readfirstlane_b32 s42, v142
	ds_read_b128 v[182:185], v151 offset:32768
	ds_read_b128 v[186:189], v151 offset:33792
	ds_read_b128 v[190:193], v151 offset:34816
	ds_read_b128 v[194:197], v151 offset:35840
	ds_read_b128 v[198:201], v151 offset:36864
	ds_read_b128 v[202:205], v151 offset:37888
	ds_read_b128 v[206:209], v151 offset:38912
	ds_read_b128 v[210:213], v151 offset:39936
	global_load_lds_dwordx4 v[214:215], off
	v_lshl_add_u64 v[214:215], v[234:235], 0, s[64:65]
	s_mov_b32 m0, s42
	s_nop 0
	global_load_lds_dwordx4 v[214:215], off
	ds_read_b128 v[214:217], v155 offset:49152
	ds_read_b128 v[218:221], v155 offset:50176
	ds_read_b128 v[230:233], v155 offset:51200
	ds_read_b128 v[238:241], v155 offset:52224
	s_waitcnt lgkmcnt(0)
	s_waitcnt vmcnt(8)
	s_barrier
; #define STAGE_A(P, br, kt) do { const char* _base = (const char*)(((kt) < G.ksplit ? G.A1 : A2m) + (long)(br) * G.lda + (long)(kt) * BK); \
;     __builtin_amdgcn_global_load_lds((const unsigned*)(_base + aoff0), (unsigned*)((char*)(P) + sb0), 16, 0, 0); \
;     __builtin_amdgcn_global_load_lds((const unsigned*)(_base + aoff1), (unsigned*)((char*)(P) + sb1), 16, 0, 0); } while (0)
; #define STAGE_B(P, br, kt) do { const char* _base = (const char*)(G.Bt + (long)(br) * G.ldb + (long)(kt) * BK); \
;     __builtin_amdgcn_global_load_lds((const unsigned*)(_base + boff0), (unsigned*)((char*)(P) + sb0), 16, 0, 0); \
;     __builtin_amdgcn_global_load_lds((const unsigned*)(_base + boff1), (unsigned*)((char*)(P) + sb1), 16, 0, 0); } while (0)
; #define LDA(dst, b, h) for (int m = 0; m < 4; ++m) for (int k = 0; k < 2; ++k) \
;     dst[m][k] = *reinterpret_cast<const bf16x8*>(a_rd + ((b) * 2 + (h)) * (HT * 2) + m * 2048 + k * 1024)
; #define LDB(dst, b, h) for (int n = 0; n < 2; ++n) for (int k = 0; k < 2; ++k) \
;     dst[n][k] = *reinterpret_cast<const bf16x8*>(b_rd + ((b) * 2 + (h)) * (HT * 2) + n * 2048 + k * 1024)
; #define MMA(ai, bj, At_, Bt_) do { __builtin_amdgcn_s_setprio(1); \
;     for (int m = 0; m < 4; ++m) for (int n = 0; n < 2; ++n) for (int k = 0; k < 2; ++k) \
;       acc[ai][bj][m][n] = __builtin_amdgcn_mfma_f32_16x16x32_bf16(Bt_[n][k], At_[m][k], acc[ai][bj][m][n], 0, 0, 0); \
;     __builtin_amdgcn_s_setprio(0); } while (0)
; #define WAIT_V(n) asm volatile("s_waitcnt vmcnt(" #n ")" ::: "memory")
; #define WAIT_L(n) asm volatile("s_waitcnt lgkmcnt(" #n ")" ::: "memory")
; #define BAR __builtin_amdgcn_s_barrier()
; #define SCHED __builtin_amdgcn_sched_barrier(0)
;     ...
;     LDB(B0, 1, 0); SCHED; LDA(At, 1, 0); STAGE_A(SA(0, 1), brow + HALF, t + 2);
;     WAIT_L(8); BAR; WAIT_L(0); MMA(0, 0, At, B0); BAR; SCHED;
;     LDB(B1, 1, 1); STAGE_B(SB(1, 0), bcol, t + 3);
;     BAR; WAIT_L(0); MMA(0, 1, At, B1); BAR;
;     LDA(At, 1, 1); STAGE_A(SA(1, 0), brow, t + 3);
;     BAR; WAIT_L(0); MMA(1, 0, At, B0); BAR; SCHED;
;     STAGE_B(SB(1, 1), bcol + HALF, t + 3);
;     WAIT_V(6); BAR; MMA(1, 1, At, B1); BAR;
;   }
	s_setprio 1
	v_mfma_f32_16x16x32_bf16 v[124:127], v[164:167], v[182:185], v[124:127]
	v_mfma_f32_16x16x32_bf16 v[120:123], v[172:175], v[182:185], v[120:123]
	v_mfma_f32_16x16x32_bf16 v[116:119], v[164:167], v[190:193], v[116:119]
	v_mfma_f32_16x16x32_bf16 v[112:115], v[172:175], v[190:193], v[112:115]
	v_mfma_f32_16x16x32_bf16 v[108:111], v[164:167], v[198:201], v[108:111]
	v_mfma_f32_16x16x32_bf16 v[104:107], v[172:175], v[198:201], v[104:107]
	v_mfma_f32_16x16x32_bf16 v[100:103], v[164:167], v[206:209], v[100:103]
	v_mfma_f32_16x16x32_bf16 v[96:99], v[172:175], v[206:209], v[96:99]
	v_mfma_f32_16x16x32_bf16 v[124:127], v[168:171], v[186:189], v[124:127]
	v_mfma_f32_16x16x32_bf16 v[120:123], v[176:179], v[186:189], v[120:123]
	v_mfma_f32_16x16x32_bf16 v[116:119], v[168:171], v[194:197], v[116:119]
	v_mfma_f32_16x16x32_bf16 v[112:115], v[176:179], v[194:197], v[112:115]
	v_mfma_f32_16x16x32_bf16 v[108:111], v[168:171], v[202:205], v[108:111]
	v_mfma_f32_16x16x32_bf16 v[104:107], v[176:179], v[202:205], v[104:107]
	v_mfma_f32_16x16x32_bf16 v[100:103], v[168:171], v[210:213], v[100:103]
	v_mfma_f32_16x16x32_bf16 v[96:99], v[176:179], v[210:213], v[96:99]
	v_mfma_f32_16x16x32_bf16 v[92:95], v[214:217], v[182:185], v[92:95]
	v_mfma_f32_16x16x32_bf16 v[88:91], v[230:233], v[182:185], v[88:91]
	v_mfma_f32_16x16x32_bf16 v[84:87], v[214:217], v[190:193], v[84:87]
	v_mfma_f32_16x16x32_bf16 v[80:83], v[230:233], v[190:193], v[80:83]
	v_mfma_f32_16x16x32_bf16 v[76:79], v[214:217], v[198:201], v[76:79]
	v_mfma_f32_16x16x32_bf16 v[72:75], v[230:233], v[198:201], v[72:75]
	v_mfma_f32_16x16x32_bf16 v[68:71], v[214:217], v[206:209], v[68:71]
	v_mfma_f32_16x16x32_bf16 v[64:67], v[230:233], v[206:209], v[64:67]
	v_mfma_f32_16x16x32_bf16 v[92:95], v[218:221], v[186:189], v[92:95]
	v_mfma_f32_16x16x32_bf16 v[88:91], v[238:241], v[186:189], v[88:91]
	v_mfma_f32_16x16x32_bf16 v[84:87], v[218:221], v[194:197], v[84:87]
	v_mfma_f32_16x16x32_bf16 v[80:83], v[238:241], v[194:197], v[80:83]
	v_mfma_f32_16x16x32_bf16 v[76:79], v[218:221], v[202:205], v[76:79]
	v_mfma_f32_16x16x32_bf16 v[72:75], v[238:241], v[202:205], v[72:75]
	s_setprio 2
	s_barrier
	v_mfma_f32_16x16x32_bf16 v[68:71], v[218:221], v[210:213], v[68:71]
	v_mfma_f32_16x16x32_bf16 v[64:67], v[238:241], v[210:213], v[64:67]
	s_setprio 0
	v_readfirstlane_b32 s42, v152
	v_lshl_add_u64 v[236:237], v[236:237], 0, s[22:23]
	s_mov_b32 m0, s42
	v_readfirstlane_b32 s42, v153
	global_load_lds_dwordx4 v[236:237], off
	v_lshl_add_u64 v[236:237], v[246:247], 0, s[22:23]
	s_mov_b32 m0, s42
	s_nop 0
	global_load_lds_dwordx4 v[236:237], off
	v_readfirstlane_b32 s42, v154
	v_lshl_add_u64 v[222:223], v[222:223], 0, s[88:89]
	s_mov_b32 m0, s42
	v_readfirstlane_b32 s42, v156
	ds_read_b128 v[182:185], v151 offset:49152
	ds_read_b128 v[186:189], v151 offset:50176
	ds_read_b128 v[190:193], v151 offset:51200
	ds_read_b128 v[194:197], v151 offset:52224
	ds_read_b128 v[198:201], v151 offset:53248
	ds_read_b128 v[202:205], v151 offset:54272
	ds_read_b128 v[206:209], v151 offset:55296
	ds_read_b128 v[210:213], v151 offset:56320
	global_load_lds_dwordx4 v[222:223], off
	v_lshl_add_u64 v[222:223], v[234:235], 0, s[88:89]
	s_mov_b32 m0, s42
	s_nop 0
	global_load_lds_dwordx4 v[222:223], off
	v_readfirstlane_b32 s42, v157
	v_lshl_add_u64 v[250:251], v[248:249], 0, s[24:25]
	s_mov_b32 m0, s42
	v_readfirstlane_b32 s42, v158
	global_load_lds_dwordx4 v[250:251], off
	v_lshl_add_u64 v[250:251], v[226:227], 0, s[24:25]
	s_mov_b32 m0, s42
	s_nop 0
	global_load_lds_dwordx4 v[250:251], off
	s_waitcnt lgkmcnt(0)
	s_waitcnt vmcnt(8)
	s_barrier
	s_setprio 1
	v_mfma_f32_16x16x32_bf16 v[60:63], v[164:167], v[182:185], v[60:63]
	v_mfma_f32_16x16x32_bf16 v[56:59], v[172:175], v[182:185], v[56:59]
	v_mfma_f32_16x16x32_bf16 v[52:55], v[164:167], v[190:193], v[52:55]
	v_mfma_f32_16x16x32_bf16 v[48:51], v[172:175], v[190:193], v[48:51]
	v_mfma_f32_16x16x32_bf16 v[44:47], v[164:167], v[198:201], v[44:47]
	v_mfma_f32_16x16x32_bf16 v[40:43], v[172:175], v[198:201], v[40:43]
	v_mfma_f32_16x16x32_bf16 v[36:39], v[164:167], v[206:209], v[36:39]
	v_mfma_f32_16x16x32_bf16 v[32:35], v[172:175], v[206:209], v[32:35]
	v_mfma_f32_16x16x32_bf16 v[60:63], v[168:171], v[186:189], v[60:63]
	v_mfma_f32_16x16x32_bf16 v[56:59], v[176:179], v[186:189], v[56:59]
	v_mfma_f32_16x16x32_bf16 v[52:55], v[168:171], v[194:197], v[52:55]
	v_mfma_f32_16x16x32_bf16 v[48:51], v[176:179], v[194:197], v[48:51]
	v_mfma_f32_16x16x32_bf16 v[44:47], v[168:171], v[202:205], v[44:47]
	v_mfma_f32_16x16x32_bf16 v[40:43], v[176:179], v[202:205], v[40:43]
	v_mfma_f32_16x16x32_bf16 v[36:39], v[168:171], v[210:213], v[36:39]
	v_mfma_f32_16x16x32_bf16 v[32:35], v[176:179], v[210:213], v[32:35]
	v_mfma_f32_16x16x32_bf16 v[28:31], v[214:217], v[182:185], v[28:31]
	v_mfma_f32_16x16x32_bf16 v[24:27], v[230:233], v[182:185], v[24:27]
	v_mfma_f32_16x16x32_bf16 v[20:23], v[214:217], v[190:193], v[20:23]
	v_mfma_f32_16x16x32_bf16 v[16:19], v[230:233], v[190:193], v[16:19]
	v_mfma_f32_16x16x32_bf16 v[12:15], v[214:217], v[198:201], v[12:15]
	v_mfma_f32_16x16x32_bf16 v[8:11], v[230:233], v[198:201], v[8:11]
	v_mfma_f32_16x16x32_bf16 v[4:7], v[214:217], v[206:209], v[4:7]
	v_mfma_f32_16x16x32_bf16 v[0:3], v[230:233], v[206:209], v[0:3]
	v_mfma_f32_16x16x32_bf16 v[28:31], v[218:221], v[186:189], v[28:31]
	v_mfma_f32_16x16x32_bf16 v[24:27], v[238:241], v[186:189], v[24:27]
	v_mfma_f32_16x16x32_bf16 v[20:23], v[218:221], v[194:197], v[20:23]
	v_mfma_f32_16x16x32_bf16 v[16:19], v[238:241], v[194:197], v[16:19]
	v_mfma_f32_16x16x32_bf16 v[12:15], v[218:221], v[202:205], v[12:15]
	v_mfma_f32_16x16x32_bf16 v[8:11], v[238:241], v[202:205], v[8:11]
	s_setprio 2
	s_barrier
	v_mfma_f32_16x16x32_bf16 v[4:7], v[218:221], v[210:213], v[4:7]
	v_mfma_f32_16x16x32_bf16 v[0:3], v[238:241], v[210:213], v[0:3]
	s_setprio 0
	s_add_i32 s11, s11, 2
	s_add_u32 s8, s8, 0x100
	s_addc_u32 s9, s9, 0
	s_cmp_lt_u32 s11, 28
	s_cbranch_scc0 .Lmy_kexit_0

; #define STAGE_A(P, br, kt) do { const char* _base = (const char*)(((kt) < G.ksplit ? G.A1 : A2m) + (long)(br) * G.lda + (long)(kt) * BK); \
;     __builtin_amdgcn_global_load_lds((const unsigned*)(_base + aoff0), (unsigned*)((char*)(P) + sb0), 16, 0, 0); \
;     __builtin_amdgcn_global_load_lds((const unsigned*)(_base + aoff1), (unsigned*)((char*)(P) + sb1), 16, 0, 0); } while (0)
; #define LDA(dst, b, h) for (int m = 0; m < 4; ++m) for (int k = 0; k < 2; ++k) \
;     dst[m][k] = *reinterpret_cast<const bf16x8*>(a_rd + ((b) * 2 + (h)) * (HT * 2) + m * 2048 + k * 1024)
; #define LDB(dst, b, h) for (int n = 0; n < 2; ++n) for (int k = 0; k < 2; ++k) \
;     dst[n][k] = *reinterpret_cast<const bf16x8*>(b_rd + ((b) * 2 + (h)) * (HT * 2) + n * 2048 + k * 1024)
; #define MMA(ai, bj, At_, Bt_) do { __builtin_amdgcn_s_setprio(1); \
;     for (int m = 0; m < 4; ++m) for (int n = 0; n < 2; ++n) for (int k = 0; k < 2; ++k) \
;       acc[ai][bj][m][n] = __builtin_amdgcn_mfma_f32_16x16x32_bf16(Bt_[n][k], At_[m][k], acc[ai][bj][m][n], 0, 0, 0); \
;     __builtin_amdgcn_s_setprio(0); } while (0)
; #define WAIT_V(n) asm volatile("s_waitcnt vmcnt(" #n ")" ::: "memory")
; #define WAIT_L(n) asm volatile("s_waitcnt lgkmcnt(" #n ")" ::: "memory")
; #define BAR __builtin_amdgcn_s_barrier()
;     ...
;   float ssv[2][4] = {};
;   if constexpr (EPI == EPI_GU || EPI == EPI_EVIN || EPI == EPI_ODIN) {
; #pragma unroll
;     for (int ai = 0; ai < 2; ++ai)
; #pragma unroll
;       for (int m = 0; m < 4; ++m) ssv[ai][m] = G.ssr[brow + ai * HALF + wr * 64 + m * 16 + fr];
;   }
;   { LDB(B0, 0, 0); LDA(At, 0, 0); STAGE_A(SA(1, 1), brow + HALF, nt - 1);
;     BAR; WAIT_L(0); MMA(0, 0, At, B0); BAR;
;     LDB(B1, 0, 1); BAR; WAIT_L(0); MMA(0, 1, At, B1); BAR;
;     LDA(At, 0, 1); WAIT_V(4); BAR; WAIT_L(0); MMA(1, 0, At, B0); MMA(1, 1, At, B1); BAR; }
;   { LDB(B0, 1, 0); LDA(At, 1, 0); WAIT_V(2); BAR; WAIT_L(0); MMA(0, 0, At, B0); BAR;
.Lmy_kexit_0:
	s_waitcnt vmcnt(6)
	v_not_b32_e32 v250, 63
	v_mov_b32_e32 v251, 0x41b17218
	v_or_b32_e32 v130, s40, v150
	v_lshl_add_u32 v130, v148, 6, v130
	v_ashrrev_i32_e32 v131, 31, v130
	v_lshl_add_u64 v[132:133], v[130:131], 2, s[30:31]
	v_add_u32_e32 v134, 0x80, v130
	v_add_u32_e32 v136, 0x90, v130
	v_add_u32_e32 v138, 0xa0, v130
	v_add_u32_e32 v130, 0xb0, v130
	s_or_b32 s57, s40, 0x80
	v_ashrrev_i32_e32 v135, 31, v134
	v_ashrrev_i32_e32 v137, 31, v136
	v_ashrrev_i32_e32 v139, 31, v138
	v_ashrrev_i32_e32 v131, 31, v130
	s_mul_i32 s8, s57, 0x1080
	v_lshl_add_u64 v[134:135], v[134:135], 2, s[30:31]
	v_lshl_add_u64 v[136:137], v[136:137], 2, s[30:31]
	v_lshl_add_u64 v[138:139], v[138:139], 2, s[30:31]
	v_lshl_add_u64 v[140:141], v[130:131], 2, s[30:31]
	global_load_dword v130, v[132:133], off
	global_load_dword v146, v[132:133], off offset:64
	global_load_dword v148, v[132:133], off offset:128
	global_load_dword v156, v[132:133], off offset:192
	global_load_dword v154, v[134:135], off
	global_load_dword v153, v[136:137], off
	global_load_dword v152, v[138:139], off
	global_load_dword v150, v[140:141], off
	s_mul_hi_i32 s9, s57, 0x1080
	s_add_u32 s8, s12, s8
	s_addc_u32 s9, s13, s9
	v_lshl_add_u64 v[140:141], s[8:9], 0, v[180:181]
	s_mov_b64 s[22:23], 0xf80
	v_readfirstlane_b32 s10, v162
	v_lshl_add_u64 v[140:141], v[140:141], 0, s[22:23]
	s_mov_b32 m0, s10
	ds_read_b128 v[132:135], v155
	ds_read_b128 v[136:139], v155 offset:1024
	ds_read_b128 v[164:167], v155 offset:2048
	ds_read_b128 v[168:171], v155 offset:3072
	ds_read_b128 v[172:175], v151
	ds_read_b128 v[176:179], v151 offset:1024
	ds_read_b128 v[182:185], v151 offset:2048
	ds_read_b128 v[186:189], v151 offset:3072
	ds_read_b128 v[190:193], v151 offset:4096
	ds_read_b128 v[194:197], v151 offset:5120
	ds_read_b128 v[198:201], v151 offset:6144
	ds_read_b128 v[202:205], v151 offset:7168
	global_load_lds_dwordx4 v[140:141], off
	v_lshl_add_u64 v[140:141], s[8:9], 0, v[128:129]
	v_readfirstlane_b32 s8, v163
	v_lshl_add_u64 v[140:141], v[140:141], 0, s[22:23]
	s_mov_b32 m0, s8
	s_nop 0
	global_load_lds_dwordx4 v[140:141], off
	s_barrier
	s_waitcnt lgkmcnt(0)
	s_setprio 1
	s_waitcnt lgkmcnt(0)
	v_mfma_f32_16x16x32_bf16 v[124:127], v[132:135], v[172:175], v[124:127]
	v_mfma_f32_16x16x32_bf16 v[120:123], v[164:167], v[172:175], v[120:123]
	v_mfma_f32_16x16x32_bf16 v[116:119], v[132:135], v[182:185], v[116:119]
	v_mfma_f32_16x16x32_bf16 v[112:115], v[164:167], v[182:185], v[112:115]
	v_mfma_f32_16x16x32_bf16 v[108:111], v[132:135], v[190:193], v[108:111]
	v_mfma_f32_16x16x32_bf16 v[104:107], v[164:167], v[190:193], v[104:107]
	v_mfma_f32_16x16x32_bf16 v[100:103], v[132:135], v[198:201], v[100:103]
	v_mfma_f32_16x16x32_bf16 v[96:99], v[164:167], v[198:201], v[96:99]
	v_mfma_f32_16x16x32_bf16 v[124:127], v[136:139], v[176:179], v[124:127]
	v_mfma_f32_16x16x32_bf16 v[120:123], v[168:171], v[176:179], v[120:123]
	v_mfma_f32_16x16x32_bf16 v[116:119], v[136:139], v[186:189], v[116:119]
	v_mfma_f32_16x16x32_bf16 v[112:115], v[168:171], v[186:189], v[112:115]
	v_mfma_f32_16x16x32_bf16 v[108:111], v[136:139], v[194:197], v[108:111]
	v_mfma_f32_16x16x32_bf16 v[104:107], v[168:171], v[194:197], v[104:107]
	s_setprio 2
	s_barrier
	v_mfma_f32_16x16x32_bf16 v[100:103], v[136:139], v[202:205], v[100:103]
	v_mfma_f32_16x16x32_bf16 v[96:99], v[168:171], v[202:205], v[96:99]
	s_setprio 0
	ds_read_b128 v[206:209], v155 offset:16384
	ds_read_b128 v[210:213], v155 offset:17408
	ds_read_b128 v[214:217], v155 offset:18432
	ds_read_b128 v[218:221], v155 offset:19456
	s_barrier
	s_waitcnt lgkmcnt(0)
	s_setprio 1
	s_waitcnt lgkmcnt(0)
	v_mfma_f32_16x16x32_bf16 v[92:95], v[206:209], v[172:175], v[92:95]
	v_mfma_f32_16x16x32_bf16 v[88:91], v[214:217], v[172:175], v[88:91]
	v_mfma_f32_16x16x32_bf16 v[84:87], v[206:209], v[182:185], v[84:87]
	v_mfma_f32_16x16x32_bf16 v[80:83], v[214:217], v[182:185], v[80:83]
	v_mfma_f32_16x16x32_bf16 v[76:79], v[206:209], v[190:193], v[76:79]
	v_mfma_f32_16x16x32_bf16 v[72:75], v[214:217], v[190:193], v[72:75]
	v_mfma_f32_16x16x32_bf16 v[68:71], v[206:209], v[198:201], v[68:71]
	v_mfma_f32_16x16x32_bf16 v[64:67], v[214:217], v[198:201], v[64:67]
	v_mfma_f32_16x16x32_bf16 v[92:95], v[210:213], v[176:179], v[92:95]
	v_mfma_f32_16x16x32_bf16 v[88:91], v[218:221], v[176:179], v[88:91]
	v_mfma_f32_16x16x32_bf16 v[84:87], v[210:213], v[186:189], v[84:87]
	v_mfma_f32_16x16x32_bf16 v[80:83], v[218:221], v[186:189], v[80:83]
	v_mfma_f32_16x16x32_bf16 v[76:79], v[210:213], v[194:197], v[76:79]
	v_mfma_f32_16x16x32_bf16 v[72:75], v[218:221], v[194:197], v[72:75]
	s_setprio 2
	s_barrier
	v_mfma_f32_16x16x32_bf16 v[68:71], v[210:213], v[202:205], v[68:71]
	v_mfma_f32_16x16x32_bf16 v[64:67], v[218:221], v[202:205], v[64:67]
	s_setprio 0
	ds_read_b128 v[172:175], v151 offset:16384
	ds_read_b128 v[176:179], v151 offset:17408
	ds_read_b128 v[182:185], v151 offset:18432
	ds_read_b128 v[186:189], v151 offset:19456
	ds_read_b128 v[190:193], v151 offset:20480
	ds_read_b128 v[194:197], v151 offset:21504
	ds_read_b128 v[198:201], v151 offset:22528
	ds_read_b128 v[202:205], v151 offset:23552
	s_waitcnt vmcnt(4)
	s_barrier
; #define LDA(dst, b, h) for (int m = 0; m < 4; ++m) for (int k = 0; k < 2; ++k) \
;     dst[m][k] = *reinterpret_cast<const bf16x8*>(a_rd + ((b) * 2 + (h)) * (HT * 2) + m * 2048 + k * 1024)
; #define LDB(dst, b, h) for (int n = 0; n < 2; ++n) for (int k = 0; k < 2; ++k) \
;     dst[n][k] = *reinterpret_cast<const bf16x8*>(b_rd + ((b) * 2 + (h)) * (HT * 2) + n * 2048 + k * 1024)
; #define MMA(ai, bj, At_, Bt_) do { __builtin_amdgcn_s_setprio(1); \
;     for (int m = 0; m < 4; ++m) for (int n = 0; n < 2; ++n) for (int k = 0; k < 2; ++k) \
;       acc[ai][bj][m][n] = __builtin_amdgcn_mfma_f32_16x16x32_bf16(Bt_[n][k], At_[m][k], acc[ai][bj][m][n], 0, 0, 0); \
;     __builtin_amdgcn_s_setprio(0); } while (0)
; #define WAIT_V(n) asm volatile("s_waitcnt vmcnt(" #n ")" ::: "memory")
; #define WAIT_L(n) asm volatile("s_waitcnt lgkmcnt(" #n ")" ::: "memory")
; #define BAR __builtin_amdgcn_s_barrier()
;     ...
;     LDA(At, 0, 1); WAIT_V(4); BAR; WAIT_L(0); MMA(1, 0, At, B0); MMA(1, 1, At, B1); BAR; }
;   { LDB(B0, 1, 0); LDA(At, 1, 0); WAIT_V(2); BAR; WAIT_L(0); MMA(0, 0, At, B0); BAR;
;     LDB(B1, 1, 1); WAIT_V(0); BAR; WAIT_L(0); MMA(0, 1, At, B1); BAR;
;     LDA(At, 1, 1); BAR; WAIT_L(0); MMA(1, 0, At, B0); MMA(1, 1, At, B1); BAR; }
	s_waitcnt lgkmcnt(0)
	s_setprio 1
	s_waitcnt lgkmcnt(0)
	v_mfma_f32_16x16x32_bf16 v[60:63], v[132:135], v[172:175], v[60:63]
	v_mfma_f32_16x16x32_bf16 v[56:59], v[164:167], v[172:175], v[56:59]
	v_mfma_f32_16x16x32_bf16 v[52:55], v[132:135], v[182:185], v[52:55]
	v_mfma_f32_16x16x32_bf16 v[48:51], v[164:167], v[182:185], v[48:51]
	v_mfma_f32_16x16x32_bf16 v[44:47], v[132:135], v[190:193], v[44:47]
	v_mfma_f32_16x16x32_bf16 v[40:43], v[164:167], v[190:193], v[40:43]
	v_mfma_f32_16x16x32_bf16 v[36:39], v[132:135], v[198:201], v[36:39]
	v_mfma_f32_16x16x32_bf16 v[32:35], v[164:167], v[198:201], v[32:35]
	v_mfma_f32_16x16x32_bf16 v[60:63], v[136:139], v[176:179], v[60:63]
	v_mfma_f32_16x16x32_bf16 v[56:59], v[168:171], v[176:179], v[56:59]
	v_mfma_f32_16x16x32_bf16 v[52:55], v[136:139], v[186:189], v[52:55]
	v_mfma_f32_16x16x32_bf16 v[48:51], v[168:171], v[186:189], v[48:51]
	v_mfma_f32_16x16x32_bf16 v[44:47], v[136:139], v[194:197], v[44:47]
	v_mfma_f32_16x16x32_bf16 v[40:43], v[168:171], v[194:197], v[40:43]
	v_mfma_f32_16x16x32_bf16 v[36:39], v[136:139], v[202:205], v[36:39]
	v_mfma_f32_16x16x32_bf16 v[32:35], v[168:171], v[202:205], v[32:35]
	s_setprio 0
	s_setprio 1
	v_mfma_f32_16x16x32_bf16 v[28:31], v[206:209], v[172:175], v[28:31]
	v_mfma_f32_16x16x32_bf16 v[24:27], v[214:217], v[172:175], v[24:27]
	v_mfma_f32_16x16x32_bf16 v[20:23], v[206:209], v[182:185], v[20:23]
	v_mfma_f32_16x16x32_bf16 v[16:19], v[214:217], v[182:185], v[16:19]
	v_mfma_f32_16x16x32_bf16 v[12:15], v[206:209], v[190:193], v[12:15]
	v_mfma_f32_16x16x32_bf16 v[8:11], v[214:217], v[190:193], v[8:11]
	v_mfma_f32_16x16x32_bf16 v[4:7], v[206:209], v[198:201], v[4:7]
	v_mfma_f32_16x16x32_bf16 v[0:3], v[214:217], v[198:201], v[0:3]
	v_mfma_f32_16x16x32_bf16 v[28:31], v[210:213], v[176:179], v[28:31]
	v_mfma_f32_16x16x32_bf16 v[24:27], v[218:221], v[176:179], v[24:27]
	v_mfma_f32_16x16x32_bf16 v[20:23], v[210:213], v[186:189], v[20:23]
	v_mfma_f32_16x16x32_bf16 v[16:19], v[218:221], v[186:189], v[16:19]
	v_mfma_f32_16x16x32_bf16 v[12:15], v[210:213], v[194:197], v[12:15]
	v_mfma_f32_16x16x32_bf16 v[8:11], v[218:221], v[194:197], v[8:11]
	s_setprio 2
	s_barrier
	v_mfma_f32_16x16x32_bf16 v[4:7], v[210:213], v[202:205], v[4:7]
	v_mfma_f32_16x16x32_bf16 v[0:3], v[218:221], v[202:205], v[0:3]
	s_setprio 0
	ds_read_b128 v[132:135], v155 offset:32768
	ds_read_b128 v[136:139], v155 offset:33792
	ds_read_b128 v[162:165], v155 offset:34816
	ds_read_b128 v[166:169], v155 offset:35840
	ds_read_b128 v[170:173], v151 offset:32768
	ds_read_b128 v[174:177], v151 offset:33792
	ds_read_b128 v[182:185], v151 offset:34816
	ds_read_b128 v[186:189], v151 offset:35840
	ds_read_b128 v[190:193], v151 offset:36864
	ds_read_b128 v[194:197], v151 offset:37888
	ds_read_b128 v[198:201], v151 offset:38912
	ds_read_b128 v[202:205], v151 offset:39936
	s_waitcnt vmcnt(2)
	s_barrier
	s_waitcnt lgkmcnt(0)
	s_setprio 1
	s_waitcnt lgkmcnt(0)
	v_mfma_f32_16x16x32_bf16 v[124:127], v[132:135], v[170:173], v[124:127]
	v_mfma_f32_16x16x32_bf16 v[120:123], v[162:165], v[170:173], v[120:123]
	v_mfma_f32_16x16x32_bf16 v[116:119], v[132:135], v[182:185], v[116:119]
	v_mfma_f32_16x16x32_bf16 v[112:115], v[162:165], v[182:185], v[112:115]
	v_mfma_f32_16x16x32_bf16 v[108:111], v[132:135], v[190:193], v[108:111]
	v_mfma_f32_16x16x32_bf16 v[104:107], v[162:165], v[190:193], v[104:107]
	v_mfma_f32_16x16x32_bf16 v[100:103], v[132:135], v[198:201], v[100:103]
	v_mfma_f32_16x16x32_bf16 v[96:99], v[162:165], v[198:201], v[96:99]
	v_mfma_f32_16x16x32_bf16 v[124:127], v[136:139], v[174:177], v[124:127]
	v_mfma_f32_16x16x32_bf16 v[120:123], v[166:169], v[174:177], v[120:123]
	v_mfma_f32_16x16x32_bf16 v[116:119], v[136:139], v[186:189], v[116:119]
	v_mfma_f32_16x16x32_bf16 v[112:115], v[166:169], v[186:189], v[112:115]
	v_mfma_f32_16x16x32_bf16 v[108:111], v[136:139], v[194:197], v[108:111]
	v_mfma_f32_16x16x32_bf16 v[104:107], v[166:169], v[194:197], v[104:107]
	s_setprio 2
	s_barrier
	v_mfma_f32_16x16x32_bf16 v[100:103], v[136:139], v[202:205], v[100:103]
	v_mfma_f32_16x16x32_bf16 v[96:99], v[166:169], v[202:205], v[96:99]
	s_setprio 0
	ds_read_b128 v[206:209], v155 offset:49152
	ds_read_b128 v[210:213], v155 offset:50176
	ds_read_b128 v[214:217], v155 offset:51200
	ds_read_b128 v[218:221], v155 offset:52224
	s_waitcnt vmcnt(0)
	s_barrier
; #define LDA(dst, b, h) for (int m = 0; m < 4; ++m) for (int k = 0; k < 2; ++k) \
;     dst[m][k] = *reinterpret_cast<const bf16x8*>(a_rd + ((b) * 2 + (h)) * (HT * 2) + m * 2048 + k * 1024)
; #define LDB(dst, b, h) for (int n = 0; n < 2; ++n) for (int k = 0; k < 2; ++k) \
;     dst[n][k] = *reinterpret_cast<const bf16x8*>(b_rd + ((b) * 2 + (h)) * (HT * 2) + n * 2048 + k * 1024)
; #define MMA(ai, bj, At_, Bt_) do { __builtin_amdgcn_s_setprio(1); \
;     for (int m = 0; m < 4; ++m) for (int n = 0; n < 2; ++n) for (int k = 0; k < 2; ++k) \
;       acc[ai][bj][m][n] = __builtin_amdgcn_mfma_f32_16x16x32_bf16(Bt_[n][k], At_[m][k], acc[ai][bj][m][n], 0, 0, 0); \
;     __builtin_amdgcn_s_setprio(0); } while (0)
; #define WAIT_V(n) asm volatile("s_waitcnt vmcnt(" #n ")" ::: "memory")
; #define WAIT_L(n) asm volatile("s_waitcnt lgkmcnt(" #n ")" ::: "memory")
; #define BAR __builtin_amdgcn_s_barrier()
;     ...
;   { LDB(B0, 1, 0); LDA(At, 1, 0); WAIT_V(2); BAR; WAIT_L(0); MMA(0, 0, At, B0); BAR;
;     LDB(B1, 1, 1); WAIT_V(0); BAR; WAIT_L(0); MMA(0, 1, At, B1); BAR;
;     LDA(At, 1, 1); BAR; WAIT_L(0); MMA(1, 0, At, B0); MMA(1, 1, At, B1); BAR; }
;   if (wr == 0) BAR;
	s_waitcnt lgkmcnt(0)
	s_setprio 1
	s_waitcnt lgkmcnt(0)
	v_mfma_f32_16x16x32_bf16 v[92:95], v[206:209], v[170:173], v[92:95]
	v_mfma_f32_16x16x32_bf16 v[88:91], v[214:217], v[170:173], v[88:91]
	v_mfma_f32_16x16x32_bf16 v[84:87], v[206:209], v[182:185], v[84:87]
	v_mfma_f32_16x16x32_bf16 v[80:83], v[214:217], v[182:185], v[80:83]
	v_mfma_f32_16x16x32_bf16 v[76:79], v[206:209], v[190:193], v[76:79]
	v_mfma_f32_16x16x32_bf16 v[72:75], v[214:217], v[190:193], v[72:75]
	v_mfma_f32_16x16x32_bf16 v[68:71], v[206:209], v[198:201], v[68:71]
	v_mfma_f32_16x16x32_bf16 v[64:67], v[214:217], v[198:201], v[64:67]
	v_mfma_f32_16x16x32_bf16 v[92:95], v[210:213], v[174:177], v[92:95]
	v_mfma_f32_16x16x32_bf16 v[88:91], v[218:221], v[174:177], v[88:91]
	v_mfma_f32_16x16x32_bf16 v[84:87], v[210:213], v[186:189], v[84:87]
	v_mfma_f32_16x16x32_bf16 v[80:83], v[218:221], v[186:189], v[80:83]
	v_mfma_f32_16x16x32_bf16 v[76:79], v[210:213], v[194:197], v[76:79]
	v_mfma_f32_16x16x32_bf16 v[72:75], v[218:221], v[194:197], v[72:75]
	s_setprio 2
	s_barrier
	v_mfma_f32_16x16x32_bf16 v[68:71], v[210:213], v[202:205], v[68:71]
	v_mfma_f32_16x16x32_bf16 v[64:67], v[218:221], v[202:205], v[64:67]
	s_setprio 0
	ds_read_b128 v[170:173], v151 offset:49152
	ds_read_b128 v[174:177], v151 offset:50176
	ds_read_b128 v[182:185], v151 offset:51200
	ds_read_b128 v[186:189], v151 offset:52224
	ds_read_b128 v[190:193], v151 offset:53248
	ds_read_b128 v[194:197], v151 offset:54272
	ds_read_b128 v[198:201], v151 offset:55296
	ds_read_b128 v[202:205], v151 offset:56320
	s_barrier
	s_waitcnt lgkmcnt(0)
	s_setprio 1
	s_waitcnt lgkmcnt(0)
	v_mfma_f32_16x16x32_bf16 v[60:63], v[132:135], v[170:173], v[60:63]
	v_mfma_f32_16x16x32_bf16 v[56:59], v[162:165], v[170:173], v[56:59]
	v_mfma_f32_16x16x32_bf16 v[52:55], v[132:135], v[182:185], v[52:55]
	v_mfma_f32_16x16x32_bf16 v[48:51], v[162:165], v[182:185], v[48:51]
	v_mfma_f32_16x16x32_bf16 v[44:47], v[132:135], v[190:193], v[44:47]
	v_mfma_f32_16x16x32_bf16 v[40:43], v[162:165], v[190:193], v[40:43]
	v_mfma_f32_16x16x32_bf16 v[36:39], v[132:135], v[198:201], v[36:39]
	v_mfma_f32_16x16x32_bf16 v[32:35], v[162:165], v[198:201], v[32:35]
	v_mfma_f32_16x16x32_bf16 v[60:63], v[136:139], v[174:177], v[60:63]
	v_mfma_f32_16x16x32_bf16 v[56:59], v[166:169], v[174:177], v[56:59]
	v_mfma_f32_16x16x32_bf16 v[52:55], v[136:139], v[186:189], v[52:55]
	v_mfma_f32_16x16x32_bf16 v[48:51], v[166:169], v[186:189], v[48:51]
	v_mfma_f32_16x16x32_bf16 v[44:47], v[136:139], v[194:197], v[44:47]
	v_mfma_f32_16x16x32_bf16 v[40:43], v[166:169], v[194:197], v[40:43]
	v_mfma_f32_16x16x32_bf16 v[36:39], v[136:139], v[202:205], v[36:39]
	v_mfma_f32_16x16x32_bf16 v[32:35], v[166:169], v[202:205], v[32:35]
	s_setprio 0
	s_setprio 1
	v_mfma_f32_16x16x32_bf16 v[28:31], v[206:209], v[170:173], v[28:31]
	v_mfma_f32_16x16x32_bf16 v[24:27], v[214:217], v[170:173], v[24:27]
	v_mfma_f32_16x16x32_bf16 v[20:23], v[206:209], v[182:185], v[20:23]
	v_mfma_f32_16x16x32_bf16 v[16:19], v[214:217], v[182:185], v[16:19]
	v_mfma_f32_16x16x32_bf16 v[12:15], v[206:209], v[190:193], v[12:15]
	v_mfma_f32_16x16x32_bf16 v[8:11], v[214:217], v[190:193], v[8:11]
	v_mfma_f32_16x16x32_bf16 v[4:7], v[206:209], v[198:201], v[4:7]
	v_mfma_f32_16x16x32_bf16 v[0:3], v[214:217], v[198:201], v[0:3]
	v_mfma_f32_16x16x32_bf16 v[28:31], v[210:213], v[174:177], v[28:31]
	v_mfma_f32_16x16x32_bf16 v[24:27], v[218:221], v[174:177], v[24:27]
	v_mfma_f32_16x16x32_bf16 v[20:23], v[210:213], v[186:189], v[20:23]
	v_mfma_f32_16x16x32_bf16 v[16:19], v[218:221], v[186:189], v[16:19]
	v_mfma_f32_16x16x32_bf16 v[12:15], v[210:213], v[194:197], v[12:15]
	v_mfma_f32_16x16x32_bf16 v[8:11], v[218:221], v[194:197], v[8:11]
	s_setprio 2
	s_barrier
	v_mfma_f32_16x16x32_bf16 v[4:7], v[210:213], v[202:205], v[4:7]
	v_mfma_f32_16x16x32_bf16 v[0:3], v[218:221], v[202:205], v[0:3]
	s_setprio 0
	v_cmp_gt_u32_e32 vcc, s60, v144
	s_and_saveexec_b64 s[8:9], vcc
	s_cbranch_execz .LBB0_749
	s_barrier

; #define STAGE_A(P, br, kt) do { const char* _base = (const char*)(((kt) < G.ksplit ? G.A1 : A2m) + (long)(br) * G.lda + (long)(kt) * BK); \
;     __builtin_amdgcn_global_load_lds((const unsigned*)(_base + aoff0), (unsigned*)((char*)(P) + sb0), 16, 0, 0); \
;     __builtin_amdgcn_global_load_lds((const unsigned*)(_base + aoff1), (unsigned*)((char*)(P) + sb1), 16, 0, 0); } while (0)
; #define STAGE_B(P, br, kt) do { const char* _base = (const char*)(G.Bt + (long)(br) * G.ldb + (long)(kt) * BK); \
;     __builtin_amdgcn_global_load_lds((const unsigned*)(_base + boff0), (unsigned*)((char*)(P) + sb0), 16, 0, 0); \
;     __builtin_amdgcn_global_load_lds((const unsigned*)(_base + boff1), (unsigned*)((char*)(P) + sb1), 16, 0, 0); } while (0)
; #define LDA(dst, b, h) for (int m = 0; m < 4; ++m) for (int k = 0; k < 2; ++k) \
;     dst[m][k] = *reinterpret_cast<const bf16x8*>(a_rd + ((b) * 2 + (h)) * (HT * 2) + m * 2048 + k * 1024)
; #define BAR __builtin_amdgcn_s_barrier()
;     ...
;   const int sb0 = t1 * 16, sb1 = sb0 + 8192;
;   const int swz_ = lds_byte(fr, fq * 8);
;   const char* a_rd = shmc + wr * 8192 + swz_;
;   const char* b_rd = shmc + 4 * (HT * 2) + wc * 4096 + swz_;
;   int r0_, c0_, r1_, c1_; stage_rc(sb0, r0_, c0_); stage_rc(sb1, r1_, c1_);
;   const unsigned aoff0 = (unsigned)(r0_ * G.lda + c0_) * 2u, aoff1 = (unsigned)(r1_ * G.lda + c1_) * 2u;
;   const unsigned boff0 = (unsigned)(r0_ * G.ldb + c0_) * 2u, boff1 = (unsigned)(r1_ * G.ldb + c1_) * 2u;
;   f32x4 acc[2][2][4][2] = {};
;   bf16x8 At[4][2], B0[2][2], B1[2][2];
;   const int nt = K / BK;
;   if (EPI == EPI_RESID || first) {
;     STAGE_B(SB(0, 0), bcol, 0); STAGE_A(SA(0, 0), brow, 0);
;     STAGE_B(SB(0, 1), bcol + HALF, 0); STAGE_A(SA(0, 1), brow + HALF, 0);
;   }
;   if (wr == 1) BAR;
;   WAIT_V(0); BAR;
;   STAGE_B(SB(1, 0), bcol, 1); STAGE_A(SA(1, 0), brow, 1); STAGE_B(SB(1, 1), bcol + HALF, 1);
;   WAIT_V(6); BAR;
;   for (int t = 0; t < nt - 2; t += 2) {
;     LDB(B0, 0, 0); SCHED; LDA(At, 0, 0); STAGE_A(SA(1, 1), brow + HALF, t + 1);
;     WAIT_L(8); BAR; WAIT_L(0); MMA(0, 0, At, B0); BAR; SCHED;
;     LDB(B1, 0, 1); STAGE_B(SB(0, 0), bcol, t + 2);
;     BAR; WAIT_L(0); MMA(0, 1, At, B1); BAR;
;     LDA(At, 0, 1); STAGE_A(SA(0, 0), brow, t + 2);
;     BAR; WAIT_L(0); MMA(1, 0, At, B0); BAR; SCHED;
;     STAGE_B(SB(0, 1), bcol + HALF, t + 2);
;     WAIT_V(6); BAR; MMA(1, 1, At, B1); BAR;
.LBB0_1800:
	s_or_b64 exec, exec, s[8:9]
	v_and_b32_e32 v20, 15, v144
	v_lshlrev_b32_e32 v22, 2, v144
	v_and_b32_e32 v21, 48, v144
	v_lshlrev_b32_e32 v20, 6, v20
	v_and_b32_e32 v22, 32, v22
	v_bitop3_b32 v20, v20, v22, v21 bitop3:0x36
	v_lshlrev_b32_e32 v21, 6, v144
	v_and_b32_e32 v21, 0x3000, v21
	v_add_u32_e32 v21, s37, v21
	v_readlane_b32 s37, v253, 46
	s_mov_b64 s[40:41], 0x80
	v_lshl_add_u64 v[2:3], v[2:3], 0, s[40:41]
	v_add_u32_e32 v153, s37, v12
	v_add_u32_e32 v154, 0x2000, v153
	v_readfirstlane_b32 s37, v153
	s_mov_b32 m0, s37
	v_readfirstlane_b32 s37, v154
	v_add_u32_e32 v155, 0x8000, v147
	s_waitcnt vmcnt(0)
	s_barrier
	global_load_lds_dwordx4 v[2:3], off
	v_lshl_add_u64 v[2:3], v[4:5], 0, s[40:41]
	s_mov_b32 m0, s37
	v_readfirstlane_b32 s37, v155
	v_add_u32_e32 v156, 0xa000, v147
	global_load_lds_dwordx4 v[2:3], off
	v_lshl_add_u64 v[2:3], v[6:7], 0, s[40:41]
	s_mov_b32 m0, s37
	v_readfirstlane_b32 s37, v156
	s_lshl_b64 s[8:9], s[20:21], 10
	global_load_lds_dwordx4 v[2:3], off
	s_mov_b32 m0, s37
	v_readlane_b32 s37, v253, 47
	s_add_u32 s38, s38, 0x84080
	v_lshl_add_u64 v[2:3], v[8:9], 0, s[40:41]
	v_add_u32_e32 v157, s37, v12
	s_addc_u32 s39, s39, 0
	v_readfirstlane_b32 s37, v157
	v_add_u32_e32 v158, 0x2000, v157
	global_load_lds_dwordx4 v[2:3], off
	v_lshl_add_u64 v[2:3], s[38:39], 0, v[180:181]
	s_mov_b32 m0, s37
	v_readfirstlane_b32 s37, v158
	global_load_lds_dwordx4 v[2:3], off
	v_lshl_add_u64 v[0:1], s[38:39], 0, v[0:1]
	s_mov_b32 m0, s37
	v_lshrrev_b32_e32 v2, 1, v11
	global_load_lds_dwordx4 v[0:1], off
	v_lshrrev_b32_e32 v1, 1, v10
	v_mul_lo_u32 v0, v13, s62
	v_mad_u64_u32 v[0:1], s[38:39], v1, s84, v[0:1]
	v_or_b32_e32 v0, v0, v14
	v_add_lshl_u32 v180, v0, v16, 1
	v_mul_lo_u32 v0, v15, s62
	v_lshlrev_b32_e32 v3, 11, v15
	v_mad_u64_u32 v[0:1], s[38:39], v2, s84, v[0:1]
	v_lshl_add_u32 v2, v2, 15, v3
	v_and_b32_e32 v3, 1, v11
	s_add_u32 s26, s14, s26
	v_lshl_or_b32 v2, v3, 6, v2
	s_addc_u32 s27, s15, s27
	v_lshl_add_u32 v2, v17, 1, v2
	v_mov_b32_e32 v3, v181
	v_or_b32_e32 v0, v0, v18
	v_lshl_add_u64 v[136:137], s[10:11], 0, v[130:131]
	v_lshl_add_u64 v[138:139], s[10:11], 0, v[2:3]
	s_add_u32 s10, s14, s24
	s_waitcnt vmcnt(6)
	v_add_lshl_u32 v0, v0, v17, 1
	v_mov_b32_e32 v1, v181
	s_addc_u32 s11, s15, s25
	v_lshl_add_u32 v19, v19, 13, 32
	v_lshl_add_u64 v[134:135], s[26:27], 0, v[0:1]
	v_lshl_add_u64 v[142:143], s[10:11], 0, v[0:1]
	v_mov_b32_e32 v245, 0x80003fff
	v_lshl_add_u64 v[132:133], s[26:27], 0, v[180:181]
	v_lshl_add_u64 v[140:141], s[10:11], 0, v[180:181]
	s_mov_b32 s24, -2
	s_mov_b64 s[10:11], 0
	v_add_u32_e32 v149, v21, v20
	v_add_u32_e32 v146, v19, v20
	s_waitcnt vmcnt(0)
	s_mov_b64 s[38:39], 0x40080
	s_mov_b64 s[40:41], 0x54e8100
	s_mov_b64 s[42:43], 0x556c100
	s_mov_b64 s[44:45], 0x40100
	s_mov_b64 s[46:47], 0x54e8180
	s_mov_b64 s[48:49], 0x556c180
	s_barrier
	ds_read_b128 v[162:165], v149
	ds_read_b128 v[166:169], v149 offset:1024
	ds_read_b128 v[170:173], v149 offset:2048
	ds_read_b128 v[174:177], v149 offset:3072
	s_add_i32 s24, s24, 2
	s_cmp_lt_u32 s24, 16
	s_cselect_b32 s27, s30, s36
	s_cselect_b32 s26, s29, s35
	v_lshl_add_u64 v[160:161], s[26:27], 0, v[136:137]
	v_add_u32_e32 v159, 0xc000, v147
	v_lshl_add_u64 v[160:161], v[160:161], 0, s[10:11]
	v_readfirstlane_b32 s25, v159
	v_lshl_add_u64 v[160:161], v[160:161], 0, s[38:39]
	s_mov_b32 m0, s25
	ds_read_b128 v[182:185], v146
	ds_read_b128 v[186:189], v146 offset:1024
	ds_read_b128 v[190:193], v146 offset:2048
	ds_read_b128 v[194:197], v146 offset:3072
	ds_read_b128 v[198:201], v146 offset:4096
	ds_read_b128 v[202:205], v146 offset:5120
	ds_read_b128 v[206:209], v146 offset:6144
	ds_read_b128 v[210:213], v146 offset:7168
	global_load_lds_dwordx4 v[160:161], off
	v_lshl_add_u64 v[160:161], s[26:27], 0, v[138:139]
	v_lshl_add_u64 v[160:161], v[160:161], 0, s[10:11]
	v_lshl_add_u64 v[178:179], v[160:161], 0, s[38:39]
	v_add_u32_e32 v160, 0xe000, v147
	s_nop 0
	v_readfirstlane_b32 s25, v160
	s_mov_b32 m0, s25
	s_nop 0
	global_load_lds_dwordx4 v[178:179], off
	ds_read_b128 v[214:217], v149 offset:16384
	ds_read_b128 v[218:221], v149 offset:17408
	ds_read_b128 v[230:233], v149 offset:18432
	ds_read_b128 v[238:241], v149 offset:19456
	s_waitcnt lgkmcnt(0)
	s_waitcnt vmcnt(8)
	s_barrier
	s_setprio 1
	v_mfma_f32_16x16x32_bf16 v[124:127], v[162:165], v[182:185], 0
	v_mfma_f32_16x16x32_bf16 v[120:123], v[170:173], v[182:185], 0
	v_mfma_f32_16x16x32_bf16 v[116:119], v[162:165], v[190:193], 0
	v_mfma_f32_16x16x32_bf16 v[112:115], v[170:173], v[190:193], 0
	v_mfma_f32_16x16x32_bf16 v[108:111], v[162:165], v[198:201], 0
	v_mfma_f32_16x16x32_bf16 v[104:107], v[170:173], v[198:201], 0
	v_mfma_f32_16x16x32_bf16 v[100:103], v[162:165], v[206:209], 0
	v_mfma_f32_16x16x32_bf16 v[96:99], v[170:173], v[206:209], 0
	v_mfma_f32_16x16x32_bf16 v[124:127], v[166:169], v[186:189], v[124:127]
	v_mfma_f32_16x16x32_bf16 v[120:123], v[174:177], v[186:189], v[120:123]
	v_mfma_f32_16x16x32_bf16 v[116:119], v[166:169], v[194:197], v[116:119]
	v_mfma_f32_16x16x32_bf16 v[112:115], v[174:177], v[194:197], v[112:115]
	v_mfma_f32_16x16x32_bf16 v[108:111], v[166:169], v[202:205], v[108:111]
	v_mfma_f32_16x16x32_bf16 v[104:107], v[174:177], v[202:205], v[104:107]
	v_mfma_f32_16x16x32_bf16 v[100:103], v[166:169], v[210:213], v[100:103]
	v_mfma_f32_16x16x32_bf16 v[96:99], v[174:177], v[210:213], v[96:99]
	v_mfma_f32_16x16x32_bf16 v[92:95], v[214:217], v[182:185], 0
	v_mfma_f32_16x16x32_bf16 v[88:91], v[230:233], v[182:185], 0
	v_mfma_f32_16x16x32_bf16 v[84:87], v[214:217], v[190:193], 0
	v_mfma_f32_16x16x32_bf16 v[80:83], v[230:233], v[190:193], 0
	v_mfma_f32_16x16x32_bf16 v[76:79], v[214:217], v[198:201], 0
	v_mfma_f32_16x16x32_bf16 v[72:75], v[230:233], v[198:201], 0
	v_mfma_f32_16x16x32_bf16 v[68:71], v[214:217], v[206:209], 0
	v_mfma_f32_16x16x32_bf16 v[64:67], v[230:233], v[206:209], 0
	v_mfma_f32_16x16x32_bf16 v[92:95], v[218:221], v[186:189], v[92:95]
	v_mfma_f32_16x16x32_bf16 v[88:91], v[238:241], v[186:189], v[88:91]
	v_mfma_f32_16x16x32_bf16 v[84:87], v[218:221], v[194:197], v[84:87]
	v_mfma_f32_16x16x32_bf16 v[80:83], v[238:241], v[194:197], v[80:83]
	v_mfma_f32_16x16x32_bf16 v[76:79], v[218:221], v[202:205], v[76:79]
	v_mfma_f32_16x16x32_bf16 v[72:75], v[238:241], v[202:205], v[72:75]
	s_setprio 2
	s_barrier
; #define STAGE_A(P, br, kt) do { const char* _base = (const char*)(((kt) < G.ksplit ? G.A1 : A2m) + (long)(br) * G.lda + (long)(kt) * BK); \
;     __builtin_amdgcn_global_load_lds((const unsigned*)(_base + aoff0), (unsigned*)((char*)(P) + sb0), 16, 0, 0); \
;     __builtin_amdgcn_global_load_lds((const unsigned*)(_base + aoff1), (unsigned*)((char*)(P) + sb1), 16, 0, 0); } while (0)
; #define STAGE_B(P, br, kt) do { const char* _base = (const char*)(G.Bt + (long)(br) * G.ldb + (long)(kt) * BK); \
;     __builtin_amdgcn_global_load_lds((const unsigned*)(_base + boff0), (unsigned*)((char*)(P) + sb0), 16, 0, 0); \
;     __builtin_amdgcn_global_load_lds((const unsigned*)(_base + boff1), (unsigned*)((char*)(P) + sb1), 16, 0, 0); } while (0)
; #define LDA(dst, b, h) for (int m = 0; m < 4; ++m) for (int k = 0; k < 2; ++k) \
;     dst[m][k] = *reinterpret_cast<const bf16x8*>(a_rd + ((b) * 2 + (h)) * (HT * 2) + m * 2048 + k * 1024)
; #define LDB(dst, b, h) for (int n = 0; n < 2; ++n) for (int k = 0; k < 2; ++k) \
;     dst[n][k] = *reinterpret_cast<const bf16x8*>(b_rd + ((b) * 2 + (h)) * (HT * 2) + n * 2048 + k * 1024)
; #define MMA(ai, bj, At_, Bt_) do { __builtin_amdgcn_s_setprio(1); \
;     for (int m = 0; m < 4; ++m) for (int n = 0; n < 2; ++n) for (int k = 0; k < 2; ++k) \
;       acc[ai][bj][m][n] = __builtin_amdgcn_mfma_f32_16x16x32_bf16(Bt_[n][k], At_[m][k], acc[ai][bj][m][n], 0, 0, 0); \
;     __builtin_amdgcn_s_setprio(0); } while (0)
; #define WAIT_V(n) asm volatile("s_waitcnt vmcnt(" #n ")" ::: "memory")
; #define WAIT_L(n) asm volatile("s_waitcnt lgkmcnt(" #n ")" ::: "memory")
; #define BAR __builtin_amdgcn_s_barrier()
; #define SCHED __builtin_amdgcn_sched_barrier(0)
;     ...
;     LDB(B0, 0, 0); SCHED; LDA(At, 0, 0); STAGE_A(SA(1, 1), brow + HALF, t + 1);
;     WAIT_L(8); BAR; WAIT_L(0); MMA(0, 0, At, B0); BAR; SCHED;
;     LDB(B1, 0, 1); STAGE_B(SB(0, 0), bcol, t + 2);
;     BAR; WAIT_L(0); MMA(0, 1, At, B1); BAR;
;     LDA(At, 0, 1); STAGE_A(SA(0, 0), brow, t + 2);
;     BAR; WAIT_L(0); MMA(1, 0, At, B0); BAR; SCHED;
;     STAGE_B(SB(0, 1), bcol + HALF, t + 2);
;     WAIT_V(6); BAR; MMA(1, 1, At, B1); BAR;
;     LDB(B0, 1, 0); SCHED; LDA(At, 1, 0); STAGE_A(SA(0, 1), brow + HALF, t + 2);
;     WAIT_L(8); BAR; WAIT_L(0); MMA(0, 0, At, B0); BAR; SCHED;
;     LDB(B1, 1, 1); STAGE_B(SB(1, 0), bcol, t + 3);
	v_mfma_f32_16x16x32_bf16 v[68:71], v[218:221], v[210:213], v[68:71]
	v_mfma_f32_16x16x32_bf16 v[64:67], v[238:241], v[210:213], v[64:67]
	s_setprio 0
	v_lshl_add_u64 v[178:179], v[132:133], 0, s[10:11]
	v_readfirstlane_b32 s25, v145
	v_lshl_add_u64 v[222:223], v[178:179], 0, s[40:41]
	s_mov_b32 m0, s25
	v_add_u32_e32 v161, 0x2000, v145
	global_load_lds_dwordx4 v[222:223], off
	v_lshl_add_u64 v[222:223], v[134:135], 0, s[10:11]
	v_readfirstlane_b32 s25, v161
	v_lshl_add_u64 v[226:227], v[222:223], 0, s[40:41]
	s_mov_b32 m0, s25
	s_nop 0
	global_load_lds_dwordx4 v[226:227], off
	s_cmp_lt_u32 s24, 14
	s_cselect_b32 s27, s30, s36
	s_cselect_b32 s26, s29, s35
	v_lshl_add_u64 v[226:227], s[26:27], 0, v[136:137]
	v_lshl_add_u64 v[226:227], v[226:227], 0, s[10:11]
	v_readfirstlane_b32 s25, v147
	v_lshl_add_u64 v[234:235], v[226:227], 0, s[90:91]
	s_mov_b32 m0, s25
	ds_read_b128 v[182:185], v146 offset:16384
	ds_read_b128 v[186:189], v146 offset:17408
	ds_read_b128 v[190:193], v146 offset:18432
	ds_read_b128 v[194:197], v146 offset:19456
	ds_read_b128 v[198:201], v146 offset:20480
	ds_read_b128 v[202:205], v146 offset:21504
	ds_read_b128 v[206:209], v146 offset:22528
	ds_read_b128 v[210:213], v146 offset:23552
	global_load_lds_dwordx4 v[234:235], off
	v_lshl_add_u64 v[234:235], s[26:27], 0, v[138:139]
	v_lshl_add_u64 v[234:235], v[234:235], 0, s[10:11]
	v_readfirstlane_b32 s25, v148
	v_lshl_add_u64 v[236:237], v[234:235], 0, s[90:91]
	s_mov_b32 m0, s25
	s_nop 0
	global_load_lds_dwordx4 v[236:237], off
	v_lshl_add_u64 v[236:237], v[140:141], 0, s[10:11]
	v_readfirstlane_b32 s25, v150
	v_add_u32_e32 v161, 0x2000, v150
	v_lshl_add_u64 v[250:251], v[236:237], 0, s[42:43]
	s_mov_b32 m0, s25
	v_lshl_add_u64 v[246:247], v[142:143], 0, s[10:11]
	v_readfirstlane_b32 s25, v161
	global_load_lds_dwordx4 v[250:251], off
	v_lshl_add_u64 v[250:251], v[246:247], 0, s[42:43]
	s_mov_b32 m0, s25
	s_nop 0
	global_load_lds_dwordx4 v[250:251], off
	s_waitcnt lgkmcnt(0)
	s_waitcnt vmcnt(8)
	s_barrier
	s_setprio 1
	v_mfma_f32_16x16x32_bf16 v[60:63], v[162:165], v[182:185], 0
	v_mfma_f32_16x16x32_bf16 v[56:59], v[170:173], v[182:185], 0
	v_mfma_f32_16x16x32_bf16 v[52:55], v[162:165], v[190:193], 0
	v_mfma_f32_16x16x32_bf16 v[48:51], v[170:173], v[190:193], 0
	v_mfma_f32_16x16x32_bf16 v[44:47], v[162:165], v[198:201], 0
	v_mfma_f32_16x16x32_bf16 v[40:43], v[170:173], v[198:201], 0
	v_mfma_f32_16x16x32_bf16 v[36:39], v[162:165], v[206:209], 0
	v_mfma_f32_16x16x32_bf16 v[32:35], v[170:173], v[206:209], 0
	v_mfma_f32_16x16x32_bf16 v[60:63], v[166:169], v[186:189], v[60:63]
	v_mfma_f32_16x16x32_bf16 v[56:59], v[174:177], v[186:189], v[56:59]
	v_mfma_f32_16x16x32_bf16 v[52:55], v[166:169], v[194:197], v[52:55]
	v_mfma_f32_16x16x32_bf16 v[48:51], v[174:177], v[194:197], v[48:51]
	v_mfma_f32_16x16x32_bf16 v[44:47], v[166:169], v[202:205], v[44:47]
	v_mfma_f32_16x16x32_bf16 v[40:43], v[174:177], v[202:205], v[40:43]
	v_mfma_f32_16x16x32_bf16 v[36:39], v[166:169], v[210:213], v[36:39]
	v_mfma_f32_16x16x32_bf16 v[32:35], v[174:177], v[210:213], v[32:35]
	v_mfma_f32_16x16x32_bf16 v[28:31], v[214:217], v[182:185], 0
	v_mfma_f32_16x16x32_bf16 v[24:27], v[230:233], v[182:185], 0
	v_mfma_f32_16x16x32_bf16 v[20:23], v[214:217], v[190:193], 0
	v_mfma_f32_16x16x32_bf16 v[16:19], v[230:233], v[190:193], 0
	v_mfma_f32_16x16x32_bf16 v[12:15], v[214:217], v[198:201], 0
	v_mfma_f32_16x16x32_bf16 v[8:11], v[230:233], v[198:201], 0
	v_mfma_f32_16x16x32_bf16 v[4:7], v[214:217], v[206:209], 0
	v_mfma_f32_16x16x32_bf16 v[0:3], v[230:233], v[206:209], 0
	v_mfma_f32_16x16x32_bf16 v[28:31], v[218:221], v[186:189], v[28:31]
	v_mfma_f32_16x16x32_bf16 v[24:27], v[238:241], v[186:189], v[24:27]
	v_mfma_f32_16x16x32_bf16 v[20:23], v[218:221], v[194:197], v[20:23]
	v_mfma_f32_16x16x32_bf16 v[16:19], v[238:241], v[194:197], v[16:19]
	v_mfma_f32_16x16x32_bf16 v[12:15], v[218:221], v[202:205], v[12:15]
	v_mfma_f32_16x16x32_bf16 v[8:11], v[238:241], v[202:205], v[8:11]
	s_setprio 2
	s_barrier
	v_mfma_f32_16x16x32_bf16 v[4:7], v[218:221], v[210:213], v[4:7]
	v_mfma_f32_16x16x32_bf16 v[0:3], v[238:241], v[210:213], v[0:3]
	s_setprio 0
	ds_read_b128 v[162:165], v149 offset:32768
	ds_read_b128 v[166:169], v149 offset:33792
	ds_read_b128 v[170:173], v149 offset:34816
	ds_read_b128 v[174:177], v149 offset:35840
	v_readfirstlane_b32 s25, v151
	v_lshl_add_u64 v[214:215], v[226:227], 0, s[44:45]
	s_mov_b32 m0, s25
	v_readfirstlane_b32 s25, v152
	ds_read_b128 v[182:185], v146 offset:32768
	ds_read_b128 v[186:189], v146 offset:33792
	ds_read_b128 v[190:193], v146 offset:34816
	ds_read_b128 v[194:197], v146 offset:35840
	ds_read_b128 v[198:201], v146 offset:36864
	ds_read_b128 v[202:205], v146 offset:37888
	ds_read_b128 v[206:209], v146 offset:38912
	ds_read_b128 v[210:213], v146 offset:39936
	global_load_lds_dwordx4 v[214:215], off
	v_lshl_add_u64 v[214:215], v[234:235], 0, s[44:45]
	s_mov_b32 m0, s25
	s_nop 0
	global_load_lds_dwordx4 v[214:215], off
	ds_read_b128 v[214:217], v149 offset:49152
	ds_read_b128 v[218:221], v149 offset:50176
	ds_read_b128 v[230:233], v149 offset:51200
	ds_read_b128 v[238:241], v149 offset:52224
	s_waitcnt lgkmcnt(0)
	s_waitcnt vmcnt(8)
	s_barrier
; #define STAGE_A(P, br, kt) do { const char* _base = (const char*)(((kt) < G.ksplit ? G.A1 : A2m) + (long)(br) * G.lda + (long)(kt) * BK); \
;     __builtin_amdgcn_global_load_lds((const unsigned*)(_base + aoff0), (unsigned*)((char*)(P) + sb0), 16, 0, 0); \
;     __builtin_amdgcn_global_load_lds((const unsigned*)(_base + aoff1), (unsigned*)((char*)(P) + sb1), 16, 0, 0); } while (0)
; #define STAGE_B(P, br, kt) do { const char* _base = (const char*)(G.Bt + (long)(br) * G.ldb + (long)(kt) * BK); \
;     __builtin_amdgcn_global_load_lds((const unsigned*)(_base + boff0), (unsigned*)((char*)(P) + sb0), 16, 0, 0); \
;     __builtin_amdgcn_global_load_lds((const unsigned*)(_base + boff1), (unsigned*)((char*)(P) + sb1), 16, 0, 0); } while (0)
; #define LDA(dst, b, h) for (int m = 0; m < 4; ++m) for (int k = 0; k < 2; ++k) \
;     dst[m][k] = *reinterpret_cast<const bf16x8*>(a_rd + ((b) * 2 + (h)) * (HT * 2) + m * 2048 + k * 1024)
; #define LDB(dst, b, h) for (int n = 0; n < 2; ++n) for (int k = 0; k < 2; ++k) \
;     dst[n][k] = *reinterpret_cast<const bf16x8*>(b_rd + ((b) * 2 + (h)) * (HT * 2) + n * 2048 + k * 1024)
; #define MMA(ai, bj, At_, Bt_) do { __builtin_amdgcn_s_setprio(1); \
;     for (int m = 0; m < 4; ++m) for (int n = 0; n < 2; ++n) for (int k = 0; k < 2; ++k) \
;       acc[ai][bj][m][n] = __builtin_amdgcn_mfma_f32_16x16x32_bf16(Bt_[n][k], At_[m][k], acc[ai][bj][m][n], 0, 0, 0); \
;     __builtin_amdgcn_s_setprio(0); } while (0)
; #define WAIT_V(n) asm volatile("s_waitcnt vmcnt(" #n ")" ::: "memory")
; #define WAIT_L(n) asm volatile("s_waitcnt lgkmcnt(" #n ")" ::: "memory")
; #define BAR __builtin_amdgcn_s_barrier()
; #define SCHED __builtin_amdgcn_sched_barrier(0)
;     ...
;     LDB(B0, 1, 0); SCHED; LDA(At, 1, 0); STAGE_A(SA(0, 1), brow + HALF, t + 2);
;     WAIT_L(8); BAR; WAIT_L(0); MMA(0, 0, At, B0); BAR; SCHED;
;     LDB(B1, 1, 1); STAGE_B(SB(1, 0), bcol, t + 3);
;     BAR; WAIT_L(0); MMA(0, 1, At, B1); BAR;
;     LDA(At, 1, 1); STAGE_A(SA(1, 0), brow, t + 3);
;     BAR; WAIT_L(0); MMA(1, 0, At, B0); BAR; SCHED;
;     STAGE_B(SB(1, 1), bcol + HALF, t + 3);
;     WAIT_V(6); BAR; MMA(1, 1, At, B1); BAR;
;   }
	s_setprio 1
	v_mfma_f32_16x16x32_bf16 v[124:127], v[162:165], v[182:185], v[124:127]
	v_mfma_f32_16x16x32_bf16 v[120:123], v[170:173], v[182:185], v[120:123]
	v_mfma_f32_16x16x32_bf16 v[116:119], v[162:165], v[190:193], v[116:119]
	v_mfma_f32_16x16x32_bf16 v[112:115], v[170:173], v[190:193], v[112:115]
	v_mfma_f32_16x16x32_bf16 v[108:111], v[162:165], v[198:201], v[108:111]
	v_mfma_f32_16x16x32_bf16 v[104:107], v[170:173], v[198:201], v[104:107]
	v_mfma_f32_16x16x32_bf16 v[100:103], v[162:165], v[206:209], v[100:103]
	v_mfma_f32_16x16x32_bf16 v[96:99], v[170:173], v[206:209], v[96:99]
	v_mfma_f32_16x16x32_bf16 v[124:127], v[166:169], v[186:189], v[124:127]
	v_mfma_f32_16x16x32_bf16 v[120:123], v[174:177], v[186:189], v[120:123]
	v_mfma_f32_16x16x32_bf16 v[116:119], v[166:169], v[194:197], v[116:119]
	v_mfma_f32_16x16x32_bf16 v[112:115], v[174:177], v[194:197], v[112:115]
	v_mfma_f32_16x16x32_bf16 v[108:111], v[166:169], v[202:205], v[108:111]
	v_mfma_f32_16x16x32_bf16 v[104:107], v[174:177], v[202:205], v[104:107]
	v_mfma_f32_16x16x32_bf16 v[100:103], v[166:169], v[210:213], v[100:103]
	v_mfma_f32_16x16x32_bf16 v[96:99], v[174:177], v[210:213], v[96:99]
	v_mfma_f32_16x16x32_bf16 v[92:95], v[214:217], v[182:185], v[92:95]
	v_mfma_f32_16x16x32_bf16 v[88:91], v[230:233], v[182:185], v[88:91]
	v_mfma_f32_16x16x32_bf16 v[84:87], v[214:217], v[190:193], v[84:87]
	v_mfma_f32_16x16x32_bf16 v[80:83], v[230:233], v[190:193], v[80:83]
	v_mfma_f32_16x16x32_bf16 v[76:79], v[214:217], v[198:201], v[76:79]
	v_mfma_f32_16x16x32_bf16 v[72:75], v[230:233], v[198:201], v[72:75]
	v_mfma_f32_16x16x32_bf16 v[68:71], v[214:217], v[206:209], v[68:71]
	v_mfma_f32_16x16x32_bf16 v[64:67], v[230:233], v[206:209], v[64:67]
	v_mfma_f32_16x16x32_bf16 v[92:95], v[218:221], v[186:189], v[92:95]
	v_mfma_f32_16x16x32_bf16 v[88:91], v[238:241], v[186:189], v[88:91]
	v_mfma_f32_16x16x32_bf16 v[84:87], v[218:221], v[194:197], v[84:87]
	v_mfma_f32_16x16x32_bf16 v[80:83], v[238:241], v[194:197], v[80:83]
	v_mfma_f32_16x16x32_bf16 v[76:79], v[218:221], v[202:205], v[76:79]
	v_mfma_f32_16x16x32_bf16 v[72:75], v[238:241], v[202:205], v[72:75]
	s_setprio 2
	s_barrier
	v_mfma_f32_16x16x32_bf16 v[68:71], v[218:221], v[210:213], v[68:71]
	v_mfma_f32_16x16x32_bf16 v[64:67], v[238:241], v[210:213], v[64:67]
	s_setprio 0
	v_readfirstlane_b32 s25, v153
	v_lshl_add_u64 v[178:179], v[178:179], 0, s[46:47]
	s_mov_b32 m0, s25
	v_readfirstlane_b32 s25, v154
	global_load_lds_dwordx4 v[178:179], off
	v_lshl_add_u64 v[178:179], v[222:223], 0, s[46:47]
	s_mov_b32 m0, s25
	s_nop 0
	global_load_lds_dwordx4 v[178:179], off
	s_cmp_lt_u32 s24, 13
	s_cselect_b32 s27, s30, s36
	s_cselect_b32 s26, s29, s35
	v_lshl_add_u64 v[178:179], s[26:27], 0, v[136:137]
	v_lshl_add_u64 v[178:179], v[178:179], 0, s[10:11]
	v_readfirstlane_b32 s25, v155
	v_lshl_add_u64 v[178:179], v[178:179], 0, s[88:89]
	s_mov_b32 m0, s25
	ds_read_b128 v[182:185], v146 offset:49152
	ds_read_b128 v[186:189], v146 offset:50176
	ds_read_b128 v[190:193], v146 offset:51200
	ds_read_b128 v[194:197], v146 offset:52224
	ds_read_b128 v[198:201], v146 offset:53248
	ds_read_b128 v[202:205], v146 offset:54272
	ds_read_b128 v[206:209], v146 offset:55296
	ds_read_b128 v[210:213], v146 offset:56320
	global_load_lds_dwordx4 v[178:179], off
	v_lshl_add_u64 v[178:179], s[26:27], 0, v[138:139]
	v_lshl_add_u64 v[178:179], v[178:179], 0, s[10:11]
	v_readfirstlane_b32 s25, v156
	v_lshl_add_u64 v[178:179], v[178:179], 0, s[88:89]
	s_mov_b32 m0, s25
	s_nop 0
	global_load_lds_dwordx4 v[178:179], off
	v_readfirstlane_b32 s25, v157
	v_lshl_add_u64 v[250:251], v[236:237], 0, s[48:49]
	s_mov_b32 m0, s25
	v_readfirstlane_b32 s25, v158
	global_load_lds_dwordx4 v[250:251], off
	v_lshl_add_u64 v[250:251], v[246:247], 0, s[48:49]
	s_mov_b32 m0, s25
	s_nop 0
	global_load_lds_dwordx4 v[250:251], off
	s_waitcnt lgkmcnt(0)
	s_waitcnt vmcnt(8)
	s_barrier
	s_setprio 1
	v_mfma_f32_16x16x32_bf16 v[60:63], v[162:165], v[182:185], v[60:63]
	v_mfma_f32_16x16x32_bf16 v[56:59], v[170:173], v[182:185], v[56:59]
	v_mfma_f32_16x16x32_bf16 v[52:55], v[162:165], v[190:193], v[52:55]
	v_mfma_f32_16x16x32_bf16 v[48:51], v[170:173], v[190:193], v[48:51]
	v_mfma_f32_16x16x32_bf16 v[44:47], v[162:165], v[198:201], v[44:47]
	v_mfma_f32_16x16x32_bf16 v[40:43], v[170:173], v[198:201], v[40:43]
	v_mfma_f32_16x16x32_bf16 v[36:39], v[162:165], v[206:209], v[36:39]
	v_mfma_f32_16x16x32_bf16 v[32:35], v[170:173], v[206:209], v[32:35]
	v_mfma_f32_16x16x32_bf16 v[60:63], v[166:169], v[186:189], v[60:63]
	v_mfma_f32_16x16x32_bf16 v[56:59], v[174:177], v[186:189], v[56:59]
	v_mfma_f32_16x16x32_bf16 v[52:55], v[166:169], v[194:197], v[52:55]
	v_mfma_f32_16x16x32_bf16 v[48:51], v[174:177], v[194:197], v[48:51]
	v_mfma_f32_16x16x32_bf16 v[44:47], v[166:169], v[202:205], v[44:47]
	v_mfma_f32_16x16x32_bf16 v[40:43], v[174:177], v[202:205], v[40:43]
	v_mfma_f32_16x16x32_bf16 v[36:39], v[166:169], v[210:213], v[36:39]
	v_mfma_f32_16x16x32_bf16 v[32:35], v[174:177], v[210:213], v[32:35]
	v_mfma_f32_16x16x32_bf16 v[28:31], v[214:217], v[182:185], v[28:31]
	v_mfma_f32_16x16x32_bf16 v[24:27], v[230:233], v[182:185], v[24:27]
	v_mfma_f32_16x16x32_bf16 v[20:23], v[214:217], v[190:193], v[20:23]
	v_mfma_f32_16x16x32_bf16 v[16:19], v[230:233], v[190:193], v[16:19]
	v_mfma_f32_16x16x32_bf16 v[12:15], v[214:217], v[198:201], v[12:15]
	v_mfma_f32_16x16x32_bf16 v[8:11], v[230:233], v[198:201], v[8:11]
	v_mfma_f32_16x16x32_bf16 v[4:7], v[214:217], v[206:209], v[4:7]
	v_mfma_f32_16x16x32_bf16 v[0:3], v[230:233], v[206:209], v[0:3]
	v_mfma_f32_16x16x32_bf16 v[28:31], v[218:221], v[186:189], v[28:31]
	v_mfma_f32_16x16x32_bf16 v[24:27], v[238:241], v[186:189], v[24:27]
	v_mfma_f32_16x16x32_bf16 v[20:23], v[218:221], v[194:197], v[20:23]
	v_mfma_f32_16x16x32_bf16 v[16:19], v[238:241], v[194:197], v[16:19]
	v_mfma_f32_16x16x32_bf16 v[12:15], v[218:221], v[202:205], v[12:15]
	v_mfma_f32_16x16x32_bf16 v[8:11], v[238:241], v[202:205], v[8:11]
	s_setprio 2
	s_barrier
	v_mfma_f32_16x16x32_bf16 v[4:7], v[218:221], v[210:213], v[4:7]
	v_mfma_f32_16x16x32_bf16 v[0:3], v[238:241], v[210:213], v[0:3]
	s_setprio 0
	s_add_u32 s10, s10, 0x100
	s_addc_u32 s11, s11, 0
	s_cmp_lt_u32 s24, 28
	s_cbranch_scc0 .Lmy_kexit_1

; #define STAGE_A(P, br, kt) do { const char* _base = (const char*)(((kt) < G.ksplit ? G.A1 : A2m) + (long)(br) * G.lda + (long)(kt) * BK); \
;     __builtin_amdgcn_global_load_lds((const unsigned*)(_base + aoff0), (unsigned*)((char*)(P) + sb0), 16, 0, 0); \
;     __builtin_amdgcn_global_load_lds((const unsigned*)(_base + aoff1), (unsigned*)((char*)(P) + sb1), 16, 0, 0); } while (0)
; #define LDA(dst, b, h) for (int m = 0; m < 4; ++m) for (int k = 0; k < 2; ++k) \
;     dst[m][k] = *reinterpret_cast<const bf16x8*>(a_rd + ((b) * 2 + (h)) * (HT * 2) + m * 2048 + k * 1024)
; #define LDB(dst, b, h) for (int n = 0; n < 2; ++n) for (int k = 0; k < 2; ++k) \
;     dst[n][k] = *reinterpret_cast<const bf16x8*>(b_rd + ((b) * 2 + (h)) * (HT * 2) + n * 2048 + k * 1024)
; #define MMA(ai, bj, At_, Bt_) do { __builtin_amdgcn_s_setprio(1); \
;     for (int m = 0; m < 4; ++m) for (int n = 0; n < 2; ++n) for (int k = 0; k < 2; ++k) \
;       acc[ai][bj][m][n] = __builtin_amdgcn_mfma_f32_16x16x32_bf16(Bt_[n][k], At_[m][k], acc[ai][bj][m][n], 0, 0, 0); \
;     __builtin_amdgcn_s_setprio(0); } while (0)
; #define WAIT_V(n) asm volatile("s_waitcnt vmcnt(" #n ")" ::: "memory")
; #define WAIT_L(n) asm volatile("s_waitcnt lgkmcnt(" #n ")" ::: "memory")
; #define BAR __builtin_amdgcn_s_barrier()
;     ...
;   { LDB(B0, 0, 0); LDA(At, 0, 0); STAGE_A(SA(1, 1), brow + HALF, nt - 1);
;     BAR; WAIT_L(0); MMA(0, 0, At, B0); BAR;
;     LDB(B1, 0, 1); BAR; WAIT_L(0); MMA(0, 1, At, B1); BAR;
;     LDA(At, 0, 1); WAIT_V(4); BAR; WAIT_L(0); MMA(1, 0, At, B0); MMA(1, 1, At, B1); BAR; }
;   { LDB(B0, 1, 0); LDA(At, 1, 0); WAIT_V(2); BAR; WAIT_L(0); MMA(0, 0, At, B0); BAR;
.Lmy_kexit_1:
	s_waitcnt vmcnt(6)
	v_not_b32_e32 v250, 63
	v_mov_b32_e32 v251, 0x41b17218
	s_lshl_b64 s[8:9], s[8:9], 1
	s_add_u32 s8, s35, s8
	s_addc_u32 s9, s36, s9
	v_lshl_add_u64 v[130:131], s[8:9], 0, v[130:131]
	s_mov_b64 s[24:25], 0xf80
	v_readfirstlane_b32 s10, v159
	v_lshl_add_u64 v[130:131], v[130:131], 0, s[24:25]
	s_mov_b32 m0, s10
	v_lshl_add_u64 v[128:129], s[8:9], 0, v[128:129]
	v_readfirstlane_b32 s8, v160
	ds_read_b128 v[132:135], v149
	ds_read_b128 v[136:139], v149 offset:1024
	ds_read_b128 v[140:143], v149 offset:2048
	ds_read_b128 v[150:153], v149 offset:3072
	ds_read_b128 v[154:157], v146
	ds_read_b128 v[162:165], v146 offset:1024
	ds_read_b128 v[166:169], v146 offset:2048
	ds_read_b128 v[170:173], v146 offset:3072
	ds_read_b128 v[174:177], v146 offset:4096
	ds_read_b128 v[182:185], v146 offset:5120
	ds_read_b128 v[186:189], v146 offset:6144
	ds_read_b128 v[190:193], v146 offset:7168
	global_load_lds_dwordx4 v[130:131], off
	v_lshl_add_u64 v[128:129], v[128:129], 0, s[24:25]
	s_mov_b32 m0, s8
	s_nop 0
	global_load_lds_dwordx4 v[128:129], off
	s_barrier
	s_waitcnt lgkmcnt(0)
	s_setprio 1
	s_waitcnt lgkmcnt(0)
	v_mfma_f32_16x16x32_bf16 v[124:127], v[132:135], v[154:157], v[124:127]
	v_mfma_f32_16x16x32_bf16 v[120:123], v[140:143], v[154:157], v[120:123]
	v_mfma_f32_16x16x32_bf16 v[116:119], v[132:135], v[166:169], v[116:119]
	v_mfma_f32_16x16x32_bf16 v[112:115], v[140:143], v[166:169], v[112:115]
	v_mfma_f32_16x16x32_bf16 v[108:111], v[132:135], v[174:177], v[108:111]
	v_mfma_f32_16x16x32_bf16 v[104:107], v[140:143], v[174:177], v[104:107]
	v_mfma_f32_16x16x32_bf16 v[100:103], v[132:135], v[186:189], v[100:103]
	v_mfma_f32_16x16x32_bf16 v[96:99], v[140:143], v[186:189], v[96:99]
	v_mfma_f32_16x16x32_bf16 v[124:127], v[136:139], v[162:165], v[124:127]
	v_mfma_f32_16x16x32_bf16 v[120:123], v[150:153], v[162:165], v[120:123]
	v_mfma_f32_16x16x32_bf16 v[116:119], v[136:139], v[170:173], v[116:119]
	v_mfma_f32_16x16x32_bf16 v[112:115], v[150:153], v[170:173], v[112:115]
	v_mfma_f32_16x16x32_bf16 v[108:111], v[136:139], v[182:185], v[108:111]
	v_mfma_f32_16x16x32_bf16 v[104:107], v[150:153], v[182:185], v[104:107]
	s_setprio 2
	s_barrier
	v_mfma_f32_16x16x32_bf16 v[100:103], v[136:139], v[190:193], v[100:103]
	v_mfma_f32_16x16x32_bf16 v[96:99], v[150:153], v[190:193], v[96:99]
	s_setprio 0
	ds_read_b128 v[128:131], v149 offset:16384
	ds_read_b128 v[158:161], v149 offset:17408
	ds_read_b128 v[194:197], v149 offset:18432
	ds_read_b128 v[198:201], v149 offset:19456
	s_barrier
	s_waitcnt lgkmcnt(0)
	s_setprio 1
	s_waitcnt lgkmcnt(0)
	v_mfma_f32_16x16x32_bf16 v[92:95], v[128:131], v[154:157], v[92:95]
	v_mfma_f32_16x16x32_bf16 v[88:91], v[194:197], v[154:157], v[88:91]
	v_mfma_f32_16x16x32_bf16 v[84:87], v[128:131], v[166:169], v[84:87]
	v_mfma_f32_16x16x32_bf16 v[80:83], v[194:197], v[166:169], v[80:83]
	v_mfma_f32_16x16x32_bf16 v[76:79], v[128:131], v[174:177], v[76:79]
	v_mfma_f32_16x16x32_bf16 v[72:75], v[194:197], v[174:177], v[72:75]
	v_mfma_f32_16x16x32_bf16 v[68:71], v[128:131], v[186:189], v[68:71]
	v_mfma_f32_16x16x32_bf16 v[64:67], v[194:197], v[186:189], v[64:67]
	v_mfma_f32_16x16x32_bf16 v[202:205], v[158:161], v[162:165], v[92:95]
	v_mfma_f32_16x16x32_bf16 v[154:157], v[198:201], v[162:165], v[88:91]
	v_mfma_f32_16x16x32_bf16 v[162:165], v[158:161], v[170:173], v[84:87]
	v_mfma_f32_16x16x32_bf16 v[166:169], v[198:201], v[170:173], v[80:83]
	v_mfma_f32_16x16x32_bf16 v[170:173], v[158:161], v[182:185], v[76:79]
	v_mfma_f32_16x16x32_bf16 v[174:177], v[198:201], v[182:185], v[72:75]
	s_setprio 2
	s_barrier
	v_mfma_f32_16x16x32_bf16 v[182:185], v[158:161], v[190:193], v[68:71]
	v_mfma_f32_16x16x32_bf16 v[186:189], v[198:201], v[190:193], v[64:67]
	s_setprio 0
	s_nop 0
	ds_read_b128 v[64:67], v146 offset:16384
	ds_read_b128 v[68:71], v146 offset:17408
	ds_read_b128 v[72:75], v146 offset:18432
	ds_read_b128 v[76:79], v146 offset:19456
	ds_read_b128 v[80:83], v146 offset:20480
	ds_read_b128 v[84:87], v146 offset:21504
	ds_read_b128 v[88:91], v146 offset:22528
	ds_read_b128 v[92:95], v146 offset:23552
	s_waitcnt vmcnt(4)
	s_barrier
	s_waitcnt lgkmcnt(0)
	s_setprio 1
	s_waitcnt lgkmcnt(0)
	v_mfma_f32_16x16x32_bf16 v[60:63], v[132:135], v[64:67], v[60:63]
	v_mfma_f32_16x16x32_bf16 v[56:59], v[140:143], v[64:67], v[56:59]
	v_mfma_f32_16x16x32_bf16 v[52:55], v[132:135], v[72:75], v[52:55]
	v_mfma_f32_16x16x32_bf16 v[48:51], v[140:143], v[72:75], v[48:51]
	v_mfma_f32_16x16x32_bf16 v[44:47], v[132:135], v[80:83], v[44:47]
	v_mfma_f32_16x16x32_bf16 v[40:43], v[140:143], v[80:83], v[40:43]
	v_mfma_f32_16x16x32_bf16 v[36:39], v[132:135], v[88:91], v[36:39]
	v_mfma_f32_16x16x32_bf16 v[32:35], v[140:143], v[88:91], v[32:35]
	v_mfma_f32_16x16x32_bf16 v[60:63], v[136:139], v[68:71], v[60:63]
	v_mfma_f32_16x16x32_bf16 v[56:59], v[150:153], v[68:71], v[56:59]
	v_mfma_f32_16x16x32_bf16 v[52:55], v[136:139], v[76:79], v[52:55]
	v_mfma_f32_16x16x32_bf16 v[48:51], v[150:153], v[76:79], v[48:51]
	v_mfma_f32_16x16x32_bf16 v[44:47], v[136:139], v[84:87], v[44:47]
	v_mfma_f32_16x16x32_bf16 v[40:43], v[150:153], v[84:87], v[40:43]
	v_mfma_f32_16x16x32_bf16 v[36:39], v[136:139], v[92:95], v[36:39]
	v_mfma_f32_16x16x32_bf16 v[32:35], v[150:153], v[92:95], v[32:35]
	s_setprio 0
	s_setprio 1
	v_mfma_f32_16x16x32_bf16 v[28:31], v[128:131], v[64:67], v[28:31]
	v_mfma_f32_16x16x32_bf16 v[24:27], v[194:197], v[64:67], v[24:27]
	v_mfma_f32_16x16x32_bf16 v[20:23], v[128:131], v[72:75], v[20:23]
	v_mfma_f32_16x16x32_bf16 v[16:19], v[194:197], v[72:75], v[16:19]
	v_mfma_f32_16x16x32_bf16 v[12:15], v[128:131], v[80:83], v[12:15]
	v_mfma_f32_16x16x32_bf16 v[8:11], v[194:197], v[80:83], v[8:11]
	v_mfma_f32_16x16x32_bf16 v[4:7], v[128:131], v[88:91], v[4:7]
	v_mfma_f32_16x16x32_bf16 v[0:3], v[194:197], v[88:91], v[0:3]
	v_mfma_f32_16x16x32_bf16 v[132:135], v[158:161], v[68:71], v[28:31]
	v_mfma_f32_16x16x32_bf16 v[136:139], v[198:201], v[68:71], v[24:27]
	v_mfma_f32_16x16x32_bf16 v[140:143], v[158:161], v[76:79], v[20:23]
	v_mfma_f32_16x16x32_bf16 v[150:153], v[198:201], v[76:79], v[16:19]
	v_mfma_f32_16x16x32_bf16 v[190:193], v[158:161], v[84:87], v[12:15]
	v_mfma_f32_16x16x32_bf16 v[206:209], v[198:201], v[84:87], v[8:11]
	s_setprio 2
	s_barrier
; #define LDA(dst, b, h) for (int m = 0; m < 4; ++m) for (int k = 0; k < 2; ++k) \
;     dst[m][k] = *reinterpret_cast<const bf16x8*>(a_rd + ((b) * 2 + (h)) * (HT * 2) + m * 2048 + k * 1024)
; #define LDB(dst, b, h) for (int n = 0; n < 2; ++n) for (int k = 0; k < 2; ++k) \
;     dst[n][k] = *reinterpret_cast<const bf16x8*>(b_rd + ((b) * 2 + (h)) * (HT * 2) + n * 2048 + k * 1024)
; #define MMA(ai, bj, At_, Bt_) do { __builtin_amdgcn_s_setprio(1); \
;     for (int m = 0; m < 4; ++m) for (int n = 0; n < 2; ++n) for (int k = 0; k < 2; ++k) \
;       acc[ai][bj][m][n] = __builtin_amdgcn_mfma_f32_16x16x32_bf16(Bt_[n][k], At_[m][k], acc[ai][bj][m][n], 0, 0, 0); \
;     __builtin_amdgcn_s_setprio(0); } while (0)
; #define WAIT_V(n) asm volatile("s_waitcnt vmcnt(" #n ")" ::: "memory")
; #define WAIT_L(n) asm volatile("s_waitcnt lgkmcnt(" #n ")" ::: "memory")
; #define BAR __builtin_amdgcn_s_barrier()
;     ...
;     LDA(At, 0, 1); WAIT_V(4); BAR; WAIT_L(0); MMA(1, 0, At, B0); MMA(1, 1, At, B1); BAR; }
;   { LDB(B0, 1, 0); LDA(At, 1, 0); WAIT_V(2); BAR; WAIT_L(0); MMA(0, 0, At, B0); BAR;
;     LDB(B1, 1, 1); WAIT_V(0); BAR; WAIT_L(0); MMA(0, 1, At, B1); BAR;
;     LDA(At, 1, 1); BAR; WAIT_L(0); MMA(1, 0, At, B0); MMA(1, 1, At, B1); BAR; }
;   if (wr == 0) BAR;
	v_mfma_f32_16x16x32_bf16 v[128:131], v[158:161], v[92:95], v[4:7]
	v_mfma_f32_16x16x32_bf16 v[158:161], v[198:201], v[92:95], v[0:3]
	s_setprio 0
	ds_read_b128 v[24:27], v149 offset:32768
	ds_read_b128 v[28:31], v149 offset:33792
	ds_read_b128 v[194:197], v149 offset:34816
	ds_read_b128 v[198:201], v149 offset:35840
	ds_read_b128 v[0:3], v146 offset:32768
	ds_read_b128 v[4:7], v146 offset:33792
	ds_read_b128 v[8:11], v146 offset:34816
	ds_read_b128 v[12:15], v146 offset:35840
	ds_read_b128 v[16:19], v146 offset:36864
	ds_read_b128 v[20:23], v146 offset:37888
	ds_read_b128 v[210:213], v146 offset:38912
	ds_read_b128 v[214:217], v146 offset:39936
	s_waitcnt vmcnt(2)
	s_barrier
	s_waitcnt lgkmcnt(0)
	s_setprio 1
	s_waitcnt lgkmcnt(0)
	v_mfma_f32_16x16x32_bf16 v[64:67], v[24:27], v[0:3], v[124:127]
	v_mfma_f32_16x16x32_bf16 v[68:71], v[194:197], v[0:3], v[120:123]
	v_mfma_f32_16x16x32_bf16 v[72:75], v[24:27], v[8:11], v[116:119]
	v_mfma_f32_16x16x32_bf16 v[76:79], v[194:197], v[8:11], v[112:115]
	v_mfma_f32_16x16x32_bf16 v[80:83], v[24:27], v[16:19], v[108:111]
	v_mfma_f32_16x16x32_bf16 v[84:87], v[194:197], v[16:19], v[104:107]
	v_mfma_f32_16x16x32_bf16 v[88:91], v[24:27], v[210:213], v[100:103]
	v_mfma_f32_16x16x32_bf16 v[92:95], v[194:197], v[210:213], v[96:99]
	v_mfma_f32_16x16x32_bf16 v[64:67], v[28:31], v[4:7], v[64:67]
	v_mfma_f32_16x16x32_bf16 v[68:71], v[198:201], v[4:7], v[68:71]
	v_mfma_f32_16x16x32_bf16 v[72:75], v[28:31], v[12:15], v[72:75]
	v_mfma_f32_16x16x32_bf16 v[76:79], v[198:201], v[12:15], v[76:79]
	v_mfma_f32_16x16x32_bf16 v[80:83], v[28:31], v[20:23], v[80:83]
	v_mfma_f32_16x16x32_bf16 v[84:87], v[198:201], v[20:23], v[84:87]
	s_setprio 2
	s_barrier
	v_mfma_f32_16x16x32_bf16 v[88:91], v[28:31], v[214:217], v[88:91]
	v_mfma_f32_16x16x32_bf16 v[92:95], v[198:201], v[214:217], v[92:95]
	s_setprio 0
	ds_read_b128 v[218:221], v149 offset:49152
	ds_read_b128 v[230:233], v149 offset:50176
	ds_read_b128 v[238:241], v149 offset:51200
	ds_read_b128 v[246:249], v149 offset:52224
	s_waitcnt vmcnt(0)
	s_barrier
	s_waitcnt lgkmcnt(0)
	s_setprio 1
	s_waitcnt lgkmcnt(0)
	v_mfma_f32_16x16x32_bf16 v[96:99], v[218:221], v[0:3], v[202:205]
	v_mfma_f32_16x16x32_bf16 v[0:3], v[238:241], v[0:3], v[154:157]
	v_mfma_f32_16x16x32_bf16 v[100:103], v[246:249], v[4:7], v[0:3]
	v_mfma_f32_16x16x32_bf16 v[0:3], v[218:221], v[8:11], v[162:165]
	v_mfma_f32_16x16x32_bf16 v[104:107], v[230:233], v[12:15], v[0:3]
	v_mfma_f32_16x16x32_bf16 v[0:3], v[238:241], v[8:11], v[166:169]
	v_mfma_f32_16x16x32_bf16 v[108:111], v[246:249], v[12:15], v[0:3]
	v_mfma_f32_16x16x32_bf16 v[0:3], v[218:221], v[16:19], v[170:173]
	v_mfma_f32_16x16x32_bf16 v[112:115], v[230:233], v[20:23], v[0:3]
	v_mfma_f32_16x16x32_bf16 v[0:3], v[238:241], v[16:19], v[174:177]
	v_mfma_f32_16x16x32_bf16 v[116:119], v[246:249], v[20:23], v[0:3]
	v_mfma_f32_16x16x32_bf16 v[0:3], v[218:221], v[210:213], v[182:185]
	v_mfma_f32_16x16x32_bf16 v[120:123], v[230:233], v[214:217], v[0:3]
	v_mfma_f32_16x16x32_bf16 v[0:3], v[238:241], v[210:213], v[186:189]
	s_setprio 2
	s_barrier
	v_mfma_f32_16x16x32_bf16 v[96:99], v[230:233], v[4:7], v[96:99]
	v_mfma_f32_16x16x32_bf16 v[124:127], v[246:249], v[214:217], v[0:3]
	s_setprio 0
	ds_read_b128 v[154:157], v146 offset:49152
	ds_read_b128 v[162:165], v146 offset:50176
	ds_read_b128 v[166:169], v146 offset:51200
	ds_read_b128 v[170:173], v146 offset:52224
	ds_read_b128 v[174:177], v146 offset:53248
	ds_read_b128 v[182:185], v146 offset:54272
	ds_read_b128 v[186:189], v146 offset:55296
	ds_read_b128 v[146:149], v146 offset:56320
	s_barrier
	s_waitcnt lgkmcnt(0)
	s_setprio 1
	s_waitcnt lgkmcnt(0)
	v_mfma_f32_16x16x32_bf16 v[0:3], v[24:27], v[154:157], v[60:63]
	v_mfma_f32_16x16x32_bf16 v[8:11], v[24:27], v[166:169], v[52:55]
	v_mfma_f32_16x16x32_bf16 v[16:19], v[24:27], v[174:177], v[44:47]
	v_mfma_f32_16x16x32_bf16 v[24:27], v[24:27], v[186:189], v[36:39]
	v_mfma_f32_16x16x32_bf16 v[0:3], v[28:31], v[162:165], v[0:3]
	v_mfma_f32_16x16x32_bf16 v[4:7], v[194:197], v[154:157], v[56:59]
	v_mfma_f32_16x16x32_bf16 v[8:11], v[28:31], v[170:173], v[8:11]
	v_mfma_f32_16x16x32_bf16 v[12:15], v[194:197], v[166:169], v[48:51]
	v_mfma_f32_16x16x32_bf16 v[16:19], v[28:31], v[182:185], v[16:19]
	v_mfma_f32_16x16x32_bf16 v[20:23], v[194:197], v[174:177], v[40:43]
	v_mfma_f32_16x16x32_bf16 v[24:27], v[28:31], v[146:149], v[24:27]
	v_mfma_f32_16x16x32_bf16 v[28:31], v[194:197], v[186:189], v[32:35]
	v_mfma_f32_16x16x32_bf16 v[4:7], v[198:201], v[162:165], v[4:7]
	v_mfma_f32_16x16x32_bf16 v[12:15], v[198:201], v[170:173], v[12:15]
	v_mfma_f32_16x16x32_bf16 v[20:23], v[198:201], v[182:185], v[20:23]
	v_mfma_f32_16x16x32_bf16 v[28:31], v[198:201], v[146:149], v[28:31]
	s_setprio 0
	s_setprio 1
	v_mfma_f32_16x16x32_bf16 v[32:35], v[218:221], v[154:157], v[132:135]
	v_mfma_f32_16x16x32_bf16 v[36:39], v[238:241], v[154:157], v[136:139]
	v_mfma_f32_16x16x32_bf16 v[40:43], v[218:221], v[166:169], v[140:143]
	v_mfma_f32_16x16x32_bf16 v[44:47], v[238:241], v[166:169], v[150:153]
	v_mfma_f32_16x16x32_bf16 v[48:51], v[218:221], v[174:177], v[190:193]
	v_mfma_f32_16x16x32_bf16 v[52:55], v[238:241], v[174:177], v[206:209]
	v_mfma_f32_16x16x32_bf16 v[56:59], v[218:221], v[186:189], v[128:131]
	v_mfma_f32_16x16x32_bf16 v[60:63], v[238:241], v[186:189], v[158:161]
	v_mfma_f32_16x16x32_bf16 v[32:35], v[230:233], v[162:165], v[32:35]
	v_mfma_f32_16x16x32_bf16 v[36:39], v[246:249], v[162:165], v[36:39]
	v_mfma_f32_16x16x32_bf16 v[40:43], v[230:233], v[170:173], v[40:43]
	v_mfma_f32_16x16x32_bf16 v[44:47], v[246:249], v[170:173], v[44:47]
	v_mfma_f32_16x16x32_bf16 v[48:51], v[230:233], v[182:185], v[48:51]
	v_mfma_f32_16x16x32_bf16 v[52:55], v[246:249], v[182:185], v[52:55]
	s_setprio 2
	s_barrier
	v_mfma_f32_16x16x32_bf16 v[56:59], v[230:233], v[146:149], v[56:59]
	v_mfma_f32_16x16x32_bf16 v[60:63], v[246:249], v[146:149], v[60:63]
	s_setprio 0
	v_cmp_gt_u32_e32 vcc, s60, v144
	s_and_saveexec_b64 s[8:9], vcc
	s_cbranch_execz .LBB0_1804
	s_barrier

; #define STAGE_A(P, br, kt) do { const char* _base = (const char*)(((kt) < G.ksplit ? G.A1 : A2m) + (long)(br) * G.lda + (long)(kt) * BK); \
;     __builtin_amdgcn_global_load_lds((const unsigned*)(_base + aoff0), (unsigned*)((char*)(P) + sb0), 16, 0, 0); \
;     __builtin_amdgcn_global_load_lds((const unsigned*)(_base + aoff1), (unsigned*)((char*)(P) + sb1), 16, 0, 0); } while (0)
; #define STAGE_B(P, br, kt) do { const char* _base = (const char*)(G.Bt + (long)(br) * G.ldb + (long)(kt) * BK); \
;     __builtin_amdgcn_global_load_lds((const unsigned*)(_base + boff0), (unsigned*)((char*)(P) + sb0), 16, 0, 0); \
;     __builtin_amdgcn_global_load_lds((const unsigned*)(_base + boff1), (unsigned*)((char*)(P) + sb1), 16, 0, 0); } while (0)
; #define LDA(dst, b, h) for (int m = 0; m < 4; ++m) for (int k = 0; k < 2; ++k) \
;     dst[m][k] = *reinterpret_cast<const bf16x8*>(a_rd + ((b) * 2 + (h)) * (HT * 2) + m * 2048 + k * 1024)
; #define BAR __builtin_amdgcn_s_barrier()
;     ...
;   const int sb0 = t1 * 16, sb1 = sb0 + 8192;
;   const int swz_ = lds_byte(fr, fq * 8);
;   const char* a_rd = shmc + wr * 8192 + swz_;
;   const char* b_rd = shmc + 4 * (HT * 2) + wc * 4096 + swz_;
;   int r0_, c0_, r1_, c1_; stage_rc(sb0, r0_, c0_); stage_rc(sb1, r1_, c1_);
;   const unsigned aoff0 = (unsigned)(r0_ * G.lda + c0_) * 2u, aoff1 = (unsigned)(r1_ * G.lda + c1_) * 2u;
;   const unsigned boff0 = (unsigned)(r0_ * G.ldb + c0_) * 2u, boff1 = (unsigned)(r1_ * G.ldb + c1_) * 2u;
;   f32x4 acc[2][2][4][2] = {};
;   bf16x8 At[4][2], B0[2][2], B1[2][2];
;   const int nt = K / BK;
;   if (EPI == EPI_RESID || first) {
;     STAGE_B(SB(0, 0), bcol, 0); STAGE_A(SA(0, 0), brow, 0);
;     STAGE_B(SB(0, 1), bcol + HALF, 0); STAGE_A(SA(0, 1), brow + HALF, 0);
;   }
;   if (wr == 1) BAR;
;   WAIT_V(0); BAR;
;   STAGE_B(SB(1, 0), bcol, 1); STAGE_A(SA(1, 0), brow, 1); STAGE_B(SB(1, 1), bcol + HALF, 1);
;   WAIT_V(6); BAR;
;   for (int t = 0; t < nt - 2; t += 2) {
;     LDB(B0, 0, 0); SCHED; LDA(At, 0, 0); STAGE_A(SA(1, 1), brow + HALF, t + 1);
;     WAIT_L(8); BAR; WAIT_L(0); MMA(0, 0, At, B0); BAR; SCHED;
;     LDB(B1, 0, 1); STAGE_B(SB(0, 0), bcol, t + 2);
;     BAR; WAIT_L(0); MMA(0, 1, At, B1); BAR;
;     LDA(At, 0, 1); STAGE_A(SA(0, 0), brow, t + 2);
;     BAR; WAIT_L(0); MMA(1, 0, At, B0); BAR; SCHED;
;     STAGE_B(SB(0, 1), bcol + HALF, t + 2);
;     WAIT_V(6); BAR; MMA(1, 1, At, B1); BAR;
.LBB0_1864:
	s_or_b64 exec, exec, s[24:25]
	v_and_b32_e32 v144, 15, v139
	v_lshlrev_b32_e32 v10, 2, v139
	s_ashr_i32 s27, s26, 31
	s_lshr_b32 s25, s30, 3
	v_and_b32_e32 v8, 48, v139
	v_lshlrev_b32_e32 v9, 6, v144
	v_and_b32_e32 v10, 32, v10
	s_add_i32 s30, 32, 0x10000
	s_lshl_b32 s24, s31, 8
	s_lshl_b64 s[26:27], s[26:27], 1
	v_bitop3_b32 v10, v9, v10, v8 bitop3:0x36
	v_lshlrev_b32_e32 v8, 6, v139
	s_add_u32 s44, s39, s26
	v_readlane_b32 s31, v253, 46
	v_and_b32_e32 v8, 0x3000, v8
	s_addc_u32 s45, s40, s27
	v_add_u32_e32 v145, s31, v142
	s_waitcnt vmcnt(0)
	v_add_u32_e32 v12, s30, v8
	v_lshl_add_u64 v[8:9], s[44:45], 0, v[180:181]
	s_mov_b64 s[46:47], 0x80
	v_readfirstlane_b32 s31, v145
	v_lshl_add_u64 v[8:9], v[8:9], 0, s[46:47]
	s_mov_b32 m0, s31
	v_mov_b32_e32 v129, v181
	v_add_u32_e32 v150, 0x2000, v145
	s_waitcnt vmcnt(0)
	s_barrier
	global_load_lds_dwordx4 v[8:9], off
	v_lshl_add_u64 v[8:9], s[44:45], 0, v[128:129]
	v_readfirstlane_b32 s31, v150
	s_add_u32 s42, s37, s42
	v_lshl_add_u64 v[8:9], v[8:9], 0, s[46:47]
	s_mov_b32 m0, s31
	s_addc_u32 s43, s38, s35
	v_add_u32_e32 v151, 0x8000, v147
	global_load_lds_dwordx4 v[8:9], off
	v_lshl_add_u64 v[8:9], s[42:43], 0, v[180:181]
	v_readfirstlane_b32 s31, v151
	v_add_u32_e32 v152, 0xa000, v147
	v_lshl_add_u64 v[8:9], v[8:9], 0, s[46:47]
	s_mov_b32 m0, s31
	v_readfirstlane_b32 s31, v152
	global_load_lds_dwordx4 v[8:9], off
	s_mov_b32 m0, s31
	s_or_b32 s31, s24, 0x80
	v_lshl_add_u64 v[8:9], s[42:43], 0, v[128:129]
	s_mul_i32 s42, s31, 0x840
	s_ashr_i32 s43, s42, 31
	s_lshl_b64 s[42:43], s[42:43], 1
	s_add_u32 s42, s39, s42
	v_readlane_b32 s31, v253, 47
	v_lshl_add_u64 v[8:9], v[8:9], 0, s[46:47]
	s_addc_u32 s43, s40, s43
	v_add_u32_e32 v153, s31, v142
	global_load_lds_dwordx4 v[8:9], off
	v_lshl_add_u64 v[8:9], s[42:43], 0, v[180:181]
	v_readfirstlane_b32 s31, v153
	v_lshl_add_u64 v[8:9], v[8:9], 0, s[46:47]
	s_mov_b32 m0, s31
	v_add_u32_e32 v154, 0x2000, v153
	global_load_lds_dwordx4 v[8:9], off
	v_lshl_add_u64 v[8:9], s[42:43], 0, v[128:129]
	v_readfirstlane_b32 s31, v154
	v_lshl_add_u64 v[8:9], v[8:9], 0, s[46:47]
	s_mov_b32 m0, s31
	v_lshl_add_u32 v11, v143, 13, 32
	global_load_lds_dwordx4 v[8:9], off
	v_lshrrev_b32_e32 v8, 1, v0
	v_mul_lo_u32 v0, v1, s62
	v_mad_u64_u32 v[0:1], s[42:43], v8, s84, v[0:1]
	v_or_b32_e32 v0, v0, v2
	v_add_lshl_u32 v0, v0, v3, 1
	v_lshrrev_b32_e32 v3, 1, v4
	v_mul_lo_u32 v2, v5, s62
	v_mad_u64_u32 v[2:3], s[42:43], v3, s84, v[2:3]
	v_or_b32_e32 v2, v2, v6
	s_waitcnt vmcnt(6)
	v_mov_b32_e32 v1, v181
	v_add_lshl_u32 v2, v2, v7, 1
	v_mov_b32_e32 v3, v181
	v_lshl_add_u64 v[130:131], s[26:27], 0, v[0:1]
	v_lshl_add_u64 v[132:133], s[26:27], 0, v[2:3]
	v_mad_i64_i32 v[134:135], s[26:27], s29, v243, v[0:1]
	v_mad_i64_i32 v[136:137], s[26:27], s29, v243, v[2:3]
	s_mov_b32 s31, -2
	v_add_u32_e32 v149, v12, v10
	v_add_u32_e32 v148, v11, v10
	s_mov_b64 s[26:27], s[10:11]
	s_mov_b64 s[42:43], 0x4360100
	s_mov_b64 s[44:45], 0x4360180
	s_mov_b64 s[46:47], 0x43e4100
	s_mov_b64 s[48:49], 0x43e4180
	s_barrier
	ds_read_b128 v[160:163], v149
	ds_read_b128 v[164:167], v149 offset:1024
	ds_read_b128 v[168:171], v149 offset:2048
	ds_read_b128 v[172:175], v149 offset:3072
	v_add_u32_e32 v158, 0xc000, v147
	v_lshl_add_u64 v[222:223], s[26:27], 0, v[134:135]
	v_readfirstlane_b32 s35, v158
	v_add_u32_e32 v159, 0xe000, v147
	v_lshl_add_u64 v[156:157], v[222:223], 0, s[94:95]
	s_mov_b32 m0, s35
	v_lshl_add_u64 v[230:231], s[26:27], 0, v[136:137]
	v_readfirstlane_b32 s35, v159
	ds_read_b128 v[176:179], v148
	ds_read_b128 v[182:185], v148 offset:1024
	ds_read_b128 v[186:189], v148 offset:2048
	ds_read_b128 v[190:193], v148 offset:3072
	ds_read_b128 v[194:197], v148 offset:4096
	ds_read_b128 v[198:201], v148 offset:5120
	ds_read_b128 v[202:205], v148 offset:6144
	ds_read_b128 v[206:209], v148 offset:7168
	global_load_lds_dwordx4 v[156:157], off
	v_lshl_add_u64 v[156:157], v[230:231], 0, s[94:95]
	s_mov_b32 m0, s35
	s_nop 0
	global_load_lds_dwordx4 v[156:157], off
	ds_read_b128 v[210:213], v149 offset:16384
	ds_read_b128 v[214:217], v149 offset:17408
	ds_read_b128 v[218:221], v149 offset:18432
	ds_read_b128 v[246:249], v149 offset:19456
	s_waitcnt lgkmcnt(0)
	s_waitcnt vmcnt(8)
	s_barrier
	s_setprio 1
	v_mfma_f32_16x16x32_bf16 v[124:127], v[160:163], v[176:179], 0
	v_mfma_f32_16x16x32_bf16 v[120:123], v[168:171], v[176:179], 0
	v_mfma_f32_16x16x32_bf16 v[116:119], v[160:163], v[186:189], 0
	v_mfma_f32_16x16x32_bf16 v[112:115], v[168:171], v[186:189], 0
	v_mfma_f32_16x16x32_bf16 v[108:111], v[160:163], v[194:197], 0
	v_mfma_f32_16x16x32_bf16 v[104:107], v[168:171], v[194:197], 0
	v_mfma_f32_16x16x32_bf16 v[100:103], v[160:163], v[202:205], 0
	v_mfma_f32_16x16x32_bf16 v[96:99], v[168:171], v[202:205], 0
	v_mfma_f32_16x16x32_bf16 v[124:127], v[164:167], v[182:185], v[124:127]
	v_mfma_f32_16x16x32_bf16 v[120:123], v[172:175], v[182:185], v[120:123]
	v_mfma_f32_16x16x32_bf16 v[116:119], v[164:167], v[190:193], v[116:119]
	v_mfma_f32_16x16x32_bf16 v[112:115], v[172:175], v[190:193], v[112:115]
	v_mfma_f32_16x16x32_bf16 v[108:111], v[164:167], v[198:201], v[108:111]
	v_mfma_f32_16x16x32_bf16 v[104:107], v[172:175], v[198:201], v[104:107]
	v_mfma_f32_16x16x32_bf16 v[100:103], v[164:167], v[206:209], v[100:103]
	v_mfma_f32_16x16x32_bf16 v[96:99], v[172:175], v[206:209], v[96:99]
	v_mfma_f32_16x16x32_bf16 v[92:95], v[210:213], v[176:179], 0
	v_mfma_f32_16x16x32_bf16 v[88:91], v[218:221], v[176:179], 0
	v_mfma_f32_16x16x32_bf16 v[84:87], v[210:213], v[186:189], 0
	v_mfma_f32_16x16x32_bf16 v[80:83], v[218:221], v[186:189], 0
	v_mfma_f32_16x16x32_bf16 v[76:79], v[210:213], v[194:197], 0
	v_mfma_f32_16x16x32_bf16 v[72:75], v[218:221], v[194:197], 0
	v_mfma_f32_16x16x32_bf16 v[68:71], v[210:213], v[202:205], 0
	v_mfma_f32_16x16x32_bf16 v[64:67], v[218:221], v[202:205], 0
	v_mfma_f32_16x16x32_bf16 v[92:95], v[214:217], v[182:185], v[92:95]
	v_mfma_f32_16x16x32_bf16 v[88:91], v[246:249], v[182:185], v[88:91]
	v_mfma_f32_16x16x32_bf16 v[84:87], v[214:217], v[190:193], v[84:87]
	v_mfma_f32_16x16x32_bf16 v[80:83], v[246:249], v[190:193], v[80:83]
	v_mfma_f32_16x16x32_bf16 v[76:79], v[214:217], v[198:201], v[76:79]
	v_mfma_f32_16x16x32_bf16 v[72:75], v[246:249], v[198:201], v[72:75]
	s_setprio 2
	s_barrier
; #define STAGE_A(P, br, kt) do { const char* _base = (const char*)(((kt) < G.ksplit ? G.A1 : A2m) + (long)(br) * G.lda + (long)(kt) * BK); \
;     __builtin_amdgcn_global_load_lds((const unsigned*)(_base + aoff0), (unsigned*)((char*)(P) + sb0), 16, 0, 0); \
;     __builtin_amdgcn_global_load_lds((const unsigned*)(_base + aoff1), (unsigned*)((char*)(P) + sb1), 16, 0, 0); } while (0)
; #define STAGE_B(P, br, kt) do { const char* _base = (const char*)(G.Bt + (long)(br) * G.ldb + (long)(kt) * BK); \
;     __builtin_amdgcn_global_load_lds((const unsigned*)(_base + boff0), (unsigned*)((char*)(P) + sb0), 16, 0, 0); \
;     __builtin_amdgcn_global_load_lds((const unsigned*)(_base + boff1), (unsigned*)((char*)(P) + sb1), 16, 0, 0); } while (0)
; #define LDA(dst, b, h) for (int m = 0; m < 4; ++m) for (int k = 0; k < 2; ++k) \
;     dst[m][k] = *reinterpret_cast<const bf16x8*>(a_rd + ((b) * 2 + (h)) * (HT * 2) + m * 2048 + k * 1024)
; #define LDB(dst, b, h) for (int n = 0; n < 2; ++n) for (int k = 0; k < 2; ++k) \
;     dst[n][k] = *reinterpret_cast<const bf16x8*>(b_rd + ((b) * 2 + (h)) * (HT * 2) + n * 2048 + k * 1024)
; #define MMA(ai, bj, At_, Bt_) do { __builtin_amdgcn_s_setprio(1); \
;     for (int m = 0; m < 4; ++m) for (int n = 0; n < 2; ++n) for (int k = 0; k < 2; ++k) \
;       acc[ai][bj][m][n] = __builtin_amdgcn_mfma_f32_16x16x32_bf16(Bt_[n][k], At_[m][k], acc[ai][bj][m][n], 0, 0, 0); \
;     __builtin_amdgcn_s_setprio(0); } while (0)
; #define WAIT_V(n) asm volatile("s_waitcnt vmcnt(" #n ")" ::: "memory")
; #define WAIT_L(n) asm volatile("s_waitcnt lgkmcnt(" #n ")" ::: "memory")
; #define BAR __builtin_amdgcn_s_barrier()
; #define SCHED __builtin_amdgcn_sched_barrier(0)
;     ...
;     LDB(B0, 0, 0); SCHED; LDA(At, 0, 0); STAGE_A(SA(1, 1), brow + HALF, t + 1);
;     WAIT_L(8); BAR; WAIT_L(0); MMA(0, 0, At, B0); BAR; SCHED;
;     LDB(B1, 0, 1); STAGE_B(SB(0, 0), bcol, t + 2);
;     BAR; WAIT_L(0); MMA(0, 1, At, B1); BAR;
;     LDA(At, 0, 1); STAGE_A(SA(0, 0), brow, t + 2);
;     BAR; WAIT_L(0); MMA(1, 0, At, B0); BAR; SCHED;
;     STAGE_B(SB(0, 1), bcol + HALF, t + 2);
;     WAIT_V(6); BAR; MMA(1, 1, At, B1); BAR;
;     LDB(B0, 1, 0); SCHED; LDA(At, 1, 0); STAGE_A(SA(0, 1), brow + HALF, t + 2);
;     WAIT_L(8); BAR; WAIT_L(0); MMA(0, 0, At, B0); BAR; SCHED;
;     LDB(B1, 1, 1); STAGE_B(SB(1, 0), bcol, t + 3);
	v_mfma_f32_16x16x32_bf16 v[68:71], v[214:217], v[206:209], v[68:71]
	v_mfma_f32_16x16x32_bf16 v[64:67], v[246:249], v[206:209], v[64:67]
	s_setprio 0
	v_add_u32_e32 v155, s30, v142
	v_lshl_add_u64 v[232:233], s[26:27], 0, v[130:131]
	v_readfirstlane_b32 s35, v155
	v_lshl_add_u64 v[156:157], v[232:233], 0, s[42:43]
	s_mov_b32 m0, s35
	global_load_lds_dwordx4 v[156:157], off
	v_add_u32_e32 v156, 0x2000, v155
	v_lshl_add_u64 v[234:235], s[26:27], 0, v[132:133]
	v_readfirstlane_b32 s35, v156
	v_lshl_add_u64 v[236:237], v[234:235], 0, s[42:43]
	s_mov_b32 m0, s35
	s_nop 0
	global_load_lds_dwordx4 v[236:237], off
	v_readfirstlane_b32 s35, v147
	v_lshl_add_u64 v[236:237], v[222:223], 0, s[4:5]
	s_mov_b32 m0, s35
	v_readfirstlane_b32 s35, v146
	ds_read_b128 v[176:179], v148 offset:16384
	ds_read_b128 v[182:185], v148 offset:17408
	ds_read_b128 v[186:189], v148 offset:18432
	ds_read_b128 v[190:193], v148 offset:19456
	ds_read_b128 v[194:197], v148 offset:20480
	ds_read_b128 v[198:201], v148 offset:21504
	ds_read_b128 v[202:205], v148 offset:22528
	ds_read_b128 v[206:209], v148 offset:23552
	global_load_lds_dwordx4 v[236:237], off
	v_lshl_add_u64 v[236:237], v[230:231], 0, s[4:5]
	s_mov_b32 m0, s35
	s_nop 0
	global_load_lds_dwordx4 v[236:237], off
	v_readfirstlane_b32 s35, v141
	v_add_u32_e32 v157, 0x2000, v141
	v_lshl_add_u64 v[250:251], v[232:233], 0, s[46:47]
	s_mov_b32 m0, s35
	v_readfirstlane_b32 s35, v157
	global_load_lds_dwordx4 v[250:251], off
	v_lshl_add_u64 v[250:251], v[234:235], 0, s[46:47]
	s_mov_b32 m0, s35
	s_nop 0
	global_load_lds_dwordx4 v[250:251], off
	s_waitcnt lgkmcnt(0)
	s_waitcnt vmcnt(8)
	s_barrier
	s_setprio 1
	v_mfma_f32_16x16x32_bf16 v[60:63], v[160:163], v[176:179], 0
	v_mfma_f32_16x16x32_bf16 v[56:59], v[168:171], v[176:179], 0
	v_mfma_f32_16x16x32_bf16 v[52:55], v[160:163], v[186:189], 0
	v_mfma_f32_16x16x32_bf16 v[48:51], v[168:171], v[186:189], 0
	v_mfma_f32_16x16x32_bf16 v[44:47], v[160:163], v[194:197], 0
	v_mfma_f32_16x16x32_bf16 v[40:43], v[168:171], v[194:197], 0
	v_mfma_f32_16x16x32_bf16 v[36:39], v[160:163], v[202:205], 0
	v_mfma_f32_16x16x32_bf16 v[32:35], v[168:171], v[202:205], 0
	v_mfma_f32_16x16x32_bf16 v[60:63], v[164:167], v[182:185], v[60:63]
	v_mfma_f32_16x16x32_bf16 v[56:59], v[172:175], v[182:185], v[56:59]
	v_mfma_f32_16x16x32_bf16 v[52:55], v[164:167], v[190:193], v[52:55]
	v_mfma_f32_16x16x32_bf16 v[48:51], v[172:175], v[190:193], v[48:51]
	v_mfma_f32_16x16x32_bf16 v[44:47], v[164:167], v[198:201], v[44:47]
	v_mfma_f32_16x16x32_bf16 v[40:43], v[172:175], v[198:201], v[40:43]
	v_mfma_f32_16x16x32_bf16 v[36:39], v[164:167], v[206:209], v[36:39]
	v_mfma_f32_16x16x32_bf16 v[32:35], v[172:175], v[206:209], v[32:35]
	v_mfma_f32_16x16x32_bf16 v[28:31], v[210:213], v[176:179], 0
	v_mfma_f32_16x16x32_bf16 v[24:27], v[218:221], v[176:179], 0
	v_mfma_f32_16x16x32_bf16 v[20:23], v[210:213], v[186:189], 0
	v_mfma_f32_16x16x32_bf16 v[16:19], v[218:221], v[186:189], 0
	v_mfma_f32_16x16x32_bf16 v[12:15], v[210:213], v[194:197], 0
	v_mfma_f32_16x16x32_bf16 v[8:11], v[218:221], v[194:197], 0
	v_mfma_f32_16x16x32_bf16 v[4:7], v[210:213], v[202:205], 0
	v_mfma_f32_16x16x32_bf16 v[0:3], v[218:221], v[202:205], 0
	v_mfma_f32_16x16x32_bf16 v[28:31], v[214:217], v[182:185], v[28:31]
	v_mfma_f32_16x16x32_bf16 v[24:27], v[246:249], v[182:185], v[24:27]
	v_mfma_f32_16x16x32_bf16 v[20:23], v[214:217], v[190:193], v[20:23]
	v_mfma_f32_16x16x32_bf16 v[16:19], v[246:249], v[190:193], v[16:19]
	v_mfma_f32_16x16x32_bf16 v[12:15], v[214:217], v[198:201], v[12:15]
	v_mfma_f32_16x16x32_bf16 v[8:11], v[246:249], v[198:201], v[8:11]
	s_setprio 2
	s_barrier
	v_mfma_f32_16x16x32_bf16 v[4:7], v[214:217], v[206:209], v[4:7]
	v_mfma_f32_16x16x32_bf16 v[0:3], v[246:249], v[206:209], v[0:3]
	s_setprio 0
	ds_read_b128 v[160:163], v149 offset:32768
	ds_read_b128 v[164:167], v149 offset:33792
	ds_read_b128 v[168:171], v149 offset:34816
	ds_read_b128 v[172:175], v149 offset:35840
	v_readfirstlane_b32 s35, v140
	v_lshl_add_u64 v[210:211], v[222:223], 0, s[96:97]
	s_mov_b32 m0, s35
	v_readfirstlane_b32 s35, v138
	ds_read_b128 v[176:179], v148 offset:32768
	ds_read_b128 v[182:185], v148 offset:33792
	ds_read_b128 v[186:189], v148 offset:34816
	ds_read_b128 v[190:193], v148 offset:35840
	ds_read_b128 v[194:197], v148 offset:36864
	ds_read_b128 v[198:201], v148 offset:37888
	ds_read_b128 v[202:205], v148 offset:38912
	ds_read_b128 v[206:209], v148 offset:39936
	global_load_lds_dwordx4 v[210:211], off
	v_lshl_add_u64 v[210:211], v[230:231], 0, s[96:97]
	s_mov_b32 m0, s35
	s_nop 0
	global_load_lds_dwordx4 v[210:211], off
	ds_read_b128 v[210:213], v149 offset:49152
	ds_read_b128 v[214:217], v149 offset:50176
	ds_read_b128 v[218:221], v149 offset:51200
	ds_read_b128 v[246:249], v149 offset:52224
	s_waitcnt lgkmcnt(0)
	s_waitcnt vmcnt(8)
	s_barrier
; #define STAGE_A(P, br, kt) do { const char* _base = (const char*)(((kt) < G.ksplit ? G.A1 : A2m) + (long)(br) * G.lda + (long)(kt) * BK); \
;     __builtin_amdgcn_global_load_lds((const unsigned*)(_base + aoff0), (unsigned*)((char*)(P) + sb0), 16, 0, 0); \
;     __builtin_amdgcn_global_load_lds((const unsigned*)(_base + aoff1), (unsigned*)((char*)(P) + sb1), 16, 0, 0); } while (0)
; #define STAGE_B(P, br, kt) do { const char* _base = (const char*)(G.Bt + (long)(br) * G.ldb + (long)(kt) * BK); \
;     __builtin_amdgcn_global_load_lds((const unsigned*)(_base + boff0), (unsigned*)((char*)(P) + sb0), 16, 0, 0); \
;     __builtin_amdgcn_global_load_lds((const unsigned*)(_base + boff1), (unsigned*)((char*)(P) + sb1), 16, 0, 0); } while (0)
; #define LDA(dst, b, h) for (int m = 0; m < 4; ++m) for (int k = 0; k < 2; ++k) \
;     dst[m][k] = *reinterpret_cast<const bf16x8*>(a_rd + ((b) * 2 + (h)) * (HT * 2) + m * 2048 + k * 1024)
; #define LDB(dst, b, h) for (int n = 0; n < 2; ++n) for (int k = 0; k < 2; ++k) \
;     dst[n][k] = *reinterpret_cast<const bf16x8*>(b_rd + ((b) * 2 + (h)) * (HT * 2) + n * 2048 + k * 1024)
; #define MMA(ai, bj, At_, Bt_) do { __builtin_amdgcn_s_setprio(1); \
;     for (int m = 0; m < 4; ++m) for (int n = 0; n < 2; ++n) for (int k = 0; k < 2; ++k) \
;       acc[ai][bj][m][n] = __builtin_amdgcn_mfma_f32_16x16x32_bf16(Bt_[n][k], At_[m][k], acc[ai][bj][m][n], 0, 0, 0); \
;     __builtin_amdgcn_s_setprio(0); } while (0)
; #define WAIT_V(n) asm volatile("s_waitcnt vmcnt(" #n ")" ::: "memory")
; #define WAIT_L(n) asm volatile("s_waitcnt lgkmcnt(" #n ")" ::: "memory")
; #define BAR __builtin_amdgcn_s_barrier()
; #define SCHED __builtin_amdgcn_sched_barrier(0)
;     ...
;     LDB(B0, 1, 0); SCHED; LDA(At, 1, 0); STAGE_A(SA(0, 1), brow + HALF, t + 2);
;     WAIT_L(8); BAR; WAIT_L(0); MMA(0, 0, At, B0); BAR; SCHED;
;     LDB(B1, 1, 1); STAGE_B(SB(1, 0), bcol, t + 3);
;     BAR; WAIT_L(0); MMA(0, 1, At, B1); BAR;
;     LDA(At, 1, 1); STAGE_A(SA(1, 0), brow, t + 3);
;     BAR; WAIT_L(0); MMA(1, 0, At, B0); BAR; SCHED;
;     STAGE_B(SB(1, 1), bcol + HALF, t + 3);
;     WAIT_V(6); BAR; MMA(1, 1, At, B1); BAR;
;   }
	s_setprio 1
	v_mfma_f32_16x16x32_bf16 v[124:127], v[160:163], v[176:179], v[124:127]
	v_mfma_f32_16x16x32_bf16 v[120:123], v[168:171], v[176:179], v[120:123]
	v_mfma_f32_16x16x32_bf16 v[116:119], v[160:163], v[186:189], v[116:119]
	v_mfma_f32_16x16x32_bf16 v[112:115], v[168:171], v[186:189], v[112:115]
	v_mfma_f32_16x16x32_bf16 v[108:111], v[160:163], v[194:197], v[108:111]
	v_mfma_f32_16x16x32_bf16 v[104:107], v[168:171], v[194:197], v[104:107]
	v_mfma_f32_16x16x32_bf16 v[100:103], v[160:163], v[202:205], v[100:103]
	v_mfma_f32_16x16x32_bf16 v[96:99], v[168:171], v[202:205], v[96:99]
	v_mfma_f32_16x16x32_bf16 v[124:127], v[164:167], v[182:185], v[124:127]
	v_mfma_f32_16x16x32_bf16 v[120:123], v[172:175], v[182:185], v[120:123]
	v_mfma_f32_16x16x32_bf16 v[116:119], v[164:167], v[190:193], v[116:119]
	v_mfma_f32_16x16x32_bf16 v[112:115], v[172:175], v[190:193], v[112:115]
	v_mfma_f32_16x16x32_bf16 v[108:111], v[164:167], v[198:201], v[108:111]
	v_mfma_f32_16x16x32_bf16 v[104:107], v[172:175], v[198:201], v[104:107]
	v_mfma_f32_16x16x32_bf16 v[100:103], v[164:167], v[206:209], v[100:103]
	v_mfma_f32_16x16x32_bf16 v[96:99], v[172:175], v[206:209], v[96:99]
	v_mfma_f32_16x16x32_bf16 v[92:95], v[210:213], v[176:179], v[92:95]
	v_mfma_f32_16x16x32_bf16 v[88:91], v[218:221], v[176:179], v[88:91]
	v_mfma_f32_16x16x32_bf16 v[84:87], v[210:213], v[186:189], v[84:87]
	v_mfma_f32_16x16x32_bf16 v[80:83], v[218:221], v[186:189], v[80:83]
	v_mfma_f32_16x16x32_bf16 v[76:79], v[210:213], v[194:197], v[76:79]
	v_mfma_f32_16x16x32_bf16 v[72:75], v[218:221], v[194:197], v[72:75]
	v_mfma_f32_16x16x32_bf16 v[68:71], v[210:213], v[202:205], v[68:71]
	v_mfma_f32_16x16x32_bf16 v[64:67], v[218:221], v[202:205], v[64:67]
	v_mfma_f32_16x16x32_bf16 v[92:95], v[214:217], v[182:185], v[92:95]
	v_mfma_f32_16x16x32_bf16 v[88:91], v[246:249], v[182:185], v[88:91]
	v_mfma_f32_16x16x32_bf16 v[84:87], v[214:217], v[190:193], v[84:87]
	v_mfma_f32_16x16x32_bf16 v[80:83], v[246:249], v[190:193], v[80:83]
	v_mfma_f32_16x16x32_bf16 v[76:79], v[214:217], v[198:201], v[76:79]
	v_mfma_f32_16x16x32_bf16 v[72:75], v[246:249], v[198:201], v[72:75]
	s_setprio 2
	s_barrier
	v_mfma_f32_16x16x32_bf16 v[68:71], v[214:217], v[206:209], v[68:71]
	v_mfma_f32_16x16x32_bf16 v[64:67], v[246:249], v[206:209], v[64:67]
	s_setprio 0
	v_readfirstlane_b32 s35, v145
	v_lshl_add_u64 v[236:237], v[232:233], 0, s[44:45]
	s_mov_b32 m0, s35
	v_readfirstlane_b32 s35, v150
	global_load_lds_dwordx4 v[236:237], off
	v_lshl_add_u64 v[236:237], v[234:235], 0, s[44:45]
	s_mov_b32 m0, s35
	s_nop 0
	global_load_lds_dwordx4 v[236:237], off
	v_readfirstlane_b32 s35, v151
	v_lshl_add_u64 v[222:223], v[222:223], 0, s[2:3]
	s_mov_b32 m0, s35
	v_readfirstlane_b32 s35, v152
	ds_read_b128 v[176:179], v148 offset:49152
	ds_read_b128 v[182:185], v148 offset:50176
	ds_read_b128 v[186:189], v148 offset:51200
	ds_read_b128 v[190:193], v148 offset:52224
	ds_read_b128 v[194:197], v148 offset:53248
	ds_read_b128 v[198:201], v148 offset:54272
	ds_read_b128 v[202:205], v148 offset:55296
	ds_read_b128 v[206:209], v148 offset:56320
	global_load_lds_dwordx4 v[222:223], off
	v_lshl_add_u64 v[222:223], v[230:231], 0, s[2:3]
	s_mov_b32 m0, s35
	s_nop 0
	global_load_lds_dwordx4 v[222:223], off
	v_readfirstlane_b32 s35, v153
	v_lshl_add_u64 v[250:251], v[232:233], 0, s[48:49]
	s_mov_b32 m0, s35
	v_readfirstlane_b32 s35, v154
	global_load_lds_dwordx4 v[250:251], off
	v_lshl_add_u64 v[250:251], v[234:235], 0, s[48:49]
	s_mov_b32 m0, s35
	s_nop 0
	global_load_lds_dwordx4 v[250:251], off
	s_waitcnt lgkmcnt(0)
	s_waitcnt vmcnt(8)
	s_barrier
	s_setprio 1
	v_mfma_f32_16x16x32_bf16 v[60:63], v[160:163], v[176:179], v[60:63]
	v_mfma_f32_16x16x32_bf16 v[56:59], v[168:171], v[176:179], v[56:59]
	v_mfma_f32_16x16x32_bf16 v[52:55], v[160:163], v[186:189], v[52:55]
	v_mfma_f32_16x16x32_bf16 v[48:51], v[168:171], v[186:189], v[48:51]
	v_mfma_f32_16x16x32_bf16 v[44:47], v[160:163], v[194:197], v[44:47]
	v_mfma_f32_16x16x32_bf16 v[40:43], v[168:171], v[194:197], v[40:43]
	v_mfma_f32_16x16x32_bf16 v[36:39], v[160:163], v[202:205], v[36:39]
	v_mfma_f32_16x16x32_bf16 v[32:35], v[168:171], v[202:205], v[32:35]
	v_mfma_f32_16x16x32_bf16 v[60:63], v[164:167], v[182:185], v[60:63]
	v_mfma_f32_16x16x32_bf16 v[56:59], v[172:175], v[182:185], v[56:59]
	v_mfma_f32_16x16x32_bf16 v[52:55], v[164:167], v[190:193], v[52:55]
	v_mfma_f32_16x16x32_bf16 v[48:51], v[172:175], v[190:193], v[48:51]
	v_mfma_f32_16x16x32_bf16 v[44:47], v[164:167], v[198:201], v[44:47]
	v_mfma_f32_16x16x32_bf16 v[40:43], v[172:175], v[198:201], v[40:43]
	v_mfma_f32_16x16x32_bf16 v[36:39], v[164:167], v[206:209], v[36:39]
	v_mfma_f32_16x16x32_bf16 v[32:35], v[172:175], v[206:209], v[32:35]
	v_mfma_f32_16x16x32_bf16 v[28:31], v[210:213], v[176:179], v[28:31]
	v_mfma_f32_16x16x32_bf16 v[24:27], v[218:221], v[176:179], v[24:27]
	v_mfma_f32_16x16x32_bf16 v[20:23], v[210:213], v[186:189], v[20:23]
	v_mfma_f32_16x16x32_bf16 v[16:19], v[218:221], v[186:189], v[16:19]
	v_mfma_f32_16x16x32_bf16 v[12:15], v[210:213], v[194:197], v[12:15]
	v_mfma_f32_16x16x32_bf16 v[8:11], v[218:221], v[194:197], v[8:11]
	v_mfma_f32_16x16x32_bf16 v[4:7], v[210:213], v[202:205], v[4:7]
	v_mfma_f32_16x16x32_bf16 v[0:3], v[218:221], v[202:205], v[0:3]
	v_mfma_f32_16x16x32_bf16 v[28:31], v[214:217], v[182:185], v[28:31]
	v_mfma_f32_16x16x32_bf16 v[24:27], v[246:249], v[182:185], v[24:27]
	v_mfma_f32_16x16x32_bf16 v[20:23], v[214:217], v[190:193], v[20:23]
	v_mfma_f32_16x16x32_bf16 v[16:19], v[246:249], v[190:193], v[16:19]
	v_mfma_f32_16x16x32_bf16 v[12:15], v[214:217], v[198:201], v[12:15]
	v_mfma_f32_16x16x32_bf16 v[8:11], v[246:249], v[198:201], v[8:11]
	s_setprio 2
	s_barrier
	v_mfma_f32_16x16x32_bf16 v[4:7], v[214:217], v[206:209], v[4:7]
	v_mfma_f32_16x16x32_bf16 v[0:3], v[246:249], v[206:209], v[0:3]
	s_setprio 0
	s_add_i32 s31, s31, 2
	s_add_u32 s26, s26, 0x100
	s_addc_u32 s27, s27, 0
	s_cmp_lt_u32 s31, 28
	s_cbranch_scc0 .Lmy_kexit_2

; #define STAGE_A(P, br, kt) do { const char* _base = (const char*)(((kt) < G.ksplit ? G.A1 : A2m) + (long)(br) * G.lda + (long)(kt) * BK); \
;     __builtin_amdgcn_global_load_lds((const unsigned*)(_base + aoff0), (unsigned*)((char*)(P) + sb0), 16, 0, 0); \
;     __builtin_amdgcn_global_load_lds((const unsigned*)(_base + aoff1), (unsigned*)((char*)(P) + sb1), 16, 0, 0); } while (0)
; #define LDA(dst, b, h) for (int m = 0; m < 4; ++m) for (int k = 0; k < 2; ++k) \
;     dst[m][k] = *reinterpret_cast<const bf16x8*>(a_rd + ((b) * 2 + (h)) * (HT * 2) + m * 2048 + k * 1024)
; #define LDB(dst, b, h) for (int n = 0; n < 2; ++n) for (int k = 0; k < 2; ++k) \
;     dst[n][k] = *reinterpret_cast<const bf16x8*>(b_rd + ((b) * 2 + (h)) * (HT * 2) + n * 2048 + k * 1024)
; #define MMA(ai, bj, At_, Bt_) do { __builtin_amdgcn_s_setprio(1); \
;     for (int m = 0; m < 4; ++m) for (int n = 0; n < 2; ++n) for (int k = 0; k < 2; ++k) \
;       acc[ai][bj][m][n] = __builtin_amdgcn_mfma_f32_16x16x32_bf16(Bt_[n][k], At_[m][k], acc[ai][bj][m][n], 0, 0, 0); \
;     __builtin_amdgcn_s_setprio(0); } while (0)
; #define WAIT_V(n) asm volatile("s_waitcnt vmcnt(" #n ")" ::: "memory")
; #define WAIT_L(n) asm volatile("s_waitcnt lgkmcnt(" #n ")" ::: "memory")
; #define BAR __builtin_amdgcn_s_barrier()
;     ...
;   float ssv[2][4] = {};
;   if constexpr (EPI == EPI_GU || EPI == EPI_EVIN || EPI == EPI_ODIN) {
; #pragma unroll
;     for (int ai = 0; ai < 2; ++ai)
; #pragma unroll
;       for (int m = 0; m < 4; ++m) ssv[ai][m] = G.ssr[brow + ai * HALF + wr * 64 + m * 16 + fr];
;   }
;   { LDB(B0, 0, 0); LDA(At, 0, 0); STAGE_A(SA(1, 1), brow + HALF, nt - 1);
;     BAR; WAIT_L(0); MMA(0, 0, At, B0); BAR;
;     LDB(B1, 0, 1); BAR; WAIT_L(0); MMA(0, 1, At, B1); BAR;
;     LDA(At, 0, 1); WAIT_V(4); BAR; WAIT_L(0); MMA(1, 0, At, B0); MMA(1, 1, At, B1); BAR; }
;   { LDB(B0, 1, 0); LDA(At, 1, 0); WAIT_V(2); BAR; WAIT_L(0); MMA(0, 0, At, B0); BAR;
.Lmy_kexit_2:
	s_waitcnt vmcnt(6)
	v_not_b32_e32 v250, 63
	v_mov_b32_e32 v251, 0x41b17218
	v_or_b32_e32 v130, s29, v144
	v_lshl_add_u32 v130, v143, 6, v130
	v_ashrrev_i32_e32 v131, 31, v130
	v_add_u32_e32 v142, 0xa0, v130
	v_lshl_add_u64 v[132:133], v[130:131], 2, s[20:21]
	v_add_u32_e32 v134, 0x80, v130
	v_add_u32_e32 v136, 0x90, v130
	v_ashrrev_i32_e32 v143, 31, v142
	v_add_u32_e32 v130, 0xb0, v130
	s_or_b32 s42, s29, 0x80
	v_ashrrev_i32_e32 v135, 31, v134
	v_ashrrev_i32_e32 v137, 31, v136
	v_lshl_add_u64 v[142:143], v[142:143], 2, s[20:21]
	v_ashrrev_i32_e32 v131, 31, v130
	s_mul_i32 s26, s42, 0x1080
	v_lshl_add_u64 v[134:135], v[134:135], 2, s[20:21]
	v_lshl_add_u64 v[136:137], v[136:137], 2, s[20:21]
	v_lshl_add_u64 v[160:161], v[130:131], 2, s[20:21]
	global_load_dword v130, v[132:133], off
	global_load_dword v152, v[132:133], off offset:64
	global_load_dword v151, v[132:133], off offset:128
	global_load_dword v150, v[132:133], off offset:192
	global_load_dword v145, v[134:135], off
	global_load_dword v144, v[136:137], off
	s_nop 0
	global_load_dword v143, v[142:143], off
	s_nop 0
	global_load_dword v142, v[160:161], off
	s_mul_hi_i32 s27, s42, 0x1080
	s_add_u32 s26, s37, s26
	s_addc_u32 s27, s38, s27
	v_lshl_add_u64 v[136:137], s[26:27], 0, v[180:181]
	s_mov_b64 s[44:45], 0xf80
	v_readfirstlane_b32 s30, v158
	v_lshl_add_u64 v[136:137], v[136:137], 0, s[44:45]
	s_mov_b32 m0, s30
	ds_read_b128 v[132:135], v149
	ds_read_b128 v[160:163], v149 offset:1024
	ds_read_b128 v[164:167], v149 offset:2048
	ds_read_b128 v[168:171], v149 offset:3072
	ds_read_b128 v[172:175], v148
	ds_read_b128 v[176:179], v148 offset:1024
	ds_read_b128 v[182:185], v148 offset:2048
	ds_read_b128 v[186:189], v148 offset:3072
	ds_read_b128 v[190:193], v148 offset:4096
	ds_read_b128 v[194:197], v148 offset:5120
	ds_read_b128 v[198:201], v148 offset:6144
	ds_read_b128 v[202:205], v148 offset:7168
	global_load_lds_dwordx4 v[136:137], off
	v_lshl_add_u64 v[136:137], s[26:27], 0, v[128:129]
	v_readfirstlane_b32 s26, v159
	v_lshl_add_u64 v[136:137], v[136:137], 0, s[44:45]
	s_mov_b32 m0, s26
	s_nop 0
	global_load_lds_dwordx4 v[136:137], off
	s_barrier
	s_waitcnt lgkmcnt(0)
	s_setprio 1
	s_waitcnt lgkmcnt(0)
	v_mfma_f32_16x16x32_bf16 v[124:127], v[132:135], v[172:175], v[124:127]
	v_mfma_f32_16x16x32_bf16 v[120:123], v[164:167], v[172:175], v[120:123]
	v_mfma_f32_16x16x32_bf16 v[116:119], v[132:135], v[182:185], v[116:119]
	v_mfma_f32_16x16x32_bf16 v[112:115], v[164:167], v[182:185], v[112:115]
	v_mfma_f32_16x16x32_bf16 v[108:111], v[132:135], v[190:193], v[108:111]
	v_mfma_f32_16x16x32_bf16 v[104:107], v[164:167], v[190:193], v[104:107]
	v_mfma_f32_16x16x32_bf16 v[100:103], v[132:135], v[198:201], v[100:103]
	v_mfma_f32_16x16x32_bf16 v[96:99], v[164:167], v[198:201], v[96:99]
	v_mfma_f32_16x16x32_bf16 v[124:127], v[160:163], v[176:179], v[124:127]
	v_mfma_f32_16x16x32_bf16 v[120:123], v[168:171], v[176:179], v[120:123]
	v_mfma_f32_16x16x32_bf16 v[116:119], v[160:163], v[186:189], v[116:119]
	v_mfma_f32_16x16x32_bf16 v[112:115], v[168:171], v[186:189], v[112:115]
	v_mfma_f32_16x16x32_bf16 v[108:111], v[160:163], v[194:197], v[108:111]
	v_mfma_f32_16x16x32_bf16 v[104:107], v[168:171], v[194:197], v[104:107]
	s_setprio 2
	s_barrier
	v_mfma_f32_16x16x32_bf16 v[100:103], v[160:163], v[202:205], v[100:103]
	v_mfma_f32_16x16x32_bf16 v[96:99], v[168:171], v[202:205], v[96:99]
	s_setprio 0
	ds_read_b128 v[206:209], v149 offset:16384
	ds_read_b128 v[210:213], v149 offset:17408
	ds_read_b128 v[214:217], v149 offset:18432
	ds_read_b128 v[218:221], v149 offset:19456
	s_barrier
	s_waitcnt lgkmcnt(0)
	s_setprio 1
	s_waitcnt lgkmcnt(0)
	v_mfma_f32_16x16x32_bf16 v[92:95], v[206:209], v[172:175], v[92:95]
	v_mfma_f32_16x16x32_bf16 v[88:91], v[214:217], v[172:175], v[88:91]
	v_mfma_f32_16x16x32_bf16 v[84:87], v[206:209], v[182:185], v[84:87]
	v_mfma_f32_16x16x32_bf16 v[80:83], v[214:217], v[182:185], v[80:83]
	v_mfma_f32_16x16x32_bf16 v[76:79], v[206:209], v[190:193], v[76:79]
	v_mfma_f32_16x16x32_bf16 v[72:75], v[214:217], v[190:193], v[72:75]
	v_mfma_f32_16x16x32_bf16 v[68:71], v[206:209], v[198:201], v[68:71]
	v_mfma_f32_16x16x32_bf16 v[64:67], v[214:217], v[198:201], v[64:67]
	v_mfma_f32_16x16x32_bf16 v[92:95], v[210:213], v[176:179], v[92:95]
	v_mfma_f32_16x16x32_bf16 v[88:91], v[218:221], v[176:179], v[88:91]
	v_mfma_f32_16x16x32_bf16 v[84:87], v[210:213], v[186:189], v[84:87]
	v_mfma_f32_16x16x32_bf16 v[80:83], v[218:221], v[186:189], v[80:83]
	v_mfma_f32_16x16x32_bf16 v[76:79], v[210:213], v[194:197], v[76:79]
	v_mfma_f32_16x16x32_bf16 v[72:75], v[218:221], v[194:197], v[72:75]
	s_setprio 2
	s_barrier
	v_mfma_f32_16x16x32_bf16 v[68:71], v[210:213], v[202:205], v[68:71]
	v_mfma_f32_16x16x32_bf16 v[64:67], v[218:221], v[202:205], v[64:67]
	s_setprio 0
	ds_read_b128 v[172:175], v148 offset:16384
	ds_read_b128 v[176:179], v148 offset:17408
	ds_read_b128 v[182:185], v148 offset:18432
	ds_read_b128 v[186:189], v148 offset:19456
	ds_read_b128 v[190:193], v148 offset:20480
	ds_read_b128 v[194:197], v148 offset:21504
	ds_read_b128 v[198:201], v148 offset:22528
	ds_read_b128 v[202:205], v148 offset:23552
	s_waitcnt vmcnt(4)
	s_barrier
; #define LDA(dst, b, h) for (int m = 0; m < 4; ++m) for (int k = 0; k < 2; ++k) \
;     dst[m][k] = *reinterpret_cast<const bf16x8*>(a_rd + ((b) * 2 + (h)) * (HT * 2) + m * 2048 + k * 1024)
; #define LDB(dst, b, h) for (int n = 0; n < 2; ++n) for (int k = 0; k < 2; ++k) \
;     dst[n][k] = *reinterpret_cast<const bf16x8*>(b_rd + ((b) * 2 + (h)) * (HT * 2) + n * 2048 + k * 1024)
; #define MMA(ai, bj, At_, Bt_) do { __builtin_amdgcn_s_setprio(1); \
;     for (int m = 0; m < 4; ++m) for (int n = 0; n < 2; ++n) for (int k = 0; k < 2; ++k) \
;       acc[ai][bj][m][n] = __builtin_amdgcn_mfma_f32_16x16x32_bf16(Bt_[n][k], At_[m][k], acc[ai][bj][m][n], 0, 0, 0); \
;     __builtin_amdgcn_s_setprio(0); } while (0)
; #define WAIT_V(n) asm volatile("s_waitcnt vmcnt(" #n ")" ::: "memory")
; #define WAIT_L(n) asm volatile("s_waitcnt lgkmcnt(" #n ")" ::: "memory")
; #define BAR __builtin_amdgcn_s_barrier()
;     ...
;     LDA(At, 0, 1); WAIT_V(4); BAR; WAIT_L(0); MMA(1, 0, At, B0); MMA(1, 1, At, B1); BAR; }
;   { LDB(B0, 1, 0); LDA(At, 1, 0); WAIT_V(2); BAR; WAIT_L(0); MMA(0, 0, At, B0); BAR;
;     LDB(B1, 1, 1); WAIT_V(0); BAR; WAIT_L(0); MMA(0, 1, At, B1); BAR;
;     LDA(At, 1, 1); BAR; WAIT_L(0); MMA(1, 0, At, B0); MMA(1, 1, At, B1); BAR; }
	s_waitcnt lgkmcnt(0)
	s_setprio 1
	s_waitcnt lgkmcnt(0)
	v_mfma_f32_16x16x32_bf16 v[60:63], v[132:135], v[172:175], v[60:63]
	v_mfma_f32_16x16x32_bf16 v[56:59], v[164:167], v[172:175], v[56:59]
	v_mfma_f32_16x16x32_bf16 v[52:55], v[132:135], v[182:185], v[52:55]
	v_mfma_f32_16x16x32_bf16 v[48:51], v[164:167], v[182:185], v[48:51]
	v_mfma_f32_16x16x32_bf16 v[44:47], v[132:135], v[190:193], v[44:47]
	v_mfma_f32_16x16x32_bf16 v[40:43], v[164:167], v[190:193], v[40:43]
	v_mfma_f32_16x16x32_bf16 v[36:39], v[132:135], v[198:201], v[36:39]
	v_mfma_f32_16x16x32_bf16 v[32:35], v[164:167], v[198:201], v[32:35]
	v_mfma_f32_16x16x32_bf16 v[60:63], v[160:163], v[176:179], v[60:63]
	v_mfma_f32_16x16x32_bf16 v[56:59], v[168:171], v[176:179], v[56:59]
	v_mfma_f32_16x16x32_bf16 v[52:55], v[160:163], v[186:189], v[52:55]
	v_mfma_f32_16x16x32_bf16 v[48:51], v[168:171], v[186:189], v[48:51]
	v_mfma_f32_16x16x32_bf16 v[44:47], v[160:163], v[194:197], v[44:47]
	v_mfma_f32_16x16x32_bf16 v[40:43], v[168:171], v[194:197], v[40:43]
	v_mfma_f32_16x16x32_bf16 v[36:39], v[160:163], v[202:205], v[36:39]
	v_mfma_f32_16x16x32_bf16 v[32:35], v[168:171], v[202:205], v[32:35]
	s_setprio 0
	s_setprio 1
	v_mfma_f32_16x16x32_bf16 v[28:31], v[206:209], v[172:175], v[28:31]
	v_mfma_f32_16x16x32_bf16 v[24:27], v[214:217], v[172:175], v[24:27]
	v_mfma_f32_16x16x32_bf16 v[20:23], v[206:209], v[182:185], v[20:23]
	v_mfma_f32_16x16x32_bf16 v[16:19], v[214:217], v[182:185], v[16:19]
	v_mfma_f32_16x16x32_bf16 v[12:15], v[206:209], v[190:193], v[12:15]
	v_mfma_f32_16x16x32_bf16 v[8:11], v[214:217], v[190:193], v[8:11]
	v_mfma_f32_16x16x32_bf16 v[4:7], v[206:209], v[198:201], v[4:7]
	v_mfma_f32_16x16x32_bf16 v[0:3], v[214:217], v[198:201], v[0:3]
	v_mfma_f32_16x16x32_bf16 v[28:31], v[210:213], v[176:179], v[28:31]
	v_mfma_f32_16x16x32_bf16 v[24:27], v[218:221], v[176:179], v[24:27]
	v_mfma_f32_16x16x32_bf16 v[20:23], v[210:213], v[186:189], v[20:23]
	v_mfma_f32_16x16x32_bf16 v[16:19], v[218:221], v[186:189], v[16:19]
	v_mfma_f32_16x16x32_bf16 v[12:15], v[210:213], v[194:197], v[12:15]
	v_mfma_f32_16x16x32_bf16 v[8:11], v[218:221], v[194:197], v[8:11]
	s_setprio 2
	s_barrier
	v_mfma_f32_16x16x32_bf16 v[4:7], v[210:213], v[202:205], v[4:7]
	v_mfma_f32_16x16x32_bf16 v[0:3], v[218:221], v[202:205], v[0:3]
	s_setprio 0
	ds_read_b128 v[132:135], v149 offset:32768
	ds_read_b128 v[158:161], v149 offset:33792
	ds_read_b128 v[162:165], v149 offset:34816
	ds_read_b128 v[166:169], v149 offset:35840
	ds_read_b128 v[170:173], v148 offset:32768
	ds_read_b128 v[174:177], v148 offset:33792
	ds_read_b128 v[182:185], v148 offset:34816
	ds_read_b128 v[186:189], v148 offset:35840
	ds_read_b128 v[190:193], v148 offset:36864
	ds_read_b128 v[194:197], v148 offset:37888
	ds_read_b128 v[198:201], v148 offset:38912
	ds_read_b128 v[202:205], v148 offset:39936
	s_waitcnt vmcnt(2)
	s_barrier
	s_waitcnt lgkmcnt(0)
	s_setprio 1
	s_waitcnt lgkmcnt(0)
	v_mfma_f32_16x16x32_bf16 v[124:127], v[132:135], v[170:173], v[124:127]
	v_mfma_f32_16x16x32_bf16 v[120:123], v[162:165], v[170:173], v[120:123]
	v_mfma_f32_16x16x32_bf16 v[116:119], v[132:135], v[182:185], v[116:119]
	v_mfma_f32_16x16x32_bf16 v[112:115], v[162:165], v[182:185], v[112:115]
	v_mfma_f32_16x16x32_bf16 v[108:111], v[132:135], v[190:193], v[108:111]
	v_mfma_f32_16x16x32_bf16 v[104:107], v[162:165], v[190:193], v[104:107]
	v_mfma_f32_16x16x32_bf16 v[100:103], v[132:135], v[198:201], v[100:103]
	v_mfma_f32_16x16x32_bf16 v[96:99], v[162:165], v[198:201], v[96:99]
	v_mfma_f32_16x16x32_bf16 v[124:127], v[158:161], v[174:177], v[124:127]
	v_mfma_f32_16x16x32_bf16 v[120:123], v[166:169], v[174:177], v[120:123]
	v_mfma_f32_16x16x32_bf16 v[116:119], v[158:161], v[186:189], v[116:119]
	v_mfma_f32_16x16x32_bf16 v[112:115], v[166:169], v[186:189], v[112:115]
	v_mfma_f32_16x16x32_bf16 v[108:111], v[158:161], v[194:197], v[108:111]
	v_mfma_f32_16x16x32_bf16 v[104:107], v[166:169], v[194:197], v[104:107]
	s_setprio 2
	s_barrier
	v_mfma_f32_16x16x32_bf16 v[100:103], v[158:161], v[202:205], v[100:103]
	v_mfma_f32_16x16x32_bf16 v[96:99], v[166:169], v[202:205], v[96:99]
	s_setprio 0
	ds_read_b128 v[206:209], v149 offset:49152
	ds_read_b128 v[210:213], v149 offset:50176
	ds_read_b128 v[214:217], v149 offset:51200
	ds_read_b128 v[218:221], v149 offset:52224
	s_waitcnt vmcnt(0)
	s_barrier
; #define LDA(dst, b, h) for (int m = 0; m < 4; ++m) for (int k = 0; k < 2; ++k) \
;     dst[m][k] = *reinterpret_cast<const bf16x8*>(a_rd + ((b) * 2 + (h)) * (HT * 2) + m * 2048 + k * 1024)
; #define LDB(dst, b, h) for (int n = 0; n < 2; ++n) for (int k = 0; k < 2; ++k) \
;     dst[n][k] = *reinterpret_cast<const bf16x8*>(b_rd + ((b) * 2 + (h)) * (HT * 2) + n * 2048 + k * 1024)
; #define MMA(ai, bj, At_, Bt_) do { __builtin_amdgcn_s_setprio(1); \
;     for (int m = 0; m < 4; ++m) for (int n = 0; n < 2; ++n) for (int k = 0; k < 2; ++k) \
;       acc[ai][bj][m][n] = __builtin_amdgcn_mfma_f32_16x16x32_bf16(Bt_[n][k], At_[m][k], acc[ai][bj][m][n], 0, 0, 0); \
;     __builtin_amdgcn_s_setprio(0); } while (0)
; #define WAIT_V(n) asm volatile("s_waitcnt vmcnt(" #n ")" ::: "memory")
; #define WAIT_L(n) asm volatile("s_waitcnt lgkmcnt(" #n ")" ::: "memory")
; #define BAR __builtin_amdgcn_s_barrier()
;     ...
;   { LDB(B0, 1, 0); LDA(At, 1, 0); WAIT_V(2); BAR; WAIT_L(0); MMA(0, 0, At, B0); BAR;
;     LDB(B1, 1, 1); WAIT_V(0); BAR; WAIT_L(0); MMA(0, 1, At, B1); BAR;
;     LDA(At, 1, 1); BAR; WAIT_L(0); MMA(1, 0, At, B0); MMA(1, 1, At, B1); BAR; }
;   if (wr == 0) BAR;
	s_waitcnt lgkmcnt(0)
	s_setprio 1
	s_waitcnt lgkmcnt(0)
	v_mfma_f32_16x16x32_bf16 v[92:95], v[206:209], v[170:173], v[92:95]
	v_mfma_f32_16x16x32_bf16 v[88:91], v[214:217], v[170:173], v[88:91]
	v_mfma_f32_16x16x32_bf16 v[84:87], v[206:209], v[182:185], v[84:87]
	v_mfma_f32_16x16x32_bf16 v[80:83], v[214:217], v[182:185], v[80:83]
	v_mfma_f32_16x16x32_bf16 v[76:79], v[206:209], v[190:193], v[76:79]
	v_mfma_f32_16x16x32_bf16 v[72:75], v[214:217], v[190:193], v[72:75]
	v_mfma_f32_16x16x32_bf16 v[68:71], v[206:209], v[198:201], v[68:71]
	v_mfma_f32_16x16x32_bf16 v[64:67], v[214:217], v[198:201], v[64:67]
	v_mfma_f32_16x16x32_bf16 v[92:95], v[210:213], v[174:177], v[92:95]
	v_mfma_f32_16x16x32_bf16 v[88:91], v[218:221], v[174:177], v[88:91]
	v_mfma_f32_16x16x32_bf16 v[84:87], v[210:213], v[186:189], v[84:87]
	v_mfma_f32_16x16x32_bf16 v[80:83], v[218:221], v[186:189], v[80:83]
	v_mfma_f32_16x16x32_bf16 v[76:79], v[210:213], v[194:197], v[76:79]
	v_mfma_f32_16x16x32_bf16 v[72:75], v[218:221], v[194:197], v[72:75]
	s_setprio 2
	s_barrier
	v_mfma_f32_16x16x32_bf16 v[68:71], v[210:213], v[202:205], v[68:71]
	v_mfma_f32_16x16x32_bf16 v[64:67], v[218:221], v[202:205], v[64:67]
	s_setprio 0
	ds_read_b128 v[170:173], v148 offset:49152
	ds_read_b128 v[174:177], v148 offset:50176
	ds_read_b128 v[182:185], v148 offset:51200
	ds_read_b128 v[186:189], v148 offset:52224
	ds_read_b128 v[190:193], v148 offset:53248
	ds_read_b128 v[194:197], v148 offset:54272
	ds_read_b128 v[198:201], v148 offset:55296
	ds_read_b128 v[202:205], v148 offset:56320
	s_barrier
	s_waitcnt lgkmcnt(0)
	s_setprio 1
	s_waitcnt lgkmcnt(0)
	v_mfma_f32_16x16x32_bf16 v[60:63], v[132:135], v[170:173], v[60:63]
	v_mfma_f32_16x16x32_bf16 v[56:59], v[162:165], v[170:173], v[56:59]
	v_mfma_f32_16x16x32_bf16 v[52:55], v[132:135], v[182:185], v[52:55]
	v_mfma_f32_16x16x32_bf16 v[48:51], v[162:165], v[182:185], v[48:51]
	v_mfma_f32_16x16x32_bf16 v[44:47], v[132:135], v[190:193], v[44:47]
	v_mfma_f32_16x16x32_bf16 v[40:43], v[162:165], v[190:193], v[40:43]
	v_mfma_f32_16x16x32_bf16 v[36:39], v[132:135], v[198:201], v[36:39]
	v_mfma_f32_16x16x32_bf16 v[32:35], v[162:165], v[198:201], v[32:35]
	v_mfma_f32_16x16x32_bf16 v[60:63], v[158:161], v[174:177], v[60:63]
	v_mfma_f32_16x16x32_bf16 v[56:59], v[166:169], v[174:177], v[56:59]
	v_mfma_f32_16x16x32_bf16 v[52:55], v[158:161], v[186:189], v[52:55]
	v_mfma_f32_16x16x32_bf16 v[48:51], v[166:169], v[186:189], v[48:51]
	v_mfma_f32_16x16x32_bf16 v[44:47], v[158:161], v[194:197], v[44:47]
	v_mfma_f32_16x16x32_bf16 v[40:43], v[166:169], v[194:197], v[40:43]
	v_mfma_f32_16x16x32_bf16 v[36:39], v[158:161], v[202:205], v[36:39]
	v_mfma_f32_16x16x32_bf16 v[32:35], v[166:169], v[202:205], v[32:35]
	s_setprio 0
	s_setprio 1
	v_mfma_f32_16x16x32_bf16 v[28:31], v[206:209], v[170:173], v[28:31]
	v_mfma_f32_16x16x32_bf16 v[24:27], v[214:217], v[170:173], v[24:27]
	v_mfma_f32_16x16x32_bf16 v[20:23], v[206:209], v[182:185], v[20:23]
	v_mfma_f32_16x16x32_bf16 v[16:19], v[214:217], v[182:185], v[16:19]
	v_mfma_f32_16x16x32_bf16 v[12:15], v[206:209], v[190:193], v[12:15]
	v_mfma_f32_16x16x32_bf16 v[8:11], v[214:217], v[190:193], v[8:11]
	v_mfma_f32_16x16x32_bf16 v[4:7], v[206:209], v[198:201], v[4:7]
	v_mfma_f32_16x16x32_bf16 v[0:3], v[214:217], v[198:201], v[0:3]
	v_mfma_f32_16x16x32_bf16 v[28:31], v[210:213], v[174:177], v[28:31]
	v_mfma_f32_16x16x32_bf16 v[24:27], v[218:221], v[174:177], v[24:27]
	v_mfma_f32_16x16x32_bf16 v[20:23], v[210:213], v[186:189], v[20:23]
	v_mfma_f32_16x16x32_bf16 v[16:19], v[218:221], v[186:189], v[16:19]
	v_mfma_f32_16x16x32_bf16 v[12:15], v[210:213], v[194:197], v[12:15]
	v_mfma_f32_16x16x32_bf16 v[8:11], v[218:221], v[194:197], v[8:11]
	s_setprio 2
	s_barrier
	v_mfma_f32_16x16x32_bf16 v[4:7], v[210:213], v[202:205], v[4:7]
	v_mfma_f32_16x16x32_bf16 v[0:3], v[218:221], v[202:205], v[0:3]
	s_setprio 0
	v_cmp_gt_u32_e32 vcc, s60, v139
	s_and_saveexec_b64 s[26:27], vcc
	s_cbranch_execz .LBB0_1868
	s_barrier

; #define STAGE_A(P, br, kt) do { const char* _base = (const char*)(((kt) < G.ksplit ? G.A1 : A2m) + (long)(br) * G.lda + (long)(kt) * BK); \
;     __builtin_amdgcn_global_load_lds((const unsigned*)(_base + aoff0), (unsigned*)((char*)(P) + sb0), 16, 0, 0); \
;     __builtin_amdgcn_global_load_lds((const unsigned*)(_base + aoff1), (unsigned*)((char*)(P) + sb1), 16, 0, 0); } while (0)
; #define STAGE_B(P, br, kt) do { const char* _base = (const char*)(G.Bt + (long)(br) * G.ldb + (long)(kt) * BK); \
;     __builtin_amdgcn_global_load_lds((const unsigned*)(_base + boff0), (unsigned*)((char*)(P) + sb0), 16, 0, 0); \
;     __builtin_amdgcn_global_load_lds((const unsigned*)(_base + boff1), (unsigned*)((char*)(P) + sb1), 16, 0, 0); } while (0)
; #define LDA(dst, b, h) for (int m = 0; m < 4; ++m) for (int k = 0; k < 2; ++k) \
;     dst[m][k] = *reinterpret_cast<const bf16x8*>(a_rd + ((b) * 2 + (h)) * (HT * 2) + m * 2048 + k * 1024)
; #define BAR __builtin_amdgcn_s_barrier()
;     ...
;   const int sb0 = t1 * 16, sb1 = sb0 + 8192;
;   const int swz_ = lds_byte(fr, fq * 8);
;   const char* a_rd = shmc + wr * 8192 + swz_;
;   const char* b_rd = shmc + 4 * (HT * 2) + wc * 4096 + swz_;
;   int r0_, c0_, r1_, c1_; stage_rc(sb0, r0_, c0_); stage_rc(sb1, r1_, c1_);
;   const unsigned aoff0 = (unsigned)(r0_ * G.lda + c0_) * 2u, aoff1 = (unsigned)(r1_ * G.lda + c1_) * 2u;
;   const unsigned boff0 = (unsigned)(r0_ * G.ldb + c0_) * 2u, boff1 = (unsigned)(r1_ * G.ldb + c1_) * 2u;
;   f32x4 acc[2][2][4][2] = {};
;   bf16x8 At[4][2], B0[2][2], B1[2][2];
;   const int nt = K / BK;
;   if (EPI == EPI_RESID || first) {
;     STAGE_B(SB(0, 0), bcol, 0); STAGE_A(SA(0, 0), brow, 0);
;     STAGE_B(SB(0, 1), bcol + HALF, 0); STAGE_A(SA(0, 1), brow + HALF, 0);
;   }
;   if (wr == 1) BAR;
;   WAIT_V(0); BAR;
;   STAGE_B(SB(1, 0), bcol, 1); STAGE_A(SA(1, 0), brow, 1); STAGE_B(SB(1, 1), bcol + HALF, 1);
;   WAIT_V(6); BAR;
;   for (int t = 0; t < nt - 2; t += 2) {
;     LDB(B0, 0, 0); SCHED; LDA(At, 0, 0); STAGE_A(SA(1, 1), brow + HALF, t + 1);
;     WAIT_L(8); BAR; WAIT_L(0); MMA(0, 0, At, B0); BAR; SCHED;
;     LDB(B1, 0, 1); STAGE_B(SB(0, 0), bcol, t + 2);
;     BAR; WAIT_L(0); MMA(0, 1, At, B1); BAR;
;     LDA(At, 0, 1); STAGE_A(SA(0, 0), brow, t + 2);
;     BAR; WAIT_L(0); MMA(1, 0, At, B0); BAR; SCHED;
;     STAGE_B(SB(0, 1), bcol + HALF, t + 2);
;     WAIT_V(6); BAR; MMA(1, 1, At, B1); BAR;
.LBB0_2500:
	s_or_b64 exec, exec, s[8:9]
	v_and_b32_e32 v20, 15, v144
	v_lshlrev_b32_e32 v22, 2, v144
	v_and_b32_e32 v21, 48, v144
	v_lshlrev_b32_e32 v20, 6, v20
	v_and_b32_e32 v22, 32, v22
	v_bitop3_b32 v20, v20, v22, v21 bitop3:0x36
	v_lshlrev_b32_e32 v21, 6, v144
	v_and_b32_e32 v21, 0x3000, v21
	v_add_u32_e32 v21, s35, v21
	v_readlane_b32 s35, v253, 46
	s_mov_b64 s[38:39], 0x80
	v_lshl_add_u64 v[2:3], v[2:3], 0, s[38:39]
	v_add_u32_e32 v153, s35, v12
	v_add_u32_e32 v154, 0x2000, v153
	v_readfirstlane_b32 s35, v153
	s_mov_b32 m0, s35
	v_readfirstlane_b32 s35, v154
	v_add_u32_e32 v155, 0x8000, v147
	s_waitcnt vmcnt(0)
	s_barrier
	global_load_lds_dwordx4 v[2:3], off
	v_lshl_add_u64 v[2:3], v[4:5], 0, s[38:39]
	s_mov_b32 m0, s35
	v_readfirstlane_b32 s35, v155
	v_add_u32_e32 v156, 0xa000, v147
	global_load_lds_dwordx4 v[2:3], off
	v_lshl_add_u64 v[2:3], v[6:7], 0, s[38:39]
	s_mov_b32 m0, s35
	v_readfirstlane_b32 s35, v156
	s_lshl_b64 s[8:9], s[18:19], 10
	global_load_lds_dwordx4 v[2:3], off
	s_mov_b32 m0, s35
	v_readlane_b32 s35, v253, 47
	s_add_u32 s36, s36, 0x84080
	v_lshl_add_u64 v[2:3], v[8:9], 0, s[38:39]
	v_add_u32_e32 v157, s35, v12
	s_addc_u32 s37, s37, 0
	v_readfirstlane_b32 s35, v157
	v_add_u32_e32 v158, 0x2000, v157
	global_load_lds_dwordx4 v[2:3], off
	v_lshl_add_u64 v[2:3], s[36:37], 0, v[180:181]
	s_mov_b32 m0, s35
	v_readfirstlane_b32 s35, v158
	global_load_lds_dwordx4 v[2:3], off
	v_lshl_add_u64 v[0:1], s[36:37], 0, v[0:1]
	s_mov_b32 m0, s35
	v_lshrrev_b32_e32 v2, 1, v11
	global_load_lds_dwordx4 v[0:1], off
	v_lshrrev_b32_e32 v1, 1, v10
	v_mul_lo_u32 v0, v13, s62
	v_mad_u64_u32 v[0:1], s[36:37], v1, s84, v[0:1]
	v_or_b32_e32 v0, v0, v14
	v_add_lshl_u32 v180, v0, v16, 1
	v_mul_lo_u32 v0, v15, s62
	v_lshlrev_b32_e32 v3, 11, v15
	v_mad_u64_u32 v[0:1], s[36:37], v2, s84, v[0:1]
	v_lshl_add_u32 v2, v2, 15, v3
	v_and_b32_e32 v3, 1, v11
	s_add_u32 s24, s12, s24
	v_lshl_or_b32 v2, v3, 6, v2
	s_addc_u32 s25, s13, s25
	v_lshl_add_u32 v2, v17, 1, v2
	v_mov_b32_e32 v3, v181
	v_or_b32_e32 v0, v0, v18
	v_lshl_add_u64 v[136:137], s[10:11], 0, v[130:131]
	v_lshl_add_u64 v[138:139], s[10:11], 0, v[2:3]
	s_add_u32 s10, s12, s22
	s_waitcnt vmcnt(6)
	v_add_lshl_u32 v0, v0, v17, 1
	v_mov_b32_e32 v1, v181
	s_addc_u32 s11, s13, s23
	v_lshl_add_u32 v19, v19, 13, 32
	v_lshl_add_u64 v[134:135], s[24:25], 0, v[0:1]
	v_lshl_add_u64 v[142:143], s[10:11], 0, v[0:1]
	v_lshl_add_u64 v[132:133], s[24:25], 0, v[180:181]
	v_lshl_add_u64 v[140:141], s[10:11], 0, v[180:181]
	s_mov_b32 s22, -2
	s_mov_b64 s[10:11], 0
	v_add_u32_e32 v149, v21, v20
	v_add_u32_e32 v146, v19, v20
	s_waitcnt vmcnt(0)
	s_mov_b64 s[36:37], 0x40080
	s_mov_b64 s[38:39], 0x54e8100
	s_mov_b64 s[40:41], 0x556c100
	s_mov_b64 s[42:43], 0x40100
	s_mov_b64 s[44:45], 0x54e8180
	s_mov_b64 s[46:47], 0x556c180
	s_barrier
	ds_read_b128 v[162:165], v149
	ds_read_b128 v[166:169], v149 offset:1024
	ds_read_b128 v[170:173], v149 offset:2048
	ds_read_b128 v[174:177], v149 offset:3072
	s_add_i32 s22, s22, 2
	s_cmp_lt_u32 s22, 16
	s_cselect_b32 s25, s28, s34
	s_cselect_b32 s24, s27, s31
	v_lshl_add_u64 v[160:161], s[24:25], 0, v[136:137]
	v_add_u32_e32 v159, 0xc000, v147
	v_lshl_add_u64 v[160:161], v[160:161], 0, s[10:11]
	v_readfirstlane_b32 s23, v159
	v_lshl_add_u64 v[160:161], v[160:161], 0, s[36:37]
	s_mov_b32 m0, s23
	ds_read_b128 v[182:185], v146
	ds_read_b128 v[186:189], v146 offset:1024
	ds_read_b128 v[190:193], v146 offset:2048
	ds_read_b128 v[194:197], v146 offset:3072
	ds_read_b128 v[198:201], v146 offset:4096
	ds_read_b128 v[202:205], v146 offset:5120
	ds_read_b128 v[206:209], v146 offset:6144
	ds_read_b128 v[210:213], v146 offset:7168
	global_load_lds_dwordx4 v[160:161], off
	v_lshl_add_u64 v[160:161], s[24:25], 0, v[138:139]
	v_lshl_add_u64 v[160:161], v[160:161], 0, s[10:11]
	v_lshl_add_u64 v[178:179], v[160:161], 0, s[36:37]
	v_add_u32_e32 v160, 0xe000, v147
	s_nop 0
	v_readfirstlane_b32 s23, v160
	s_mov_b32 m0, s23
	s_nop 0
	global_load_lds_dwordx4 v[178:179], off
	ds_read_b128 v[214:217], v149 offset:16384
	ds_read_b128 v[218:221], v149 offset:17408
	ds_read_b128 v[246:249], v149 offset:18432
	ds_read_b128 v[230:233], v149 offset:19456
	s_waitcnt lgkmcnt(0)
	s_waitcnt vmcnt(8)
	s_barrier
	s_setprio 1
	v_mfma_f32_16x16x32_bf16 v[124:127], v[162:165], v[182:185], 0
	v_mfma_f32_16x16x32_bf16 v[120:123], v[170:173], v[182:185], 0
	v_mfma_f32_16x16x32_bf16 v[116:119], v[162:165], v[190:193], 0
	v_mfma_f32_16x16x32_bf16 v[112:115], v[170:173], v[190:193], 0
	v_mfma_f32_16x16x32_bf16 v[108:111], v[162:165], v[198:201], 0
	v_mfma_f32_16x16x32_bf16 v[104:107], v[170:173], v[198:201], 0
	v_mfma_f32_16x16x32_bf16 v[100:103], v[162:165], v[206:209], 0
	v_mfma_f32_16x16x32_bf16 v[96:99], v[170:173], v[206:209], 0
	v_mfma_f32_16x16x32_bf16 v[124:127], v[166:169], v[186:189], v[124:127]
	v_mfma_f32_16x16x32_bf16 v[120:123], v[174:177], v[186:189], v[120:123]
	v_mfma_f32_16x16x32_bf16 v[116:119], v[166:169], v[194:197], v[116:119]
	v_mfma_f32_16x16x32_bf16 v[112:115], v[174:177], v[194:197], v[112:115]
	v_mfma_f32_16x16x32_bf16 v[108:111], v[166:169], v[202:205], v[108:111]
	v_mfma_f32_16x16x32_bf16 v[104:107], v[174:177], v[202:205], v[104:107]
	v_mfma_f32_16x16x32_bf16 v[100:103], v[166:169], v[210:213], v[100:103]
	v_mfma_f32_16x16x32_bf16 v[96:99], v[174:177], v[210:213], v[96:99]
	v_mfma_f32_16x16x32_bf16 v[92:95], v[214:217], v[182:185], 0
	v_mfma_f32_16x16x32_bf16 v[88:91], v[246:249], v[182:185], 0
	v_mfma_f32_16x16x32_bf16 v[84:87], v[214:217], v[190:193], 0
	v_mfma_f32_16x16x32_bf16 v[80:83], v[246:249], v[190:193], 0
	v_mfma_f32_16x16x32_bf16 v[76:79], v[214:217], v[198:201], 0
	v_mfma_f32_16x16x32_bf16 v[72:75], v[246:249], v[198:201], 0
	v_mfma_f32_16x16x32_bf16 v[68:71], v[214:217], v[206:209], 0
	v_mfma_f32_16x16x32_bf16 v[64:67], v[246:249], v[206:209], 0
	v_mfma_f32_16x16x32_bf16 v[92:95], v[218:221], v[186:189], v[92:95]
	v_mfma_f32_16x16x32_bf16 v[88:91], v[230:233], v[186:189], v[88:91]
	v_mfma_f32_16x16x32_bf16 v[84:87], v[218:221], v[194:197], v[84:87]
	v_mfma_f32_16x16x32_bf16 v[80:83], v[230:233], v[194:197], v[80:83]
	v_mfma_f32_16x16x32_bf16 v[76:79], v[218:221], v[202:205], v[76:79]
	v_mfma_f32_16x16x32_bf16 v[72:75], v[230:233], v[202:205], v[72:75]
	s_setprio 2
	s_barrier
; #define STAGE_A(P, br, kt) do { const char* _base = (const char*)(((kt) < G.ksplit ? G.A1 : A2m) + (long)(br) * G.lda + (long)(kt) * BK); \
;     __builtin_amdgcn_global_load_lds((const unsigned*)(_base + aoff0), (unsigned*)((char*)(P) + sb0), 16, 0, 0); \
;     __builtin_amdgcn_global_load_lds((const unsigned*)(_base + aoff1), (unsigned*)((char*)(P) + sb1), 16, 0, 0); } while (0)
; #define STAGE_B(P, br, kt) do { const char* _base = (const char*)(G.Bt + (long)(br) * G.ldb + (long)(kt) * BK); \
;     __builtin_amdgcn_global_load_lds((const unsigned*)(_base + boff0), (unsigned*)((char*)(P) + sb0), 16, 0, 0); \
;     __builtin_amdgcn_global_load_lds((const unsigned*)(_base + boff1), (unsigned*)((char*)(P) + sb1), 16, 0, 0); } while (0)
; #define LDA(dst, b, h) for (int m = 0; m < 4; ++m) for (int k = 0; k < 2; ++k) \
;     dst[m][k] = *reinterpret_cast<const bf16x8*>(a_rd + ((b) * 2 + (h)) * (HT * 2) + m * 2048 + k * 1024)
; #define LDB(dst, b, h) for (int n = 0; n < 2; ++n) for (int k = 0; k < 2; ++k) \
;     dst[n][k] = *reinterpret_cast<const bf16x8*>(b_rd + ((b) * 2 + (h)) * (HT * 2) + n * 2048 + k * 1024)
; #define MMA(ai, bj, At_, Bt_) do { __builtin_amdgcn_s_setprio(1); \
;     for (int m = 0; m < 4; ++m) for (int n = 0; n < 2; ++n) for (int k = 0; k < 2; ++k) \
;       acc[ai][bj][m][n] = __builtin_amdgcn_mfma_f32_16x16x32_bf16(Bt_[n][k], At_[m][k], acc[ai][bj][m][n], 0, 0, 0); \
;     __builtin_amdgcn_s_setprio(0); } while (0)
; #define WAIT_V(n) asm volatile("s_waitcnt vmcnt(" #n ")" ::: "memory")
; #define WAIT_L(n) asm volatile("s_waitcnt lgkmcnt(" #n ")" ::: "memory")
; #define BAR __builtin_amdgcn_s_barrier()
; #define SCHED __builtin_amdgcn_sched_barrier(0)
;     ...
;     LDB(B0, 0, 0); SCHED; LDA(At, 0, 0); STAGE_A(SA(1, 1), brow + HALF, t + 1);
;     WAIT_L(8); BAR; WAIT_L(0); MMA(0, 0, At, B0); BAR; SCHED;
;     LDB(B1, 0, 1); STAGE_B(SB(0, 0), bcol, t + 2);
;     BAR; WAIT_L(0); MMA(0, 1, At, B1); BAR;
;     LDA(At, 0, 1); STAGE_A(SA(0, 0), brow, t + 2);
;     BAR; WAIT_L(0); MMA(1, 0, At, B0); BAR; SCHED;
;     STAGE_B(SB(0, 1), bcol + HALF, t + 2);
;     WAIT_V(6); BAR; MMA(1, 1, At, B1); BAR;
;     LDB(B0, 1, 0); SCHED; LDA(At, 1, 0); STAGE_A(SA(0, 1), brow + HALF, t + 2);
;     WAIT_L(8); BAR; WAIT_L(0); MMA(0, 0, At, B0); BAR; SCHED;
;     LDB(B1, 1, 1); STAGE_B(SB(1, 0), bcol, t + 3);
	v_mfma_f32_16x16x32_bf16 v[68:71], v[218:221], v[210:213], v[68:71]
	v_mfma_f32_16x16x32_bf16 v[64:67], v[230:233], v[210:213], v[64:67]
	s_setprio 0
	v_lshl_add_u64 v[178:179], v[132:133], 0, s[10:11]
	v_readfirstlane_b32 s23, v145
	v_lshl_add_u64 v[222:223], v[178:179], 0, s[38:39]
	s_mov_b32 m0, s23
	v_add_u32_e32 v161, 0x2000, v145
	global_load_lds_dwordx4 v[222:223], off
	v_lshl_add_u64 v[222:223], v[134:135], 0, s[10:11]
	v_readfirstlane_b32 s23, v161
	v_lshl_add_u64 v[234:235], v[222:223], 0, s[38:39]
	s_mov_b32 m0, s23
	s_nop 0
	global_load_lds_dwordx4 v[234:235], off
	s_cmp_lt_u32 s22, 14
	s_cselect_b32 s25, s28, s34
	s_cselect_b32 s24, s27, s31
	v_lshl_add_u64 v[234:235], s[24:25], 0, v[136:137]
	v_lshl_add_u64 v[234:235], v[234:235], 0, s[10:11]
	v_readfirstlane_b32 s23, v147
	v_lshl_add_u64 v[236:237], v[234:235], 0, s[90:91]
	s_mov_b32 m0, s23
	ds_read_b128 v[182:185], v146 offset:16384
	ds_read_b128 v[186:189], v146 offset:17408
	ds_read_b128 v[190:193], v146 offset:18432
	ds_read_b128 v[194:197], v146 offset:19456
	ds_read_b128 v[198:201], v146 offset:20480
	ds_read_b128 v[202:205], v146 offset:21504
	ds_read_b128 v[206:209], v146 offset:22528
	ds_read_b128 v[210:213], v146 offset:23552
	global_load_lds_dwordx4 v[236:237], off
	v_lshl_add_u64 v[236:237], s[24:25], 0, v[138:139]
	v_lshl_add_u64 v[236:237], v[236:237], 0, s[10:11]
	v_readfirstlane_b32 s23, v148
	v_lshl_add_u64 v[238:239], v[236:237], 0, s[90:91]
	s_mov_b32 m0, s23
	s_nop 0
	global_load_lds_dwordx4 v[238:239], off
	v_lshl_add_u64 v[238:239], v[140:141], 0, s[10:11]
	v_readfirstlane_b32 s23, v150
	v_add_u32_e32 v161, 0x2000, v150
	v_lshl_add_u64 v[250:251], v[238:239], 0, s[40:41]
	s_mov_b32 m0, s23
	v_lshl_add_u64 v[240:241], v[142:143], 0, s[10:11]
	v_readfirstlane_b32 s23, v161
	global_load_lds_dwordx4 v[250:251], off
	v_lshl_add_u64 v[250:251], v[240:241], 0, s[40:41]
	s_mov_b32 m0, s23
	s_nop 0
	global_load_lds_dwordx4 v[250:251], off
	s_waitcnt lgkmcnt(0)
	s_waitcnt vmcnt(8)
	s_barrier
	s_setprio 1
	v_mfma_f32_16x16x32_bf16 v[60:63], v[162:165], v[182:185], 0
	v_mfma_f32_16x16x32_bf16 v[56:59], v[170:173], v[182:185], 0
	v_mfma_f32_16x16x32_bf16 v[52:55], v[162:165], v[190:193], 0
	v_mfma_f32_16x16x32_bf16 v[48:51], v[170:173], v[190:193], 0
	v_mfma_f32_16x16x32_bf16 v[44:47], v[162:165], v[198:201], 0
	v_mfma_f32_16x16x32_bf16 v[40:43], v[170:173], v[198:201], 0
	v_mfma_f32_16x16x32_bf16 v[36:39], v[162:165], v[206:209], 0
	v_mfma_f32_16x16x32_bf16 v[32:35], v[170:173], v[206:209], 0
	v_mfma_f32_16x16x32_bf16 v[60:63], v[166:169], v[186:189], v[60:63]
	v_mfma_f32_16x16x32_bf16 v[56:59], v[174:177], v[186:189], v[56:59]
	v_mfma_f32_16x16x32_bf16 v[52:55], v[166:169], v[194:197], v[52:55]
	v_mfma_f32_16x16x32_bf16 v[48:51], v[174:177], v[194:197], v[48:51]
	v_mfma_f32_16x16x32_bf16 v[44:47], v[166:169], v[202:205], v[44:47]
	v_mfma_f32_16x16x32_bf16 v[40:43], v[174:177], v[202:205], v[40:43]
	v_mfma_f32_16x16x32_bf16 v[36:39], v[166:169], v[210:213], v[36:39]
	v_mfma_f32_16x16x32_bf16 v[32:35], v[174:177], v[210:213], v[32:35]
	v_mfma_f32_16x16x32_bf16 v[28:31], v[214:217], v[182:185], 0
	v_mfma_f32_16x16x32_bf16 v[24:27], v[246:249], v[182:185], 0
	v_mfma_f32_16x16x32_bf16 v[20:23], v[214:217], v[190:193], 0
	v_mfma_f32_16x16x32_bf16 v[16:19], v[246:249], v[190:193], 0
	v_mfma_f32_16x16x32_bf16 v[12:15], v[214:217], v[198:201], 0
	v_mfma_f32_16x16x32_bf16 v[8:11], v[246:249], v[198:201], 0
	v_mfma_f32_16x16x32_bf16 v[4:7], v[214:217], v[206:209], 0
	v_mfma_f32_16x16x32_bf16 v[0:3], v[246:249], v[206:209], 0
	v_mfma_f32_16x16x32_bf16 v[28:31], v[218:221], v[186:189], v[28:31]
	v_mfma_f32_16x16x32_bf16 v[24:27], v[230:233], v[186:189], v[24:27]
	v_mfma_f32_16x16x32_bf16 v[20:23], v[218:221], v[194:197], v[20:23]
	v_mfma_f32_16x16x32_bf16 v[16:19], v[230:233], v[194:197], v[16:19]
	v_mfma_f32_16x16x32_bf16 v[12:15], v[218:221], v[202:205], v[12:15]
	v_mfma_f32_16x16x32_bf16 v[8:11], v[230:233], v[202:205], v[8:11]
	s_setprio 2
	s_barrier
	v_mfma_f32_16x16x32_bf16 v[4:7], v[218:221], v[210:213], v[4:7]
	v_mfma_f32_16x16x32_bf16 v[0:3], v[230:233], v[210:213], v[0:3]
	s_setprio 0
	ds_read_b128 v[162:165], v149 offset:32768
	ds_read_b128 v[166:169], v149 offset:33792
	ds_read_b128 v[170:173], v149 offset:34816
	ds_read_b128 v[174:177], v149 offset:35840
	v_readfirstlane_b32 s23, v151
	v_lshl_add_u64 v[214:215], v[234:235], 0, s[42:43]
	s_mov_b32 m0, s23
	v_readfirstlane_b32 s23, v152
	ds_read_b128 v[182:185], v146 offset:32768
	ds_read_b128 v[186:189], v146 offset:33792
	ds_read_b128 v[190:193], v146 offset:34816
	ds_read_b128 v[194:197], v146 offset:35840
	ds_read_b128 v[198:201], v146 offset:36864
	ds_read_b128 v[202:205], v146 offset:37888
	ds_read_b128 v[206:209], v146 offset:38912
	ds_read_b128 v[210:213], v146 offset:39936
	global_load_lds_dwordx4 v[214:215], off
	v_lshl_add_u64 v[214:215], v[236:237], 0, s[42:43]
	s_mov_b32 m0, s23
	s_nop 0
	global_load_lds_dwordx4 v[214:215], off
	ds_read_b128 v[214:217], v149 offset:49152
	ds_read_b128 v[218:221], v149 offset:50176
	ds_read_b128 v[230:233], v149 offset:51200
	ds_read_b128 v[246:249], v149 offset:52224
	s_waitcnt lgkmcnt(0)
	s_waitcnt vmcnt(8)
	s_barrier
; #define STAGE_A(P, br, kt) do { const char* _base = (const char*)(((kt) < G.ksplit ? G.A1 : A2m) + (long)(br) * G.lda + (long)(kt) * BK); \
;     __builtin_amdgcn_global_load_lds((const unsigned*)(_base + aoff0), (unsigned*)((char*)(P) + sb0), 16, 0, 0); \
;     __builtin_amdgcn_global_load_lds((const unsigned*)(_base + aoff1), (unsigned*)((char*)(P) + sb1), 16, 0, 0); } while (0)
; #define STAGE_B(P, br, kt) do { const char* _base = (const char*)(G.Bt + (long)(br) * G.ldb + (long)(kt) * BK); \
;     __builtin_amdgcn_global_load_lds((const unsigned*)(_base + boff0), (unsigned*)((char*)(P) + sb0), 16, 0, 0); \
;     __builtin_amdgcn_global_load_lds((const unsigned*)(_base + boff1), (unsigned*)((char*)(P) + sb1), 16, 0, 0); } while (0)
; #define LDA(dst, b, h) for (int m = 0; m < 4; ++m) for (int k = 0; k < 2; ++k) \
;     dst[m][k] = *reinterpret_cast<const bf16x8*>(a_rd + ((b) * 2 + (h)) * (HT * 2) + m * 2048 + k * 1024)
; #define LDB(dst, b, h) for (int n = 0; n < 2; ++n) for (int k = 0; k < 2; ++k) \
;     dst[n][k] = *reinterpret_cast<const bf16x8*>(b_rd + ((b) * 2 + (h)) * (HT * 2) + n * 2048 + k * 1024)
; #define MMA(ai, bj, At_, Bt_) do { __builtin_amdgcn_s_setprio(1); \
;     for (int m = 0; m < 4; ++m) for (int n = 0; n < 2; ++n) for (int k = 0; k < 2; ++k) \
;       acc[ai][bj][m][n] = __builtin_amdgcn_mfma_f32_16x16x32_bf16(Bt_[n][k], At_[m][k], acc[ai][bj][m][n], 0, 0, 0); \
;     __builtin_amdgcn_s_setprio(0); } while (0)
; #define WAIT_V(n) asm volatile("s_waitcnt vmcnt(" #n ")" ::: "memory")
; #define WAIT_L(n) asm volatile("s_waitcnt lgkmcnt(" #n ")" ::: "memory")
; #define BAR __builtin_amdgcn_s_barrier()
; #define SCHED __builtin_amdgcn_sched_barrier(0)
;     ...
;     LDB(B0, 1, 0); SCHED; LDA(At, 1, 0); STAGE_A(SA(0, 1), brow + HALF, t + 2);
;     WAIT_L(8); BAR; WAIT_L(0); MMA(0, 0, At, B0); BAR; SCHED;
;     LDB(B1, 1, 1); STAGE_B(SB(1, 0), bcol, t + 3);
;     BAR; WAIT_L(0); MMA(0, 1, At, B1); BAR;
;     LDA(At, 1, 1); STAGE_A(SA(1, 0), brow, t + 3);
;     BAR; WAIT_L(0); MMA(1, 0, At, B0); BAR; SCHED;
;     STAGE_B(SB(1, 1), bcol + HALF, t + 3);
;     WAIT_V(6); BAR; MMA(1, 1, At, B1); BAR;
;   }
	s_setprio 1
	v_mfma_f32_16x16x32_bf16 v[124:127], v[162:165], v[182:185], v[124:127]
	v_mfma_f32_16x16x32_bf16 v[120:123], v[170:173], v[182:185], v[120:123]
	v_mfma_f32_16x16x32_bf16 v[116:119], v[162:165], v[190:193], v[116:119]
	v_mfma_f32_16x16x32_bf16 v[112:115], v[170:173], v[190:193], v[112:115]
	v_mfma_f32_16x16x32_bf16 v[108:111], v[162:165], v[198:201], v[108:111]
	v_mfma_f32_16x16x32_bf16 v[104:107], v[170:173], v[198:201], v[104:107]
	v_mfma_f32_16x16x32_bf16 v[100:103], v[162:165], v[206:209], v[100:103]
	v_mfma_f32_16x16x32_bf16 v[96:99], v[170:173], v[206:209], v[96:99]
	v_mfma_f32_16x16x32_bf16 v[124:127], v[166:169], v[186:189], v[124:127]
	v_mfma_f32_16x16x32_bf16 v[120:123], v[174:177], v[186:189], v[120:123]
	v_mfma_f32_16x16x32_bf16 v[116:119], v[166:169], v[194:197], v[116:119]
	v_mfma_f32_16x16x32_bf16 v[112:115], v[174:177], v[194:197], v[112:115]
	v_mfma_f32_16x16x32_bf16 v[108:111], v[166:169], v[202:205], v[108:111]
	v_mfma_f32_16x16x32_bf16 v[104:107], v[174:177], v[202:205], v[104:107]
	v_mfma_f32_16x16x32_bf16 v[100:103], v[166:169], v[210:213], v[100:103]
	v_mfma_f32_16x16x32_bf16 v[96:99], v[174:177], v[210:213], v[96:99]
	v_mfma_f32_16x16x32_bf16 v[92:95], v[214:217], v[182:185], v[92:95]
	v_mfma_f32_16x16x32_bf16 v[88:91], v[230:233], v[182:185], v[88:91]
	v_mfma_f32_16x16x32_bf16 v[84:87], v[214:217], v[190:193], v[84:87]
	v_mfma_f32_16x16x32_bf16 v[80:83], v[230:233], v[190:193], v[80:83]
	v_mfma_f32_16x16x32_bf16 v[76:79], v[214:217], v[198:201], v[76:79]
	v_mfma_f32_16x16x32_bf16 v[72:75], v[230:233], v[198:201], v[72:75]
	v_mfma_f32_16x16x32_bf16 v[68:71], v[214:217], v[206:209], v[68:71]
	v_mfma_f32_16x16x32_bf16 v[64:67], v[230:233], v[206:209], v[64:67]
	v_mfma_f32_16x16x32_bf16 v[92:95], v[218:221], v[186:189], v[92:95]
	v_mfma_f32_16x16x32_bf16 v[88:91], v[246:249], v[186:189], v[88:91]
	v_mfma_f32_16x16x32_bf16 v[84:87], v[218:221], v[194:197], v[84:87]
	v_mfma_f32_16x16x32_bf16 v[80:83], v[246:249], v[194:197], v[80:83]
	v_mfma_f32_16x16x32_bf16 v[76:79], v[218:221], v[202:205], v[76:79]
	v_mfma_f32_16x16x32_bf16 v[72:75], v[246:249], v[202:205], v[72:75]
	s_setprio 2
	s_barrier
	v_mfma_f32_16x16x32_bf16 v[68:71], v[218:221], v[210:213], v[68:71]
	v_mfma_f32_16x16x32_bf16 v[64:67], v[246:249], v[210:213], v[64:67]
	s_setprio 0
	v_readfirstlane_b32 s23, v153
	v_lshl_add_u64 v[178:179], v[178:179], 0, s[44:45]
	s_mov_b32 m0, s23
	v_readfirstlane_b32 s23, v154
	global_load_lds_dwordx4 v[178:179], off
	v_lshl_add_u64 v[178:179], v[222:223], 0, s[44:45]
	s_mov_b32 m0, s23
	s_nop 0
	global_load_lds_dwordx4 v[178:179], off
	s_cmp_lt_u32 s22, 13
	s_cselect_b32 s25, s28, s34
	s_cselect_b32 s24, s27, s31
	v_lshl_add_u64 v[178:179], s[24:25], 0, v[136:137]
	v_lshl_add_u64 v[178:179], v[178:179], 0, s[10:11]
	v_readfirstlane_b32 s23, v155
	v_lshl_add_u64 v[178:179], v[178:179], 0, s[88:89]
	s_mov_b32 m0, s23
	ds_read_b128 v[182:185], v146 offset:49152
	ds_read_b128 v[186:189], v146 offset:50176
	ds_read_b128 v[190:193], v146 offset:51200
	ds_read_b128 v[194:197], v146 offset:52224
	ds_read_b128 v[198:201], v146 offset:53248
	ds_read_b128 v[202:205], v146 offset:54272
	ds_read_b128 v[206:209], v146 offset:55296
	ds_read_b128 v[210:213], v146 offset:56320
	global_load_lds_dwordx4 v[178:179], off
	v_lshl_add_u64 v[178:179], s[24:25], 0, v[138:139]
	v_lshl_add_u64 v[178:179], v[178:179], 0, s[10:11]
	v_readfirstlane_b32 s23, v156
	v_lshl_add_u64 v[178:179], v[178:179], 0, s[88:89]
	s_mov_b32 m0, s23
	s_nop 0
	global_load_lds_dwordx4 v[178:179], off
	v_readfirstlane_b32 s23, v157
	v_lshl_add_u64 v[250:251], v[238:239], 0, s[46:47]
	s_mov_b32 m0, s23
	v_readfirstlane_b32 s23, v158
	global_load_lds_dwordx4 v[250:251], off
	v_lshl_add_u64 v[250:251], v[240:241], 0, s[46:47]
	s_mov_b32 m0, s23
	s_nop 0
	global_load_lds_dwordx4 v[250:251], off
	s_waitcnt lgkmcnt(0)
	s_waitcnt vmcnt(8)
	s_barrier
	s_setprio 1
	v_mfma_f32_16x16x32_bf16 v[60:63], v[162:165], v[182:185], v[60:63]
	v_mfma_f32_16x16x32_bf16 v[56:59], v[170:173], v[182:185], v[56:59]
	v_mfma_f32_16x16x32_bf16 v[52:55], v[162:165], v[190:193], v[52:55]
	v_mfma_f32_16x16x32_bf16 v[48:51], v[170:173], v[190:193], v[48:51]
	v_mfma_f32_16x16x32_bf16 v[44:47], v[162:165], v[198:201], v[44:47]
	v_mfma_f32_16x16x32_bf16 v[40:43], v[170:173], v[198:201], v[40:43]
	v_mfma_f32_16x16x32_bf16 v[36:39], v[162:165], v[206:209], v[36:39]
	v_mfma_f32_16x16x32_bf16 v[32:35], v[170:173], v[206:209], v[32:35]
	v_mfma_f32_16x16x32_bf16 v[60:63], v[166:169], v[186:189], v[60:63]
	v_mfma_f32_16x16x32_bf16 v[56:59], v[174:177], v[186:189], v[56:59]
	v_mfma_f32_16x16x32_bf16 v[52:55], v[166:169], v[194:197], v[52:55]
	v_mfma_f32_16x16x32_bf16 v[48:51], v[174:177], v[194:197], v[48:51]
	v_mfma_f32_16x16x32_bf16 v[44:47], v[166:169], v[202:205], v[44:47]
	v_mfma_f32_16x16x32_bf16 v[40:43], v[174:177], v[202:205], v[40:43]
	v_mfma_f32_16x16x32_bf16 v[36:39], v[166:169], v[210:213], v[36:39]
	v_mfma_f32_16x16x32_bf16 v[32:35], v[174:177], v[210:213], v[32:35]
	v_mfma_f32_16x16x32_bf16 v[28:31], v[214:217], v[182:185], v[28:31]
	v_mfma_f32_16x16x32_bf16 v[24:27], v[230:233], v[182:185], v[24:27]
	v_mfma_f32_16x16x32_bf16 v[20:23], v[214:217], v[190:193], v[20:23]
	v_mfma_f32_16x16x32_bf16 v[16:19], v[230:233], v[190:193], v[16:19]
	v_mfma_f32_16x16x32_bf16 v[12:15], v[214:217], v[198:201], v[12:15]
	v_mfma_f32_16x16x32_bf16 v[8:11], v[230:233], v[198:201], v[8:11]
	v_mfma_f32_16x16x32_bf16 v[4:7], v[214:217], v[206:209], v[4:7]
	v_mfma_f32_16x16x32_bf16 v[0:3], v[230:233], v[206:209], v[0:3]
	v_mfma_f32_16x16x32_bf16 v[28:31], v[218:221], v[186:189], v[28:31]
	v_mfma_f32_16x16x32_bf16 v[24:27], v[246:249], v[186:189], v[24:27]
	v_mfma_f32_16x16x32_bf16 v[20:23], v[218:221], v[194:197], v[20:23]
	v_mfma_f32_16x16x32_bf16 v[16:19], v[246:249], v[194:197], v[16:19]
	v_mfma_f32_16x16x32_bf16 v[12:15], v[218:221], v[202:205], v[12:15]
	v_mfma_f32_16x16x32_bf16 v[8:11], v[246:249], v[202:205], v[8:11]
	s_setprio 2
	s_barrier
	v_mfma_f32_16x16x32_bf16 v[4:7], v[218:221], v[210:213], v[4:7]
	v_mfma_f32_16x16x32_bf16 v[0:3], v[246:249], v[210:213], v[0:3]
	s_setprio 0
	s_add_u32 s10, s10, 0x100
	s_addc_u32 s11, s11, 0
	s_cmp_lt_u32 s22, 28
	s_cbranch_scc0 .Lmy_kexit_3

; #define STAGE_A(P, br, kt) do { const char* _base = (const char*)(((kt) < G.ksplit ? G.A1 : A2m) + (long)(br) * G.lda + (long)(kt) * BK); \
;     __builtin_amdgcn_global_load_lds((const unsigned*)(_base + aoff0), (unsigned*)((char*)(P) + sb0), 16, 0, 0); \
;     __builtin_amdgcn_global_load_lds((const unsigned*)(_base + aoff1), (unsigned*)((char*)(P) + sb1), 16, 0, 0); } while (0)
; #define LDA(dst, b, h) for (int m = 0; m < 4; ++m) for (int k = 0; k < 2; ++k) \
;     dst[m][k] = *reinterpret_cast<const bf16x8*>(a_rd + ((b) * 2 + (h)) * (HT * 2) + m * 2048 + k * 1024)
; #define LDB(dst, b, h) for (int n = 0; n < 2; ++n) for (int k = 0; k < 2; ++k) \
;     dst[n][k] = *reinterpret_cast<const bf16x8*>(b_rd + ((b) * 2 + (h)) * (HT * 2) + n * 2048 + k * 1024)
; #define MMA(ai, bj, At_, Bt_) do { __builtin_amdgcn_s_setprio(1); \
;     for (int m = 0; m < 4; ++m) for (int n = 0; n < 2; ++n) for (int k = 0; k < 2; ++k) \
;       acc[ai][bj][m][n] = __builtin_amdgcn_mfma_f32_16x16x32_bf16(Bt_[n][k], At_[m][k], acc[ai][bj][m][n], 0, 0, 0); \
;     __builtin_amdgcn_s_setprio(0); } while (0)
; #define WAIT_V(n) asm volatile("s_waitcnt vmcnt(" #n ")" ::: "memory")
; #define WAIT_L(n) asm volatile("s_waitcnt lgkmcnt(" #n ")" ::: "memory")
; #define BAR __builtin_amdgcn_s_barrier()
;     ...
;   { LDB(B0, 0, 0); LDA(At, 0, 0); STAGE_A(SA(1, 1), brow + HALF, nt - 1);
;     BAR; WAIT_L(0); MMA(0, 0, At, B0); BAR;
;     LDB(B1, 0, 1); BAR; WAIT_L(0); MMA(0, 1, At, B1); BAR;
;     LDA(At, 0, 1); WAIT_V(4); BAR; WAIT_L(0); MMA(1, 0, At, B0); MMA(1, 1, At, B1); BAR; }
;   { LDB(B0, 1, 0); LDA(At, 1, 0); WAIT_V(2); BAR; WAIT_L(0); MMA(0, 0, At, B0); BAR;
.Lmy_kexit_3:
	s_waitcnt vmcnt(6)
	v_not_b32_e32 v250, 63
	v_mov_b32_e32 v251, 0x41b17218
	s_lshl_b64 s[8:9], s[8:9], 1
	s_add_u32 s8, s31, s8
	s_addc_u32 s9, s34, s9
	v_lshl_add_u64 v[130:131], s[8:9], 0, v[130:131]
	v_readfirstlane_b32 s10, v159
	v_lshl_add_u64 v[130:131], v[130:131], 0, s[52:53]
	s_mov_b32 m0, s10
	v_lshl_add_u64 v[128:129], s[8:9], 0, v[128:129]
	v_readfirstlane_b32 s8, v160
	ds_read_b128 v[132:135], v149
	ds_read_b128 v[136:139], v149 offset:1024
	ds_read_b128 v[140:143], v149 offset:2048
	ds_read_b128 v[150:153], v149 offset:3072
	ds_read_b128 v[154:157], v146
	ds_read_b128 v[162:165], v146 offset:1024
	ds_read_b128 v[166:169], v146 offset:2048
	ds_read_b128 v[170:173], v146 offset:3072
	ds_read_b128 v[174:177], v146 offset:4096
	ds_read_b128 v[182:185], v146 offset:5120
	ds_read_b128 v[186:189], v146 offset:6144
	ds_read_b128 v[190:193], v146 offset:7168
	global_load_lds_dwordx4 v[130:131], off
	v_lshl_add_u64 v[128:129], v[128:129], 0, s[52:53]
	s_mov_b32 m0, s8
	s_nop 0
	global_load_lds_dwordx4 v[128:129], off
	s_barrier
	s_waitcnt lgkmcnt(0)
	s_setprio 1
	s_waitcnt lgkmcnt(0)
	v_mfma_f32_16x16x32_bf16 v[124:127], v[132:135], v[154:157], v[124:127]
	v_mfma_f32_16x16x32_bf16 v[120:123], v[140:143], v[154:157], v[120:123]
	v_mfma_f32_16x16x32_bf16 v[116:119], v[132:135], v[166:169], v[116:119]
	v_mfma_f32_16x16x32_bf16 v[112:115], v[140:143], v[166:169], v[112:115]
	v_mfma_f32_16x16x32_bf16 v[108:111], v[132:135], v[174:177], v[108:111]
	v_mfma_f32_16x16x32_bf16 v[104:107], v[140:143], v[174:177], v[104:107]
	v_mfma_f32_16x16x32_bf16 v[100:103], v[132:135], v[186:189], v[100:103]
	v_mfma_f32_16x16x32_bf16 v[96:99], v[140:143], v[186:189], v[96:99]
	v_mfma_f32_16x16x32_bf16 v[124:127], v[136:139], v[162:165], v[124:127]
	v_mfma_f32_16x16x32_bf16 v[120:123], v[150:153], v[162:165], v[120:123]
	v_mfma_f32_16x16x32_bf16 v[116:119], v[136:139], v[170:173], v[116:119]
	v_mfma_f32_16x16x32_bf16 v[112:115], v[150:153], v[170:173], v[112:115]
	v_mfma_f32_16x16x32_bf16 v[108:111], v[136:139], v[182:185], v[108:111]
	v_mfma_f32_16x16x32_bf16 v[104:107], v[150:153], v[182:185], v[104:107]
	s_setprio 2
	s_barrier
	v_mfma_f32_16x16x32_bf16 v[100:103], v[136:139], v[190:193], v[100:103]
	v_mfma_f32_16x16x32_bf16 v[96:99], v[150:153], v[190:193], v[96:99]
	s_setprio 0
	ds_read_b128 v[128:131], v149 offset:16384
	ds_read_b128 v[158:161], v149 offset:17408
	ds_read_b128 v[194:197], v149 offset:18432
	ds_read_b128 v[198:201], v149 offset:19456
	s_barrier
	s_waitcnt lgkmcnt(0)
	s_setprio 1
	s_waitcnt lgkmcnt(0)
	v_mfma_f32_16x16x32_bf16 v[92:95], v[128:131], v[154:157], v[92:95]
	v_mfma_f32_16x16x32_bf16 v[88:91], v[194:197], v[154:157], v[88:91]
	v_mfma_f32_16x16x32_bf16 v[84:87], v[128:131], v[166:169], v[84:87]
	v_mfma_f32_16x16x32_bf16 v[80:83], v[194:197], v[166:169], v[80:83]
	v_mfma_f32_16x16x32_bf16 v[76:79], v[128:131], v[174:177], v[76:79]
	v_mfma_f32_16x16x32_bf16 v[72:75], v[194:197], v[174:177], v[72:75]
	v_mfma_f32_16x16x32_bf16 v[68:71], v[128:131], v[186:189], v[68:71]
	v_mfma_f32_16x16x32_bf16 v[64:67], v[194:197], v[186:189], v[64:67]
	v_mfma_f32_16x16x32_bf16 v[202:205], v[158:161], v[162:165], v[92:95]
	v_mfma_f32_16x16x32_bf16 v[154:157], v[198:201], v[162:165], v[88:91]
	v_mfma_f32_16x16x32_bf16 v[162:165], v[158:161], v[170:173], v[84:87]
	v_mfma_f32_16x16x32_bf16 v[166:169], v[198:201], v[170:173], v[80:83]
	v_mfma_f32_16x16x32_bf16 v[170:173], v[158:161], v[182:185], v[76:79]
	v_mfma_f32_16x16x32_bf16 v[174:177], v[198:201], v[182:185], v[72:75]
	s_setprio 2
	s_barrier
	v_mfma_f32_16x16x32_bf16 v[182:185], v[158:161], v[190:193], v[68:71]
	v_mfma_f32_16x16x32_bf16 v[186:189], v[198:201], v[190:193], v[64:67]
	s_setprio 0
	s_nop 0
	ds_read_b128 v[64:67], v146 offset:16384
	ds_read_b128 v[68:71], v146 offset:17408
	ds_read_b128 v[72:75], v146 offset:18432
	ds_read_b128 v[76:79], v146 offset:19456
	ds_read_b128 v[80:83], v146 offset:20480
	ds_read_b128 v[84:87], v146 offset:21504
	ds_read_b128 v[88:91], v146 offset:22528
	ds_read_b128 v[92:95], v146 offset:23552
	s_waitcnt vmcnt(4)
	s_barrier
	s_waitcnt lgkmcnt(0)
	s_setprio 1
	s_waitcnt lgkmcnt(0)
	v_mfma_f32_16x16x32_bf16 v[60:63], v[132:135], v[64:67], v[60:63]
	v_mfma_f32_16x16x32_bf16 v[56:59], v[140:143], v[64:67], v[56:59]
	v_mfma_f32_16x16x32_bf16 v[52:55], v[132:135], v[72:75], v[52:55]
	v_mfma_f32_16x16x32_bf16 v[48:51], v[140:143], v[72:75], v[48:51]
	v_mfma_f32_16x16x32_bf16 v[44:47], v[132:135], v[80:83], v[44:47]
	v_mfma_f32_16x16x32_bf16 v[40:43], v[140:143], v[80:83], v[40:43]
	v_mfma_f32_16x16x32_bf16 v[36:39], v[132:135], v[88:91], v[36:39]
	v_mfma_f32_16x16x32_bf16 v[32:35], v[140:143], v[88:91], v[32:35]
	v_mfma_f32_16x16x32_bf16 v[60:63], v[136:139], v[68:71], v[60:63]
	v_mfma_f32_16x16x32_bf16 v[56:59], v[150:153], v[68:71], v[56:59]
	v_mfma_f32_16x16x32_bf16 v[52:55], v[136:139], v[76:79], v[52:55]
	v_mfma_f32_16x16x32_bf16 v[48:51], v[150:153], v[76:79], v[48:51]
	v_mfma_f32_16x16x32_bf16 v[44:47], v[136:139], v[84:87], v[44:47]
	v_mfma_f32_16x16x32_bf16 v[40:43], v[150:153], v[84:87], v[40:43]
	v_mfma_f32_16x16x32_bf16 v[36:39], v[136:139], v[92:95], v[36:39]
	v_mfma_f32_16x16x32_bf16 v[32:35], v[150:153], v[92:95], v[32:35]
	s_setprio 0
	s_setprio 1
	v_mfma_f32_16x16x32_bf16 v[28:31], v[128:131], v[64:67], v[28:31]
	v_mfma_f32_16x16x32_bf16 v[24:27], v[194:197], v[64:67], v[24:27]
	v_mfma_f32_16x16x32_bf16 v[20:23], v[128:131], v[72:75], v[20:23]
	v_mfma_f32_16x16x32_bf16 v[16:19], v[194:197], v[72:75], v[16:19]
	v_mfma_f32_16x16x32_bf16 v[12:15], v[128:131], v[80:83], v[12:15]
	v_mfma_f32_16x16x32_bf16 v[8:11], v[194:197], v[80:83], v[8:11]
	v_mfma_f32_16x16x32_bf16 v[4:7], v[128:131], v[88:91], v[4:7]
	v_mfma_f32_16x16x32_bf16 v[0:3], v[194:197], v[88:91], v[0:3]
	v_mfma_f32_16x16x32_bf16 v[132:135], v[158:161], v[68:71], v[28:31]
	v_mfma_f32_16x16x32_bf16 v[136:139], v[198:201], v[68:71], v[24:27]
	v_mfma_f32_16x16x32_bf16 v[140:143], v[158:161], v[76:79], v[20:23]
	v_mfma_f32_16x16x32_bf16 v[150:153], v[198:201], v[76:79], v[16:19]
	v_mfma_f32_16x16x32_bf16 v[190:193], v[158:161], v[84:87], v[12:15]
	v_mfma_f32_16x16x32_bf16 v[206:209], v[198:201], v[84:87], v[8:11]
	s_setprio 2
	s_barrier
; #define LDA(dst, b, h) for (int m = 0; m < 4; ++m) for (int k = 0; k < 2; ++k) \
;     dst[m][k] = *reinterpret_cast<const bf16x8*>(a_rd + ((b) * 2 + (h)) * (HT * 2) + m * 2048 + k * 1024)
; #define LDB(dst, b, h) for (int n = 0; n < 2; ++n) for (int k = 0; k < 2; ++k) \
;     dst[n][k] = *reinterpret_cast<const bf16x8*>(b_rd + ((b) * 2 + (h)) * (HT * 2) + n * 2048 + k * 1024)
; #define MMA(ai, bj, At_, Bt_) do { __builtin_amdgcn_s_setprio(1); \
;     for (int m = 0; m < 4; ++m) for (int n = 0; n < 2; ++n) for (int k = 0; k < 2; ++k) \
;       acc[ai][bj][m][n] = __builtin_amdgcn_mfma_f32_16x16x32_bf16(Bt_[n][k], At_[m][k], acc[ai][bj][m][n], 0, 0, 0); \
;     __builtin_amdgcn_s_setprio(0); } while (0)
; #define WAIT_V(n) asm volatile("s_waitcnt vmcnt(" #n ")" ::: "memory")
; #define WAIT_L(n) asm volatile("s_waitcnt lgkmcnt(" #n ")" ::: "memory")
; #define BAR __builtin_amdgcn_s_barrier()
;     ...
;   { LDB(B0, 1, 0); LDA(At, 1, 0); WAIT_V(2); BAR; WAIT_L(0); MMA(0, 0, At, B0); BAR;
;     LDB(B1, 1, 1); WAIT_V(0); BAR; WAIT_L(0); MMA(0, 1, At, B1); BAR;
;     LDA(At, 1, 1); BAR; WAIT_L(0); MMA(1, 0, At, B0); MMA(1, 1, At, B1); BAR; }
;   if (wr == 0) BAR;
	v_mfma_f32_16x16x32_bf16 v[128:131], v[158:161], v[92:95], v[4:7]
	v_mfma_f32_16x16x32_bf16 v[158:161], v[198:201], v[92:95], v[0:3]
	s_setprio 0
	ds_read_b128 v[24:27], v149 offset:32768
	ds_read_b128 v[28:31], v149 offset:33792
	ds_read_b128 v[194:197], v149 offset:34816
	ds_read_b128 v[198:201], v149 offset:35840
	ds_read_b128 v[0:3], v146 offset:32768
	ds_read_b128 v[4:7], v146 offset:33792
	ds_read_b128 v[8:11], v146 offset:34816
	ds_read_b128 v[12:15], v146 offset:35840
	ds_read_b128 v[16:19], v146 offset:36864
	ds_read_b128 v[20:23], v146 offset:37888
	ds_read_b128 v[210:213], v146 offset:38912
	ds_read_b128 v[214:217], v146 offset:39936
	s_waitcnt vmcnt(2)
	s_barrier
	s_waitcnt lgkmcnt(0)
	s_setprio 1
	s_waitcnt lgkmcnt(0)
	v_mfma_f32_16x16x32_bf16 v[64:67], v[24:27], v[0:3], v[124:127]
	v_mfma_f32_16x16x32_bf16 v[68:71], v[194:197], v[0:3], v[120:123]
	v_mfma_f32_16x16x32_bf16 v[72:75], v[24:27], v[8:11], v[116:119]
	v_mfma_f32_16x16x32_bf16 v[76:79], v[194:197], v[8:11], v[112:115]
	v_mfma_f32_16x16x32_bf16 v[80:83], v[24:27], v[16:19], v[108:111]
	v_mfma_f32_16x16x32_bf16 v[84:87], v[194:197], v[16:19], v[104:107]
	v_mfma_f32_16x16x32_bf16 v[88:91], v[24:27], v[210:213], v[100:103]
	v_mfma_f32_16x16x32_bf16 v[92:95], v[194:197], v[210:213], v[96:99]
	v_mfma_f32_16x16x32_bf16 v[64:67], v[28:31], v[4:7], v[64:67]
	v_mfma_f32_16x16x32_bf16 v[68:71], v[198:201], v[4:7], v[68:71]
	v_mfma_f32_16x16x32_bf16 v[72:75], v[28:31], v[12:15], v[72:75]
	v_mfma_f32_16x16x32_bf16 v[76:79], v[198:201], v[12:15], v[76:79]
	v_mfma_f32_16x16x32_bf16 v[80:83], v[28:31], v[20:23], v[80:83]
	v_mfma_f32_16x16x32_bf16 v[84:87], v[198:201], v[20:23], v[84:87]
	s_setprio 2
	s_barrier
	v_mfma_f32_16x16x32_bf16 v[88:91], v[28:31], v[214:217], v[88:91]
	v_mfma_f32_16x16x32_bf16 v[92:95], v[198:201], v[214:217], v[92:95]
	s_setprio 0
	ds_read_b128 v[218:221], v149 offset:49152
	ds_read_b128 v[230:233], v149 offset:50176
	ds_read_b128 v[246:249], v149 offset:51200
	ds_read_b128 v[238:241], v149 offset:52224
	s_waitcnt vmcnt(0)
	s_barrier
	s_waitcnt lgkmcnt(0)
	s_setprio 1
	s_waitcnt lgkmcnt(0)
	v_mfma_f32_16x16x32_bf16 v[96:99], v[218:221], v[0:3], v[202:205]
	v_mfma_f32_16x16x32_bf16 v[0:3], v[246:249], v[0:3], v[154:157]
	v_mfma_f32_16x16x32_bf16 v[100:103], v[238:241], v[4:7], v[0:3]
	v_mfma_f32_16x16x32_bf16 v[0:3], v[218:221], v[8:11], v[162:165]
	v_mfma_f32_16x16x32_bf16 v[104:107], v[230:233], v[12:15], v[0:3]
	v_mfma_f32_16x16x32_bf16 v[0:3], v[246:249], v[8:11], v[166:169]
	v_mfma_f32_16x16x32_bf16 v[108:111], v[238:241], v[12:15], v[0:3]
	v_mfma_f32_16x16x32_bf16 v[0:3], v[218:221], v[16:19], v[170:173]
	v_mfma_f32_16x16x32_bf16 v[112:115], v[230:233], v[20:23], v[0:3]
	v_mfma_f32_16x16x32_bf16 v[0:3], v[246:249], v[16:19], v[174:177]
	v_mfma_f32_16x16x32_bf16 v[116:119], v[238:241], v[20:23], v[0:3]
	v_mfma_f32_16x16x32_bf16 v[0:3], v[218:221], v[210:213], v[182:185]
	v_mfma_f32_16x16x32_bf16 v[120:123], v[230:233], v[214:217], v[0:3]
	v_mfma_f32_16x16x32_bf16 v[0:3], v[246:249], v[210:213], v[186:189]
	s_setprio 2
	s_barrier
	v_mfma_f32_16x16x32_bf16 v[96:99], v[230:233], v[4:7], v[96:99]
	v_mfma_f32_16x16x32_bf16 v[124:127], v[238:241], v[214:217], v[0:3]
	s_setprio 0
	ds_read_b128 v[154:157], v146 offset:49152
	ds_read_b128 v[162:165], v146 offset:50176
	ds_read_b128 v[166:169], v146 offset:51200
	ds_read_b128 v[170:173], v146 offset:52224
	ds_read_b128 v[174:177], v146 offset:53248
	ds_read_b128 v[182:185], v146 offset:54272
	ds_read_b128 v[186:189], v146 offset:55296
	ds_read_b128 v[146:149], v146 offset:56320
	s_barrier
	s_waitcnt lgkmcnt(0)
	s_setprio 1
	s_waitcnt lgkmcnt(0)
	v_mfma_f32_16x16x32_bf16 v[0:3], v[24:27], v[154:157], v[60:63]
	v_mfma_f32_16x16x32_bf16 v[8:11], v[24:27], v[166:169], v[52:55]
	v_mfma_f32_16x16x32_bf16 v[16:19], v[24:27], v[174:177], v[44:47]
	v_mfma_f32_16x16x32_bf16 v[24:27], v[24:27], v[186:189], v[36:39]
	v_mfma_f32_16x16x32_bf16 v[0:3], v[28:31], v[162:165], v[0:3]
	v_mfma_f32_16x16x32_bf16 v[4:7], v[194:197], v[154:157], v[56:59]
	v_mfma_f32_16x16x32_bf16 v[8:11], v[28:31], v[170:173], v[8:11]
	v_mfma_f32_16x16x32_bf16 v[12:15], v[194:197], v[166:169], v[48:51]
	v_mfma_f32_16x16x32_bf16 v[16:19], v[28:31], v[182:185], v[16:19]
	v_mfma_f32_16x16x32_bf16 v[20:23], v[194:197], v[174:177], v[40:43]
	v_mfma_f32_16x16x32_bf16 v[24:27], v[28:31], v[146:149], v[24:27]
	v_mfma_f32_16x16x32_bf16 v[28:31], v[194:197], v[186:189], v[32:35]
	v_mfma_f32_16x16x32_bf16 v[4:7], v[198:201], v[162:165], v[4:7]
	v_mfma_f32_16x16x32_bf16 v[12:15], v[198:201], v[170:173], v[12:15]
	v_mfma_f32_16x16x32_bf16 v[20:23], v[198:201], v[182:185], v[20:23]
	v_mfma_f32_16x16x32_bf16 v[28:31], v[198:201], v[146:149], v[28:31]
	s_setprio 0
	s_setprio 1
	v_mfma_f32_16x16x32_bf16 v[32:35], v[218:221], v[154:157], v[132:135]
	v_mfma_f32_16x16x32_bf16 v[36:39], v[246:249], v[154:157], v[136:139]
	v_mfma_f32_16x16x32_bf16 v[40:43], v[218:221], v[166:169], v[140:143]
	v_mfma_f32_16x16x32_bf16 v[44:47], v[246:249], v[166:169], v[150:153]
	v_mfma_f32_16x16x32_bf16 v[48:51], v[218:221], v[174:177], v[190:193]
	v_mfma_f32_16x16x32_bf16 v[52:55], v[246:249], v[174:177], v[206:209]
	v_mfma_f32_16x16x32_bf16 v[56:59], v[218:221], v[186:189], v[128:131]
	v_mfma_f32_16x16x32_bf16 v[60:63], v[246:249], v[186:189], v[158:161]
	v_mfma_f32_16x16x32_bf16 v[32:35], v[230:233], v[162:165], v[32:35]
	v_mfma_f32_16x16x32_bf16 v[36:39], v[238:241], v[162:165], v[36:39]
	v_mfma_f32_16x16x32_bf16 v[40:43], v[230:233], v[170:173], v[40:43]
	v_mfma_f32_16x16x32_bf16 v[44:47], v[238:241], v[170:173], v[44:47]
	v_mfma_f32_16x16x32_bf16 v[48:51], v[230:233], v[182:185], v[48:51]
	v_mfma_f32_16x16x32_bf16 v[52:55], v[238:241], v[182:185], v[52:55]
	s_setprio 2
	s_barrier
	v_mfma_f32_16x16x32_bf16 v[56:59], v[230:233], v[146:149], v[56:59]
	v_mfma_f32_16x16x32_bf16 v[60:63], v[238:241], v[146:149], v[60:63]
	s_setprio 0
	v_cmp_gt_u32_e32 vcc, s60, v144
	s_and_saveexec_b64 s[8:9], vcc
	s_cbranch_execz .LBB0_2504
	s_barrier

; #define STAGE_A(P, br, kt) do { const char* _base = (const char*)(((kt) < G.ksplit ? G.A1 : A2m) + (long)(br) * G.lda + (long)(kt) * BK); \
;     __builtin_amdgcn_global_load_lds((const unsigned*)(_base + aoff0), (unsigned*)((char*)(P) + sb0), 16, 0, 0); \
;     __builtin_amdgcn_global_load_lds((const unsigned*)(_base + aoff1), (unsigned*)((char*)(P) + sb1), 16, 0, 0); } while (0)
; #define STAGE_B(P, br, kt) do { const char* _base = (const char*)(G.Bt + (long)(br) * G.ldb + (long)(kt) * BK); \
;     __builtin_amdgcn_global_load_lds((const unsigned*)(_base + boff0), (unsigned*)((char*)(P) + sb0), 16, 0, 0); \
;     __builtin_amdgcn_global_load_lds((const unsigned*)(_base + boff1), (unsigned*)((char*)(P) + sb1), 16, 0, 0); } while (0)
;     ...
;   const int K = G.K;
;   const u16* A2m = G.A2 - (long)G.ksplit * BK;
;   int t1 = otid();
;   const int wid = t1 >> 6, lane = t1 & 63, wr = wid >> 2, wc = wid & 3, fr = lane & 15, fq = lane >> 4;
;   const int sb0 = t1 * 16, sb1 = sb0 + 8192;
;   const int swz_ = lds_byte(fr, fq * 8);
;   const char* a_rd = shmc + wr * 8192 + swz_;
;   const char* b_rd = shmc + 4 * (HT * 2) + wc * 4096 + swz_;
;   int r0_, c0_, r1_, c1_; stage_rc(sb0, r0_, c0_); stage_rc(sb1, r1_, c1_);
;   const unsigned aoff0 = (unsigned)(r0_ * G.lda + c0_) * 2u, aoff1 = (unsigned)(r1_ * G.lda + c1_) * 2u;
;   const unsigned boff0 = (unsigned)(r0_ * G.ldb + c0_) * 2u, boff1 = (unsigned)(r1_ * G.ldb + c1_) * 2u;
;   f32x4 acc[2][2][4][2] = {};
;   bf16x8 At[4][2], B0[2][2], B1[2][2];
;   const int nt = K / BK;
;   if (EPI == EPI_RESID || first) {
;     STAGE_B(SB(0, 0), bcol, 0); STAGE_A(SA(0, 0), brow, 0);
;     STAGE_B(SB(0, 1), bcol + HALF, 0); STAGE_A(SA(0, 1), brow + HALF, 0);
;   }
;   if (wr == 1) BAR;
;   WAIT_V(0); BAR;
;   STAGE_B(SB(1, 0), bcol, 1); STAGE_A(SA(1, 0), brow, 1); STAGE_B(SB(1, 1), bcol + HALF, 1);
;   WAIT_V(6); BAR;
;   for (int t = 0; t < nt - 2; t += 2) {
;     LDB(B0, 0, 0); SCHED; LDA(At, 0, 0); STAGE_A(SA(1, 1), brow + HALF, t + 1);
;     WAIT_L(8); BAR; WAIT_L(0); MMA(0, 0, At, B0); BAR; SCHED;
;     LDB(B1, 0, 1); STAGE_B(SB(0, 0), bcol, t + 2);
;     BAR; WAIT_L(0); MMA(0, 1, At, B1); BAR;
;     LDA(At, 0, 1); STAGE_A(SA(0, 0), brow, t + 2);
;     BAR; WAIT_L(0); MMA(1, 0, At, B0); BAR; SCHED;
;     STAGE_B(SB(0, 1), bcol + HALF, t + 2);
;     WAIT_V(6); BAR; MMA(1, 1, At, B1); BAR;
.LBB0_2565:
	s_or_b64 exec, exec, s[20:21]
	v_and_b32_e32 v152, 15, v144
	v_lshlrev_b32_e32 v10, 2, v144
	s_ashr_i32 s19, s18, 31
	v_and_b32_e32 v8, 48, v144
	v_lshlrev_b32_e32 v9, 6, v152
	v_and_b32_e32 v10, 32, v10
	s_add_i32 s21, 32, 0x10000
	s_lshl_b32 s29, s29, 8
	s_lshl_b64 s[36:37], s[18:19], 1
	v_bitop3_b32 v10, v9, v10, v8 bitop3:0x36
	v_lshlrev_b32_e32 v8, 6, v144
	s_add_u32 s38, s8, s36
	v_readlane_b32 s19, v253, 46
	v_and_b32_e32 v8, 0x3000, v8
	s_addc_u32 s39, s9, s37
	v_add_u32_e32 v153, s19, v148
	s_waitcnt vmcnt(16)
	v_add_u32_e32 v12, s21, v8
	v_lshl_add_u64 v[8:9], s[38:39], 0, v[180:181]
	s_mov_b64 s[44:45], 0x80
	v_readfirstlane_b32 s19, v153
	v_lshl_add_u64 v[8:9], v[8:9], 0, s[44:45]
	s_mov_b32 m0, s19
	v_mov_b32_e32 v129, v181
	v_add_u32_e32 v154, 0x2000, v153
	s_waitcnt vmcnt(16)
	s_barrier
	global_load_lds_dwordx4 v[8:9], off
	v_lshl_add_u64 v[8:9], s[38:39], 0, v[128:129]
	v_readfirstlane_b32 s19, v154
	s_add_u32 s34, s23, s34
	v_lshl_add_u64 v[8:9], v[8:9], 0, s[44:45]
	s_mov_b32 m0, s19
	s_addc_u32 s35, s24, s31
	v_add_u32_e32 v155, 0x8000, v147
	global_load_lds_dwordx4 v[8:9], off
	v_lshl_add_u64 v[8:9], s[34:35], 0, v[180:181]
	v_readfirstlane_b32 s19, v155
	v_lshl_add_u64 v[8:9], v[8:9], 0, s[44:45]
	s_mov_b32 m0, s19
	s_or_b32 s20, s29, 0x80
	global_load_lds_dwordx4 v[8:9], off
	v_lshl_add_u64 v[8:9], s[34:35], 0, v[128:129]
	s_mul_i32 s34, s20, 0x840
	v_add_u32_e32 v156, 0xa000, v147
	s_ashr_i32 s35, s34, 31
	v_readfirstlane_b32 s19, v156
	s_lshl_b64 s[34:35], s[34:35], 1
	s_mov_b32 m0, s19
	s_add_u32 s34, s8, s34
	v_readlane_b32 s19, v253, 47
	v_lshl_add_u64 v[8:9], v[8:9], 0, s[44:45]
	s_addc_u32 s35, s9, s35
	v_add_u32_e32 v157, s19, v148
	global_load_lds_dwordx4 v[8:9], off
	v_lshl_add_u64 v[8:9], s[34:35], 0, v[180:181]
	v_readfirstlane_b32 s19, v157
	v_lshl_add_u64 v[8:9], v[8:9], 0, s[44:45]
	s_mov_b32 m0, s19
	v_add_u32_e32 v158, 0x2000, v157
	global_load_lds_dwordx4 v[8:9], off
	v_lshl_add_u64 v[8:9], s[34:35], 0, v[128:129]
	v_readfirstlane_b32 s19, v158
	v_lshl_add_u64 v[8:9], v[8:9], 0, s[44:45]
	s_mov_b32 m0, s19
	s_add_i32 s18, s18, 0x40000
	global_load_lds_dwordx4 v[8:9], off
	v_lshrrev_b32_e32 v8, 1, v0
	v_mul_lo_u32 v0, v1, s41
	v_mad_u64_u32 v[0:1], s[34:35], v8, s84, v[0:1]
	v_or_b32_e32 v0, v0, v2
	v_add_lshl_u32 v0, v0, v3, 1
	v_lshrrev_b32_e32 v3, 1, v4
	v_mul_lo_u32 v2, v5, s41
	v_mad_u64_u32 v[2:3], s[34:35], v3, s84, v[2:3]
	s_ashr_i32 s19, s18, 31
	s_waitcnt vmcnt(6)
	v_mov_b32_e32 v1, v181
	v_or_b32_e32 v2, v2, v6
	s_lshl_b64 s[18:19], s[18:19], 1
	v_lshl_add_u32 v11, v151, 13, 32
	v_lshl_add_u64 v[130:131], s[36:37], 0, v[0:1]
	v_add_lshl_u32 v2, v2, v7, 1
	v_mov_b32_e32 v3, v181
	v_mad_i64_i32 v[134:135], s[34:35], s28, v243, v[0:1]
	v_lshl_add_u64 v[138:139], s[18:19], 0, v[0:1]
	v_mov_b32_e32 v245, 0x80003fff
	v_lshl_add_u64 v[132:133], s[36:37], 0, v[2:3]
	v_mad_i64_i32 v[136:137], s[34:35], s28, v243, v[2:3]
	v_lshl_add_u64 v[140:141], s[18:19], 0, v[2:3]
	s_mov_b32 s31, -2
	v_add_u32_e32 v150, v12, v10
	v_add_u32_e32 v149, v11, v10
	s_mov_b64 s[18:19], s[8:9]
	s_barrier
	ds_read_b128 v[164:167], v150
	ds_read_b128 v[168:171], v150 offset:1024
	ds_read_b128 v[172:175], v150 offset:2048
	ds_read_b128 v[176:179], v150 offset:3072
	v_add_u32_e32 v162, 0xc000, v147
	v_lshl_add_u64 v[222:223], s[18:19], 0, v[134:135]
	v_readfirstlane_b32 s34, v162
	v_add_u32_e32 v163, 0xe000, v147
	v_lshl_add_u64 v[160:161], v[222:223], 0, s[94:95]
	s_mov_b32 m0, s34
	v_lshl_add_u64 v[226:227], s[18:19], 0, v[136:137]
	v_readfirstlane_b32 s34, v163
	ds_read_b128 v[182:185], v149
	ds_read_b128 v[186:189], v149 offset:1024
	ds_read_b128 v[190:193], v149 offset:2048
	ds_read_b128 v[194:197], v149 offset:3072
	ds_read_b128 v[198:201], v149 offset:4096
	ds_read_b128 v[202:205], v149 offset:5120
	ds_read_b128 v[206:209], v149 offset:6144
	ds_read_b128 v[210:213], v149 offset:7168
	global_load_lds_dwordx4 v[160:161], off
	v_lshl_add_u64 v[160:161], v[226:227], 0, s[94:95]
	s_mov_b32 m0, s34
	s_nop 0
	global_load_lds_dwordx4 v[160:161], off
	ds_read_b128 v[214:217], v150 offset:16384
	ds_read_b128 v[218:221], v150 offset:17408
	ds_read_b128 v[230:233], v150 offset:18432
	ds_read_b128 v[238:241], v150 offset:19456
	s_waitcnt lgkmcnt(0)
	s_waitcnt vmcnt(8)
	s_barrier
	s_setprio 1
	v_mfma_f32_16x16x32_bf16 v[124:127], v[164:167], v[182:185], 0
	v_mfma_f32_16x16x32_bf16 v[120:123], v[172:175], v[182:185], 0
	v_mfma_f32_16x16x32_bf16 v[116:119], v[164:167], v[190:193], 0
	v_mfma_f32_16x16x32_bf16 v[112:115], v[172:175], v[190:193], 0
	v_mfma_f32_16x16x32_bf16 v[108:111], v[164:167], v[198:201], 0
	v_mfma_f32_16x16x32_bf16 v[104:107], v[172:175], v[198:201], 0
	v_mfma_f32_16x16x32_bf16 v[100:103], v[164:167], v[206:209], 0
	v_mfma_f32_16x16x32_bf16 v[96:99], v[172:175], v[206:209], 0
	v_mfma_f32_16x16x32_bf16 v[124:127], v[168:171], v[186:189], v[124:127]
	v_mfma_f32_16x16x32_bf16 v[120:123], v[176:179], v[186:189], v[120:123]
	v_mfma_f32_16x16x32_bf16 v[116:119], v[168:171], v[194:197], v[116:119]
	v_mfma_f32_16x16x32_bf16 v[112:115], v[176:179], v[194:197], v[112:115]
	v_mfma_f32_16x16x32_bf16 v[108:111], v[168:171], v[202:205], v[108:111]
	v_mfma_f32_16x16x32_bf16 v[104:107], v[176:179], v[202:205], v[104:107]
	v_mfma_f32_16x16x32_bf16 v[100:103], v[168:171], v[210:213], v[100:103]
	v_mfma_f32_16x16x32_bf16 v[96:99], v[176:179], v[210:213], v[96:99]
	v_mfma_f32_16x16x32_bf16 v[92:95], v[214:217], v[182:185], 0
	v_mfma_f32_16x16x32_bf16 v[88:91], v[230:233], v[182:185], 0
	v_mfma_f32_16x16x32_bf16 v[84:87], v[214:217], v[190:193], 0
	v_mfma_f32_16x16x32_bf16 v[80:83], v[230:233], v[190:193], 0
	v_mfma_f32_16x16x32_bf16 v[76:79], v[214:217], v[198:201], 0
	v_mfma_f32_16x16x32_bf16 v[72:75], v[230:233], v[198:201], 0
	v_mfma_f32_16x16x32_bf16 v[68:71], v[214:217], v[206:209], 0
	v_mfma_f32_16x16x32_bf16 v[64:67], v[230:233], v[206:209], 0
	v_mfma_f32_16x16x32_bf16 v[92:95], v[218:221], v[186:189], v[92:95]
	v_mfma_f32_16x16x32_bf16 v[88:91], v[238:241], v[186:189], v[88:91]
	v_mfma_f32_16x16x32_bf16 v[84:87], v[218:221], v[194:197], v[84:87]
	v_mfma_f32_16x16x32_bf16 v[80:83], v[238:241], v[194:197], v[80:83]
	v_mfma_f32_16x16x32_bf16 v[76:79], v[218:221], v[202:205], v[76:79]
	v_mfma_f32_16x16x32_bf16 v[72:75], v[238:241], v[202:205], v[72:75]
	s_setprio 2
	s_barrier
; #define STAGE_A(P, br, kt) do { const char* _base = (const char*)(((kt) < G.ksplit ? G.A1 : A2m) + (long)(br) * G.lda + (long)(kt) * BK); \
;     __builtin_amdgcn_global_load_lds((const unsigned*)(_base + aoff0), (unsigned*)((char*)(P) + sb0), 16, 0, 0); \
;     __builtin_amdgcn_global_load_lds((const unsigned*)(_base + aoff1), (unsigned*)((char*)(P) + sb1), 16, 0, 0); } while (0)
; #define STAGE_B(P, br, kt) do { const char* _base = (const char*)(G.Bt + (long)(br) * G.ldb + (long)(kt) * BK); \
;     __builtin_amdgcn_global_load_lds((const unsigned*)(_base + boff0), (unsigned*)((char*)(P) + sb0), 16, 0, 0); \
;     __builtin_amdgcn_global_load_lds((const unsigned*)(_base + boff1), (unsigned*)((char*)(P) + sb1), 16, 0, 0); } while (0)
; #define LDA(dst, b, h) for (int m = 0; m < 4; ++m) for (int k = 0; k < 2; ++k) \
;     dst[m][k] = *reinterpret_cast<const bf16x8*>(a_rd + ((b) * 2 + (h)) * (HT * 2) + m * 2048 + k * 1024)
; #define LDB(dst, b, h) for (int n = 0; n < 2; ++n) for (int k = 0; k < 2; ++k) \
;     dst[n][k] = *reinterpret_cast<const bf16x8*>(b_rd + ((b) * 2 + (h)) * (HT * 2) + n * 2048 + k * 1024)
; #define MMA(ai, bj, At_, Bt_) do { __builtin_amdgcn_s_setprio(1); \
;     for (int m = 0; m < 4; ++m) for (int n = 0; n < 2; ++n) for (int k = 0; k < 2; ++k) \
;       acc[ai][bj][m][n] = __builtin_amdgcn_mfma_f32_16x16x32_bf16(Bt_[n][k], At_[m][k], acc[ai][bj][m][n], 0, 0, 0); \
;     __builtin_amdgcn_s_setprio(0); } while (0)
; #define WAIT_V(n) asm volatile("s_waitcnt vmcnt(" #n ")" ::: "memory")
; #define WAIT_L(n) asm volatile("s_waitcnt lgkmcnt(" #n ")" ::: "memory")
;     ...
;   for (int t = 0; t < nt - 2; t += 2) {
;     LDB(B0, 0, 0); SCHED; LDA(At, 0, 0); STAGE_A(SA(1, 1), brow + HALF, t + 1);
;     WAIT_L(8); BAR; WAIT_L(0); MMA(0, 0, At, B0); BAR; SCHED;
;     LDB(B1, 0, 1); STAGE_B(SB(0, 0), bcol, t + 2);
;     BAR; WAIT_L(0); MMA(0, 1, At, B1); BAR;
;     LDA(At, 0, 1); STAGE_A(SA(0, 0), brow, t + 2);
;     BAR; WAIT_L(0); MMA(1, 0, At, B0); BAR; SCHED;
;     STAGE_B(SB(0, 1), bcol + HALF, t + 2);
;     WAIT_V(6); BAR; MMA(1, 1, At, B1); BAR;
;     LDB(B0, 1, 0); SCHED; LDA(At, 1, 0); STAGE_A(SA(0, 1), brow + HALF, t + 2);
;     WAIT_L(8); BAR; WAIT_L(0); MMA(0, 0, At, B0); BAR; SCHED;
;     LDB(B1, 1, 1); STAGE_B(SB(1, 0), bcol, t + 3);
;     BAR; WAIT_L(0); MMA(0, 1, At, B1); BAR;
;     LDA(At, 1, 1); STAGE_A(SA(1, 0), brow, t + 3);
	v_mfma_f32_16x16x32_bf16 v[68:71], v[218:221], v[210:213], v[68:71]
	v_mfma_f32_16x16x32_bf16 v[64:67], v[238:241], v[210:213], v[64:67]
	s_setprio 0
	v_add_u32_e32 v159, s21, v148
	v_lshl_add_u64 v[234:235], s[18:19], 0, v[130:131]
	v_readfirstlane_b32 s34, v159
	v_lshl_add_u64 v[160:161], v[234:235], 0, s[90:91]
	s_mov_b32 m0, s34
	global_load_lds_dwordx4 v[160:161], off
	v_add_u32_e32 v160, 0x2000, v159
	v_lshl_add_u64 v[236:237], s[18:19], 0, v[132:133]
	v_readfirstlane_b32 s34, v160
	v_lshl_add_u64 v[246:247], v[236:237], 0, s[90:91]
	s_mov_b32 m0, s34
	s_nop 0
	global_load_lds_dwordx4 v[246:247], off
	v_readfirstlane_b32 s34, v147
	v_lshl_add_u64 v[246:247], v[222:223], 0, s[4:5]
	s_mov_b32 m0, s34
	v_readfirstlane_b32 s34, v146
	ds_read_b128 v[182:185], v149 offset:16384
	ds_read_b128 v[186:189], v149 offset:17408
	ds_read_b128 v[190:193], v149 offset:18432
	ds_read_b128 v[194:197], v149 offset:19456
	ds_read_b128 v[198:201], v149 offset:20480
	ds_read_b128 v[202:205], v149 offset:21504
	ds_read_b128 v[206:209], v149 offset:22528
	ds_read_b128 v[210:213], v149 offset:23552
	global_load_lds_dwordx4 v[246:247], off
	v_lshl_add_u64 v[246:247], v[226:227], 0, s[4:5]
	s_mov_b32 m0, s34
	s_nop 0
	global_load_lds_dwordx4 v[246:247], off
	v_lshl_add_u64 v[246:247], s[18:19], 0, v[138:139]
	v_readfirstlane_b32 s34, v145
	v_add_u32_e32 v161, 0x2000, v145
	v_lshl_add_u64 v[250:251], v[246:247], 0, s[68:69]
	s_mov_b32 m0, s34
	v_lshl_add_u64 v[248:249], s[18:19], 0, v[140:141]
	v_readfirstlane_b32 s34, v161
	global_load_lds_dwordx4 v[250:251], off
	v_lshl_add_u64 v[250:251], v[248:249], 0, s[68:69]
	s_mov_b32 m0, s34
	s_nop 0
	global_load_lds_dwordx4 v[250:251], off
	s_waitcnt lgkmcnt(0)
	s_waitcnt vmcnt(8)
	s_barrier
	s_setprio 1
	v_mfma_f32_16x16x32_bf16 v[60:63], v[164:167], v[182:185], 0
	v_mfma_f32_16x16x32_bf16 v[56:59], v[172:175], v[182:185], 0
	v_mfma_f32_16x16x32_bf16 v[52:55], v[164:167], v[190:193], 0
	v_mfma_f32_16x16x32_bf16 v[48:51], v[172:175], v[190:193], 0
	v_mfma_f32_16x16x32_bf16 v[44:47], v[164:167], v[198:201], 0
	v_mfma_f32_16x16x32_bf16 v[40:43], v[172:175], v[198:201], 0
	v_mfma_f32_16x16x32_bf16 v[36:39], v[164:167], v[206:209], 0
	v_mfma_f32_16x16x32_bf16 v[32:35], v[172:175], v[206:209], 0
	v_mfma_f32_16x16x32_bf16 v[60:63], v[168:171], v[186:189], v[60:63]
	v_mfma_f32_16x16x32_bf16 v[56:59], v[176:179], v[186:189], v[56:59]
	v_mfma_f32_16x16x32_bf16 v[52:55], v[168:171], v[194:197], v[52:55]
	v_mfma_f32_16x16x32_bf16 v[48:51], v[176:179], v[194:197], v[48:51]
	v_mfma_f32_16x16x32_bf16 v[44:47], v[168:171], v[202:205], v[44:47]
	v_mfma_f32_16x16x32_bf16 v[40:43], v[176:179], v[202:205], v[40:43]
	v_mfma_f32_16x16x32_bf16 v[36:39], v[168:171], v[210:213], v[36:39]
	v_mfma_f32_16x16x32_bf16 v[32:35], v[176:179], v[210:213], v[32:35]
	v_mfma_f32_16x16x32_bf16 v[28:31], v[214:217], v[182:185], 0
	v_mfma_f32_16x16x32_bf16 v[24:27], v[230:233], v[182:185], 0
	v_mfma_f32_16x16x32_bf16 v[20:23], v[214:217], v[190:193], 0
	v_mfma_f32_16x16x32_bf16 v[16:19], v[230:233], v[190:193], 0
	v_mfma_f32_16x16x32_bf16 v[12:15], v[214:217], v[198:201], 0
	v_mfma_f32_16x16x32_bf16 v[8:11], v[230:233], v[198:201], 0
	v_mfma_f32_16x16x32_bf16 v[4:7], v[214:217], v[206:209], 0
	v_mfma_f32_16x16x32_bf16 v[0:3], v[230:233], v[206:209], 0
	v_mfma_f32_16x16x32_bf16 v[28:31], v[218:221], v[186:189], v[28:31]
	v_mfma_f32_16x16x32_bf16 v[24:27], v[238:241], v[186:189], v[24:27]
	v_mfma_f32_16x16x32_bf16 v[20:23], v[218:221], v[194:197], v[20:23]
	v_mfma_f32_16x16x32_bf16 v[16:19], v[238:241], v[194:197], v[16:19]
	v_mfma_f32_16x16x32_bf16 v[12:15], v[218:221], v[202:205], v[12:15]
	v_mfma_f32_16x16x32_bf16 v[8:11], v[238:241], v[202:205], v[8:11]
	s_setprio 2
	s_barrier
	v_mfma_f32_16x16x32_bf16 v[4:7], v[218:221], v[210:213], v[4:7]
	v_mfma_f32_16x16x32_bf16 v[0:3], v[238:241], v[210:213], v[0:3]
	s_setprio 0
	ds_read_b128 v[164:167], v150 offset:32768
	ds_read_b128 v[168:171], v150 offset:33792
	ds_read_b128 v[172:175], v150 offset:34816
	ds_read_b128 v[176:179], v150 offset:35840
	v_readfirstlane_b32 s34, v143
	v_lshl_add_u64 v[214:215], v[222:223], 0, s[96:97]
	s_mov_b32 m0, s34
	v_readfirstlane_b32 s34, v142
	ds_read_b128 v[182:185], v149 offset:32768
	ds_read_b128 v[186:189], v149 offset:33792
	ds_read_b128 v[190:193], v149 offset:34816
	ds_read_b128 v[194:197], v149 offset:35840
	ds_read_b128 v[198:201], v149 offset:36864
	ds_read_b128 v[202:205], v149 offset:37888
	ds_read_b128 v[206:209], v149 offset:38912
	ds_read_b128 v[210:213], v149 offset:39936
	global_load_lds_dwordx4 v[214:215], off
	v_lshl_add_u64 v[214:215], v[226:227], 0, s[96:97]
	s_mov_b32 m0, s34
	s_nop 0
	global_load_lds_dwordx4 v[214:215], off
	ds_read_b128 v[214:217], v150 offset:49152
	ds_read_b128 v[218:221], v150 offset:50176
	ds_read_b128 v[230:233], v150 offset:51200
	ds_read_b128 v[238:241], v150 offset:52224
	s_waitcnt lgkmcnt(0)
	s_waitcnt vmcnt(8)
	s_barrier
; #define STAGE_A(P, br, kt) do { const char* _base = (const char*)(((kt) < G.ksplit ? G.A1 : A2m) + (long)(br) * G.lda + (long)(kt) * BK); \
;     __builtin_amdgcn_global_load_lds((const unsigned*)(_base + aoff0), (unsigned*)((char*)(P) + sb0), 16, 0, 0); \
;     __builtin_amdgcn_global_load_lds((const unsigned*)(_base + aoff1), (unsigned*)((char*)(P) + sb1), 16, 0, 0); } while (0)
; #define STAGE_B(P, br, kt) do { const char* _base = (const char*)(G.Bt + (long)(br) * G.ldb + (long)(kt) * BK); \
;     __builtin_amdgcn_global_load_lds((const unsigned*)(_base + boff0), (unsigned*)((char*)(P) + sb0), 16, 0, 0); \
;     __builtin_amdgcn_global_load_lds((const unsigned*)(_base + boff1), (unsigned*)((char*)(P) + sb1), 16, 0, 0); } while (0)
; #define LDA(dst, b, h) for (int m = 0; m < 4; ++m) for (int k = 0; k < 2; ++k) \
;     dst[m][k] = *reinterpret_cast<const bf16x8*>(a_rd + ((b) * 2 + (h)) * (HT * 2) + m * 2048 + k * 1024)
; #define LDB(dst, b, h) for (int n = 0; n < 2; ++n) for (int k = 0; k < 2; ++k) \
;     dst[n][k] = *reinterpret_cast<const bf16x8*>(b_rd + ((b) * 2 + (h)) * (HT * 2) + n * 2048 + k * 1024)
; #define MMA(ai, bj, At_, Bt_) do { __builtin_amdgcn_s_setprio(1); \
;     for (int m = 0; m < 4; ++m) for (int n = 0; n < 2; ++n) for (int k = 0; k < 2; ++k) \
;       acc[ai][bj][m][n] = __builtin_amdgcn_mfma_f32_16x16x32_bf16(Bt_[n][k], At_[m][k], acc[ai][bj][m][n], 0, 0, 0); \
;     __builtin_amdgcn_s_setprio(0); } while (0)
; #define WAIT_V(n) asm volatile("s_waitcnt vmcnt(" #n ")" ::: "memory")
; #define WAIT_L(n) asm volatile("s_waitcnt lgkmcnt(" #n ")" ::: "memory")
; #define BAR __builtin_amdgcn_s_barrier()
; #define SCHED __builtin_amdgcn_sched_barrier(0)
;     ...
;     LDB(B0, 1, 0); SCHED; LDA(At, 1, 0); STAGE_A(SA(0, 1), brow + HALF, t + 2);
;     WAIT_L(8); BAR; WAIT_L(0); MMA(0, 0, At, B0); BAR; SCHED;
;     LDB(B1, 1, 1); STAGE_B(SB(1, 0), bcol, t + 3);
;     BAR; WAIT_L(0); MMA(0, 1, At, B1); BAR;
;     LDA(At, 1, 1); STAGE_A(SA(1, 0), brow, t + 3);
;     BAR; WAIT_L(0); MMA(1, 0, At, B0); BAR; SCHED;
;     STAGE_B(SB(1, 1), bcol + HALF, t + 3);
;     WAIT_V(6); BAR; MMA(1, 1, At, B1); BAR;
;   }
	s_setprio 1
	v_mfma_f32_16x16x32_bf16 v[124:127], v[164:167], v[182:185], v[124:127]
	v_mfma_f32_16x16x32_bf16 v[120:123], v[172:175], v[182:185], v[120:123]
	v_mfma_f32_16x16x32_bf16 v[116:119], v[164:167], v[190:193], v[116:119]
	v_mfma_f32_16x16x32_bf16 v[112:115], v[172:175], v[190:193], v[112:115]
	v_mfma_f32_16x16x32_bf16 v[108:111], v[164:167], v[198:201], v[108:111]
	v_mfma_f32_16x16x32_bf16 v[104:107], v[172:175], v[198:201], v[104:107]
	v_mfma_f32_16x16x32_bf16 v[100:103], v[164:167], v[206:209], v[100:103]
	v_mfma_f32_16x16x32_bf16 v[96:99], v[172:175], v[206:209], v[96:99]
	v_mfma_f32_16x16x32_bf16 v[124:127], v[168:171], v[186:189], v[124:127]
	v_mfma_f32_16x16x32_bf16 v[120:123], v[176:179], v[186:189], v[120:123]
	v_mfma_f32_16x16x32_bf16 v[116:119], v[168:171], v[194:197], v[116:119]
	v_mfma_f32_16x16x32_bf16 v[112:115], v[176:179], v[194:197], v[112:115]
	v_mfma_f32_16x16x32_bf16 v[108:111], v[168:171], v[202:205], v[108:111]
	v_mfma_f32_16x16x32_bf16 v[104:107], v[176:179], v[202:205], v[104:107]
	v_mfma_f32_16x16x32_bf16 v[100:103], v[168:171], v[210:213], v[100:103]
	v_mfma_f32_16x16x32_bf16 v[96:99], v[176:179], v[210:213], v[96:99]
	v_mfma_f32_16x16x32_bf16 v[92:95], v[214:217], v[182:185], v[92:95]
	v_mfma_f32_16x16x32_bf16 v[88:91], v[230:233], v[182:185], v[88:91]
	v_mfma_f32_16x16x32_bf16 v[84:87], v[214:217], v[190:193], v[84:87]
	v_mfma_f32_16x16x32_bf16 v[80:83], v[230:233], v[190:193], v[80:83]
	v_mfma_f32_16x16x32_bf16 v[76:79], v[214:217], v[198:201], v[76:79]
	v_mfma_f32_16x16x32_bf16 v[72:75], v[230:233], v[198:201], v[72:75]
	v_mfma_f32_16x16x32_bf16 v[68:71], v[214:217], v[206:209], v[68:71]
	v_mfma_f32_16x16x32_bf16 v[64:67], v[230:233], v[206:209], v[64:67]
	v_mfma_f32_16x16x32_bf16 v[92:95], v[218:221], v[186:189], v[92:95]
	v_mfma_f32_16x16x32_bf16 v[88:91], v[238:241], v[186:189], v[88:91]
	v_mfma_f32_16x16x32_bf16 v[84:87], v[218:221], v[194:197], v[84:87]
	v_mfma_f32_16x16x32_bf16 v[80:83], v[238:241], v[194:197], v[80:83]
	v_mfma_f32_16x16x32_bf16 v[76:79], v[218:221], v[202:205], v[76:79]
	v_mfma_f32_16x16x32_bf16 v[72:75], v[238:241], v[202:205], v[72:75]
	s_setprio 2
	s_barrier
	v_mfma_f32_16x16x32_bf16 v[68:71], v[218:221], v[210:213], v[68:71]
	v_mfma_f32_16x16x32_bf16 v[64:67], v[238:241], v[210:213], v[64:67]
	s_setprio 0
	v_readfirstlane_b32 s34, v153
	v_lshl_add_u64 v[234:235], v[234:235], 0, s[88:89]
	s_mov_b32 m0, s34
	v_readfirstlane_b32 s34, v154
	global_load_lds_dwordx4 v[234:235], off
	v_lshl_add_u64 v[234:235], v[236:237], 0, s[88:89]
	s_mov_b32 m0, s34
	s_nop 0
	global_load_lds_dwordx4 v[234:235], off
	v_readfirstlane_b32 s34, v155
	v_lshl_add_u64 v[222:223], v[222:223], 0, s[2:3]
	s_mov_b32 m0, s34
	v_readfirstlane_b32 s34, v156
	ds_read_b128 v[182:185], v149 offset:49152
	ds_read_b128 v[186:189], v149 offset:50176
	ds_read_b128 v[190:193], v149 offset:51200
	ds_read_b128 v[194:197], v149 offset:52224
	ds_read_b128 v[198:201], v149 offset:53248
	ds_read_b128 v[202:205], v149 offset:54272
	ds_read_b128 v[206:209], v149 offset:55296
	ds_read_b128 v[210:213], v149 offset:56320
	global_load_lds_dwordx4 v[222:223], off
	v_lshl_add_u64 v[222:223], v[226:227], 0, s[2:3]
	s_mov_b32 m0, s34
	s_nop 0
	global_load_lds_dwordx4 v[222:223], off
	v_readfirstlane_b32 s34, v157
	v_lshl_add_u64 v[250:251], v[246:247], 0, s[70:71]
	s_mov_b32 m0, s34
	v_readfirstlane_b32 s34, v158
	global_load_lds_dwordx4 v[250:251], off
	v_lshl_add_u64 v[250:251], v[248:249], 0, s[70:71]
	s_mov_b32 m0, s34
	s_nop 0
	global_load_lds_dwordx4 v[250:251], off
	s_waitcnt lgkmcnt(0)
	s_waitcnt vmcnt(8)
	s_barrier
	s_setprio 1
	v_mfma_f32_16x16x32_bf16 v[60:63], v[164:167], v[182:185], v[60:63]
	v_mfma_f32_16x16x32_bf16 v[56:59], v[172:175], v[182:185], v[56:59]
	v_mfma_f32_16x16x32_bf16 v[52:55], v[164:167], v[190:193], v[52:55]
	v_mfma_f32_16x16x32_bf16 v[48:51], v[172:175], v[190:193], v[48:51]
	v_mfma_f32_16x16x32_bf16 v[44:47], v[164:167], v[198:201], v[44:47]
	v_mfma_f32_16x16x32_bf16 v[40:43], v[172:175], v[198:201], v[40:43]
	v_mfma_f32_16x16x32_bf16 v[36:39], v[164:167], v[206:209], v[36:39]
	v_mfma_f32_16x16x32_bf16 v[32:35], v[172:175], v[206:209], v[32:35]
	v_mfma_f32_16x16x32_bf16 v[60:63], v[168:171], v[186:189], v[60:63]
	v_mfma_f32_16x16x32_bf16 v[56:59], v[176:179], v[186:189], v[56:59]
	v_mfma_f32_16x16x32_bf16 v[52:55], v[168:171], v[194:197], v[52:55]
	v_mfma_f32_16x16x32_bf16 v[48:51], v[176:179], v[194:197], v[48:51]
	v_mfma_f32_16x16x32_bf16 v[44:47], v[168:171], v[202:205], v[44:47]
	v_mfma_f32_16x16x32_bf16 v[40:43], v[176:179], v[202:205], v[40:43]
	v_mfma_f32_16x16x32_bf16 v[36:39], v[168:171], v[210:213], v[36:39]
	v_mfma_f32_16x16x32_bf16 v[32:35], v[176:179], v[210:213], v[32:35]
	v_mfma_f32_16x16x32_bf16 v[28:31], v[214:217], v[182:185], v[28:31]
	v_mfma_f32_16x16x32_bf16 v[24:27], v[230:233], v[182:185], v[24:27]
	v_mfma_f32_16x16x32_bf16 v[20:23], v[214:217], v[190:193], v[20:23]
	v_mfma_f32_16x16x32_bf16 v[16:19], v[230:233], v[190:193], v[16:19]
	v_mfma_f32_16x16x32_bf16 v[12:15], v[214:217], v[198:201], v[12:15]
	v_mfma_f32_16x16x32_bf16 v[8:11], v[230:233], v[198:201], v[8:11]
	v_mfma_f32_16x16x32_bf16 v[4:7], v[214:217], v[206:209], v[4:7]
	v_mfma_f32_16x16x32_bf16 v[0:3], v[230:233], v[206:209], v[0:3]
	v_mfma_f32_16x16x32_bf16 v[28:31], v[218:221], v[186:189], v[28:31]
	v_mfma_f32_16x16x32_bf16 v[24:27], v[238:241], v[186:189], v[24:27]
	v_mfma_f32_16x16x32_bf16 v[20:23], v[218:221], v[194:197], v[20:23]
	v_mfma_f32_16x16x32_bf16 v[16:19], v[238:241], v[194:197], v[16:19]
	v_mfma_f32_16x16x32_bf16 v[12:15], v[218:221], v[202:205], v[12:15]
	v_mfma_f32_16x16x32_bf16 v[8:11], v[238:241], v[202:205], v[8:11]
	s_setprio 2
	s_barrier
	v_mfma_f32_16x16x32_bf16 v[4:7], v[218:221], v[210:213], v[4:7]
	v_mfma_f32_16x16x32_bf16 v[0:3], v[238:241], v[210:213], v[0:3]
	s_setprio 0
	s_add_i32 s31, s31, 2
	s_add_u32 s18, s18, 0x100
	s_addc_u32 s19, s19, 0
	s_cmp_lt_u32 s31, 28
	s_cbranch_scc0 .Lmy_kexit_4

; #define STAGE_A(P, br, kt) do { const char* _base = (const char*)(((kt) < G.ksplit ? G.A1 : A2m) + (long)(br) * G.lda + (long)(kt) * BK); \
;     __builtin_amdgcn_global_load_lds((const unsigned*)(_base + aoff0), (unsigned*)((char*)(P) + sb0), 16, 0, 0); \
;     __builtin_amdgcn_global_load_lds((const unsigned*)(_base + aoff1), (unsigned*)((char*)(P) + sb1), 16, 0, 0); } while (0)
; #define LDA(dst, b, h) for (int m = 0; m < 4; ++m) for (int k = 0; k < 2; ++k) \
;     dst[m][k] = *reinterpret_cast<const bf16x8*>(a_rd + ((b) * 2 + (h)) * (HT * 2) + m * 2048 + k * 1024)
; #define LDB(dst, b, h) for (int n = 0; n < 2; ++n) for (int k = 0; k < 2; ++k) \
;     dst[n][k] = *reinterpret_cast<const bf16x8*>(b_rd + ((b) * 2 + (h)) * (HT * 2) + n * 2048 + k * 1024)
; #define MMA(ai, bj, At_, Bt_) do { __builtin_amdgcn_s_setprio(1); \
;     for (int m = 0; m < 4; ++m) for (int n = 0; n < 2; ++n) for (int k = 0; k < 2; ++k) \
;       acc[ai][bj][m][n] = __builtin_amdgcn_mfma_f32_16x16x32_bf16(Bt_[n][k], At_[m][k], acc[ai][bj][m][n], 0, 0, 0); \
;     __builtin_amdgcn_s_setprio(0); } while (0)
; #define WAIT_V(n) asm volatile("s_waitcnt vmcnt(" #n ")" ::: "memory")
; #define WAIT_L(n) asm volatile("s_waitcnt lgkmcnt(" #n ")" ::: "memory")
; #define BAR __builtin_amdgcn_s_barrier()
;     ...
;   float ssv[2][4] = {};
;   if constexpr (EPI == EPI_GU || EPI == EPI_EVIN || EPI == EPI_ODIN) {
; #pragma unroll
;     for (int ai = 0; ai < 2; ++ai)
; #pragma unroll
;       for (int m = 0; m < 4; ++m) ssv[ai][m] = G.ssr[brow + ai * HALF + wr * 64 + m * 16 + fr];
;   }
;   { LDB(B0, 0, 0); LDA(At, 0, 0); STAGE_A(SA(1, 1), brow + HALF, nt - 1);
;     BAR; WAIT_L(0); MMA(0, 0, At, B0); BAR;
;     LDB(B1, 0, 1); BAR; WAIT_L(0); MMA(0, 1, At, B1); BAR;
;     LDA(At, 0, 1); WAIT_V(4); BAR; WAIT_L(0); MMA(1, 0, At, B0); MMA(1, 1, At, B1); BAR; }
.Lmy_kexit_4:
	s_waitcnt vmcnt(6)
	v_not_b32_e32 v250, 63
	v_mov_b32_e32 v251, 0x41b17218
	v_or_b32_e32 v130, s28, v152
	v_lshl_add_u32 v130, v151, 6, v130
	v_add_u32_e32 v134, 0x80, v130
	v_ashrrev_i32_e32 v135, 31, v134
	v_lshl_add_u64 v[140:141], v[134:135], 2, s[12:13]
	v_add_u32_e32 v134, 0x90, v130
	v_ashrrev_i32_e32 v131, 31, v130
	v_ashrrev_i32_e32 v135, 31, v134
	v_lshl_add_u64 v[132:133], v[130:131], 2, s[12:13]
	v_lshl_add_u64 v[152:153], v[134:135], 2, s[12:13]
	v_add_u32_e32 v134, 0xa0, v130
	v_add_u32_e32 v130, 0xb0, v130
	s_or_b32 s21, s28, 0x80
	v_ashrrev_i32_e32 v135, 31, v134
	v_ashrrev_i32_e32 v131, 31, v130
	s_mul_i32 s18, s21, 0x1080
	v_lshl_add_u64 v[154:155], v[134:135], 2, s[12:13]
	v_lshl_add_u64 v[156:157], v[130:131], 2, s[12:13]
	global_load_dword v139, v[132:133], off
	global_load_dword v138, v[132:133], off offset:64
	global_load_dword v137, v[132:133], off offset:128
	global_load_dword v134, v[132:133], off offset:192
	s_nop 0
	global_load_dword v133, v[140:141], off
	global_load_dword v132, v[152:153], off
	global_load_dword v131, v[154:155], off
	global_load_dword v130, v[156:157], off
	s_mul_hi_i32 s19, s21, 0x1080
	s_add_u32 s18, s23, s18
	s_addc_u32 s19, s24, s19
	v_lshl_add_u64 v[140:141], s[18:19], 0, v[180:181]
	v_readfirstlane_b32 s31, v162
	v_lshl_add_u64 v[140:141], v[140:141], 0, s[46:47]
	s_mov_b32 m0, s31
	ds_read_b128 v[152:155], v150
	ds_read_b128 v[164:167], v150 offset:1024
	ds_read_b128 v[168:171], v150 offset:2048
	ds_read_b128 v[172:175], v150 offset:3072
	ds_read_b128 v[176:179], v149
	ds_read_b128 v[182:185], v149 offset:1024
	ds_read_b128 v[186:189], v149 offset:2048
	ds_read_b128 v[190:193], v149 offset:3072
	ds_read_b128 v[194:197], v149 offset:4096
	ds_read_b128 v[198:201], v149 offset:5120
	ds_read_b128 v[202:205], v149 offset:6144
	ds_read_b128 v[206:209], v149 offset:7168
	global_load_lds_dwordx4 v[140:141], off
	v_lshl_add_u64 v[140:141], s[18:19], 0, v[128:129]
	v_readfirstlane_b32 s18, v163
	v_lshl_add_u64 v[140:141], v[140:141], 0, s[46:47]
	s_mov_b32 m0, s18
	s_nop 0
	global_load_lds_dwordx4 v[140:141], off
	s_barrier
	s_waitcnt lgkmcnt(0)
	s_setprio 1
	s_waitcnt lgkmcnt(0)
	v_mfma_f32_16x16x32_bf16 v[124:127], v[152:155], v[176:179], v[124:127]
	v_mfma_f32_16x16x32_bf16 v[116:119], v[152:155], v[186:189], v[116:119]
	v_mfma_f32_16x16x32_bf16 v[108:111], v[152:155], v[194:197], v[108:111]
	v_mfma_f32_16x16x32_bf16 v[100:103], v[152:155], v[202:205], v[100:103]
	v_mfma_f32_16x16x32_bf16 v[124:127], v[164:167], v[182:185], v[124:127]
	v_mfma_f32_16x16x32_bf16 v[120:123], v[168:171], v[176:179], v[120:123]
	v_mfma_f32_16x16x32_bf16 v[116:119], v[164:167], v[190:193], v[116:119]
	v_mfma_f32_16x16x32_bf16 v[112:115], v[168:171], v[186:189], v[112:115]
	v_mfma_f32_16x16x32_bf16 v[108:111], v[164:167], v[198:201], v[108:111]
	v_mfma_f32_16x16x32_bf16 v[104:107], v[168:171], v[194:197], v[104:107]
	v_mfma_f32_16x16x32_bf16 v[100:103], v[164:167], v[206:209], v[100:103]
	v_mfma_f32_16x16x32_bf16 v[96:99], v[168:171], v[202:205], v[96:99]
	v_mfma_f32_16x16x32_bf16 v[210:213], v[172:175], v[182:185], v[120:123]
	v_mfma_f32_16x16x32_bf16 v[214:217], v[172:175], v[190:193], v[112:115]
	s_setprio 2
	s_barrier
	v_mfma_f32_16x16x32_bf16 v[218:221], v[172:175], v[198:201], v[104:107]
	v_mfma_f32_16x16x32_bf16 v[230:233], v[172:175], v[206:209], v[96:99]
	s_setprio 0
	s_nop 1
	ds_read_b128 v[96:99], v150 offset:16384
	ds_read_b128 v[104:107], v150 offset:17408
	ds_read_b128 v[112:115], v150 offset:18432
	ds_read_b128 v[120:123], v150 offset:19456
	s_barrier
	s_waitcnt lgkmcnt(0)
	s_setprio 1
	s_waitcnt lgkmcnt(0)
	v_mfma_f32_16x16x32_bf16 v[92:95], v[96:99], v[176:179], v[92:95]
	v_mfma_f32_16x16x32_bf16 v[84:87], v[96:99], v[186:189], v[84:87]
	v_mfma_f32_16x16x32_bf16 v[76:79], v[96:99], v[194:197], v[76:79]
	v_mfma_f32_16x16x32_bf16 v[68:71], v[96:99], v[202:205], v[68:71]
	v_mfma_f32_16x16x32_bf16 v[92:95], v[104:107], v[182:185], v[92:95]
	v_mfma_f32_16x16x32_bf16 v[88:91], v[112:115], v[176:179], v[88:91]
	v_mfma_f32_16x16x32_bf16 v[84:87], v[104:107], v[190:193], v[84:87]
	v_mfma_f32_16x16x32_bf16 v[80:83], v[112:115], v[186:189], v[80:83]
	v_mfma_f32_16x16x32_bf16 v[76:79], v[104:107], v[198:201], v[76:79]
	v_mfma_f32_16x16x32_bf16 v[72:75], v[112:115], v[194:197], v[72:75]
	v_mfma_f32_16x16x32_bf16 v[68:71], v[104:107], v[206:209], v[68:71]
	v_mfma_f32_16x16x32_bf16 v[64:67], v[112:115], v[202:205], v[64:67]
	v_mfma_f32_16x16x32_bf16 v[176:179], v[120:123], v[182:185], v[88:91]
	v_mfma_f32_16x16x32_bf16 v[182:185], v[120:123], v[190:193], v[80:83]
	s_setprio 2
	s_barrier
	v_mfma_f32_16x16x32_bf16 v[186:189], v[120:123], v[198:201], v[72:75]
	v_mfma_f32_16x16x32_bf16 v[190:193], v[120:123], v[206:209], v[64:67]
	s_setprio 0
	s_nop 1
	ds_read_b128 v[64:67], v149 offset:16384
	ds_read_b128 v[72:75], v149 offset:17408
	ds_read_b128 v[80:83], v149 offset:18432
	ds_read_b128 v[88:91], v149 offset:19456
	ds_read_b128 v[194:197], v149 offset:20480
	ds_read_b128 v[198:201], v149 offset:21504
	ds_read_b128 v[202:205], v149 offset:22528
	ds_read_b128 v[206:209], v149 offset:23552
	s_waitcnt vmcnt(4)
	s_barrier
; #define LDA(dst, b, h) for (int m = 0; m < 4; ++m) for (int k = 0; k < 2; ++k) \
;     dst[m][k] = *reinterpret_cast<const bf16x8*>(a_rd + ((b) * 2 + (h)) * (HT * 2) + m * 2048 + k * 1024)
; #define LDB(dst, b, h) for (int n = 0; n < 2; ++n) for (int k = 0; k < 2; ++k) \
;     dst[n][k] = *reinterpret_cast<const bf16x8*>(b_rd + ((b) * 2 + (h)) * (HT * 2) + n * 2048 + k * 1024)
; #define MMA(ai, bj, At_, Bt_) do { __builtin_amdgcn_s_setprio(1); \
;     for (int m = 0; m < 4; ++m) for (int n = 0; n < 2; ++n) for (int k = 0; k < 2; ++k) \
;       acc[ai][bj][m][n] = __builtin_amdgcn_mfma_f32_16x16x32_bf16(Bt_[n][k], At_[m][k], acc[ai][bj][m][n], 0, 0, 0); \
;     __builtin_amdgcn_s_setprio(0); } while (0)
; #define WAIT_V(n) asm volatile("s_waitcnt vmcnt(" #n ")" ::: "memory")
; #define WAIT_L(n) asm volatile("s_waitcnt lgkmcnt(" #n ")" ::: "memory")
; #define BAR __builtin_amdgcn_s_barrier()
;     ...
;     LDA(At, 0, 1); WAIT_V(4); BAR; WAIT_L(0); MMA(1, 0, At, B0); MMA(1, 1, At, B1); BAR; }
;   { LDB(B0, 1, 0); LDA(At, 1, 0); WAIT_V(2); BAR; WAIT_L(0); MMA(0, 0, At, B0); BAR;
;     LDB(B1, 1, 1); WAIT_V(0); BAR; WAIT_L(0); MMA(0, 1, At, B1); BAR;
;     LDA(At, 1, 1); BAR; WAIT_L(0); MMA(1, 0, At, B0); MMA(1, 1, At, B1); BAR; }
	s_waitcnt lgkmcnt(0)
	s_setprio 1
	s_waitcnt lgkmcnt(0)
	v_mfma_f32_16x16x32_bf16 v[60:63], v[152:155], v[64:67], v[60:63]
	v_mfma_f32_16x16x32_bf16 v[52:55], v[152:155], v[80:83], v[52:55]
	v_mfma_f32_16x16x32_bf16 v[44:47], v[152:155], v[194:197], v[44:47]
	v_mfma_f32_16x16x32_bf16 v[36:39], v[152:155], v[202:205], v[36:39]
	v_mfma_f32_16x16x32_bf16 v[60:63], v[164:167], v[72:75], v[60:63]
	v_mfma_f32_16x16x32_bf16 v[56:59], v[168:171], v[64:67], v[56:59]
	v_mfma_f32_16x16x32_bf16 v[52:55], v[164:167], v[88:91], v[52:55]
	v_mfma_f32_16x16x32_bf16 v[48:51], v[168:171], v[80:83], v[48:51]
	v_mfma_f32_16x16x32_bf16 v[44:47], v[164:167], v[198:201], v[44:47]
	v_mfma_f32_16x16x32_bf16 v[40:43], v[168:171], v[194:197], v[40:43]
	v_mfma_f32_16x16x32_bf16 v[36:39], v[164:167], v[206:209], v[36:39]
	v_mfma_f32_16x16x32_bf16 v[32:35], v[168:171], v[202:205], v[32:35]
	v_mfma_f32_16x16x32_bf16 v[238:241], v[172:175], v[72:75], v[56:59]
	v_mfma_f32_16x16x32_bf16 v[246:249], v[172:175], v[88:91], v[48:51]
	v_mfma_f32_16x16x32_bf16 v[234:237], v[172:175], v[198:201], v[40:43]
	v_mfma_f32_16x16x32_bf16 v[152:155], v[172:175], v[206:209], v[32:35]
	s_setprio 0
	s_setprio 1
	v_mfma_f32_16x16x32_bf16 v[28:31], v[96:99], v[64:67], v[28:31]
	v_mfma_f32_16x16x32_bf16 v[20:23], v[96:99], v[80:83], v[20:23]
	v_mfma_f32_16x16x32_bf16 v[12:15], v[96:99], v[194:197], v[12:15]
	v_mfma_f32_16x16x32_bf16 v[4:7], v[96:99], v[202:205], v[4:7]
	v_mfma_f32_16x16x32_bf16 v[28:31], v[104:107], v[72:75], v[28:31]
	v_mfma_f32_16x16x32_bf16 v[24:27], v[112:115], v[64:67], v[24:27]
	v_mfma_f32_16x16x32_bf16 v[20:23], v[104:107], v[88:91], v[20:23]
	v_mfma_f32_16x16x32_bf16 v[16:19], v[112:115], v[80:83], v[16:19]
	v_mfma_f32_16x16x32_bf16 v[12:15], v[104:107], v[198:201], v[12:15]
	v_mfma_f32_16x16x32_bf16 v[8:11], v[112:115], v[194:197], v[8:11]
	v_mfma_f32_16x16x32_bf16 v[4:7], v[104:107], v[206:209], v[4:7]
	v_mfma_f32_16x16x32_bf16 v[0:3], v[112:115], v[202:205], v[0:3]
	v_mfma_f32_16x16x32_bf16 v[162:165], v[120:123], v[72:75], v[24:27]
	v_mfma_f32_16x16x32_bf16 v[166:169], v[120:123], v[88:91], v[16:19]
	s_setprio 2
	s_barrier
	v_mfma_f32_16x16x32_bf16 v[170:173], v[120:123], v[198:201], v[8:11]
	v_mfma_f32_16x16x32_bf16 v[194:197], v[120:123], v[206:209], v[0:3]
	s_setprio 0
	s_nop 1
	ds_read_b128 v[0:3], v150 offset:32768
	ds_read_b128 v[8:11], v150 offset:33792
	ds_read_b128 v[16:19], v150 offset:34816
	ds_read_b128 v[24:27], v150 offset:35840
	ds_read_b128 v[32:35], v149 offset:32768
	ds_read_b128 v[40:43], v149 offset:33792
	ds_read_b128 v[48:51], v149 offset:34816
	ds_read_b128 v[56:59], v149 offset:35840
	ds_read_b128 v[64:67], v149 offset:36864
	ds_read_b128 v[198:201], v149 offset:37888
	ds_read_b128 v[202:205], v149 offset:38912
	ds_read_b128 v[206:209], v149 offset:39936
	s_waitcnt vmcnt(2)
	s_barrier
	s_waitcnt lgkmcnt(0)
	s_setprio 1
	s_waitcnt lgkmcnt(0)
	v_mfma_f32_16x16x32_bf16 v[72:75], v[0:3], v[32:35], v[124:127]
	v_mfma_f32_16x16x32_bf16 v[120:123], v[8:11], v[40:43], v[72:75]
	v_mfma_f32_16x16x32_bf16 v[72:75], v[16:19], v[32:35], v[210:213]
	v_mfma_f32_16x16x32_bf16 v[124:127], v[24:27], v[40:43], v[72:75]
	v_mfma_f32_16x16x32_bf16 v[72:75], v[0:3], v[48:51], v[116:119]
	v_mfma_f32_16x16x32_bf16 v[112:115], v[8:11], v[56:59], v[72:75]
	v_mfma_f32_16x16x32_bf16 v[72:75], v[16:19], v[48:51], v[214:217]
	v_mfma_f32_16x16x32_bf16 v[116:119], v[24:27], v[56:59], v[72:75]
	v_mfma_f32_16x16x32_bf16 v[72:75], v[0:3], v[64:67], v[108:111]
	v_mfma_f32_16x16x32_bf16 v[104:107], v[8:11], v[198:201], v[72:75]
	v_mfma_f32_16x16x32_bf16 v[72:75], v[16:19], v[64:67], v[218:221]
	v_mfma_f32_16x16x32_bf16 v[108:111], v[24:27], v[198:201], v[72:75]
	v_mfma_f32_16x16x32_bf16 v[72:75], v[0:3], v[202:205], v[100:103]
	v_mfma_f32_16x16x32_bf16 v[96:99], v[8:11], v[206:209], v[72:75]
	s_setprio 2
	s_barrier
	v_mfma_f32_16x16x32_bf16 v[72:75], v[16:19], v[202:205], v[230:233]
	v_mfma_f32_16x16x32_bf16 v[100:103], v[24:27], v[206:209], v[72:75]
	s_setprio 0
	ds_read_b128 v[210:213], v150 offset:49152
	ds_read_b128 v[214:217], v150 offset:50176
	ds_read_b128 v[218:221], v150 offset:51200
	ds_read_b128 v[230:233], v150 offset:52224
	s_waitcnt vmcnt(0)
	s_barrier
; #define LDA(dst, b, h) for (int m = 0; m < 4; ++m) for (int k = 0; k < 2; ++k) \
;     dst[m][k] = *reinterpret_cast<const bf16x8*>(a_rd + ((b) * 2 + (h)) * (HT * 2) + m * 2048 + k * 1024)
; #define LDB(dst, b, h) for (int n = 0; n < 2; ++n) for (int k = 0; k < 2; ++k) \
;     dst[n][k] = *reinterpret_cast<const bf16x8*>(b_rd + ((b) * 2 + (h)) * (HT * 2) + n * 2048 + k * 1024)
; #define MMA(ai, bj, At_, Bt_) do { __builtin_amdgcn_s_setprio(1); \
;     for (int m = 0; m < 4; ++m) for (int n = 0; n < 2; ++n) for (int k = 0; k < 2; ++k) \
;       acc[ai][bj][m][n] = __builtin_amdgcn_mfma_f32_16x16x32_bf16(Bt_[n][k], At_[m][k], acc[ai][bj][m][n], 0, 0, 0); \
;     __builtin_amdgcn_s_setprio(0); } while (0)
; #define WAIT_V(n) asm volatile("s_waitcnt vmcnt(" #n ")" ::: "memory")
; #define WAIT_L(n) asm volatile("s_waitcnt lgkmcnt(" #n ")" ::: "memory")
; #define BAR __builtin_amdgcn_s_barrier()
;     ...
;   { LDB(B0, 1, 0); LDA(At, 1, 0); WAIT_V(2); BAR; WAIT_L(0); MMA(0, 0, At, B0); BAR;
;     LDB(B1, 1, 1); WAIT_V(0); BAR; WAIT_L(0); MMA(0, 1, At, B1); BAR;
;     LDA(At, 1, 1); BAR; WAIT_L(0); MMA(1, 0, At, B0); MMA(1, 1, At, B1); BAR; }
;   if (wr == 0) BAR;
	s_waitcnt lgkmcnt(0)
	s_setprio 1
	s_waitcnt lgkmcnt(0)
	v_mfma_f32_16x16x32_bf16 v[72:75], v[210:213], v[32:35], v[92:95]
	v_mfma_f32_16x16x32_bf16 v[32:35], v[218:221], v[32:35], v[176:179]
	v_mfma_f32_16x16x32_bf16 v[92:95], v[230:233], v[40:43], v[32:35]
	v_mfma_f32_16x16x32_bf16 v[32:35], v[210:213], v[48:51], v[84:87]
	v_mfma_f32_16x16x32_bf16 v[80:83], v[214:217], v[56:59], v[32:35]
	v_mfma_f32_16x16x32_bf16 v[32:35], v[218:221], v[48:51], v[182:185]
	v_mfma_f32_16x16x32_bf16 v[84:87], v[230:233], v[56:59], v[32:35]
	v_mfma_f32_16x16x32_bf16 v[32:35], v[210:213], v[64:67], v[76:79]
	v_mfma_f32_16x16x32_bf16 v[88:91], v[214:217], v[40:43], v[72:75]
	v_mfma_f32_16x16x32_bf16 v[72:75], v[214:217], v[198:201], v[32:35]
	v_mfma_f32_16x16x32_bf16 v[32:35], v[218:221], v[64:67], v[186:189]
	v_mfma_f32_16x16x32_bf16 v[76:79], v[230:233], v[198:201], v[32:35]
	v_mfma_f32_16x16x32_bf16 v[32:35], v[210:213], v[202:205], v[68:71]
	v_mfma_f32_16x16x32_bf16 v[64:67], v[214:217], v[206:209], v[32:35]
	s_setprio 2
	s_barrier
	v_mfma_f32_16x16x32_bf16 v[32:35], v[218:221], v[202:205], v[190:193]
	v_mfma_f32_16x16x32_bf16 v[68:71], v[230:233], v[206:209], v[32:35]
	s_setprio 0
	ds_read_b128 v[174:177], v149 offset:49152
	ds_read_b128 v[182:185], v149 offset:50176
	ds_read_b128 v[186:189], v149 offset:51200
	ds_read_b128 v[190:193], v149 offset:52224
	ds_read_b128 v[198:201], v149 offset:53248
	ds_read_b128 v[202:205], v149 offset:54272
	ds_read_b128 v[206:209], v149 offset:55296
	ds_read_b128 v[148:151], v149 offset:56320
	s_barrier
	s_waitcnt lgkmcnt(0)
	s_setprio 1
	s_waitcnt lgkmcnt(0)
	v_mfma_f32_16x16x32_bf16 v[32:35], v[0:3], v[174:177], v[60:63]
	v_mfma_f32_16x16x32_bf16 v[56:59], v[8:11], v[182:185], v[32:35]
	v_mfma_f32_16x16x32_bf16 v[32:35], v[16:19], v[174:177], v[238:241]
	v_mfma_f32_16x16x32_bf16 v[60:63], v[24:27], v[182:185], v[32:35]
	v_mfma_f32_16x16x32_bf16 v[32:35], v[0:3], v[186:189], v[52:55]
	v_mfma_f32_16x16x32_bf16 v[48:51], v[8:11], v[190:193], v[32:35]
	v_mfma_f32_16x16x32_bf16 v[32:35], v[16:19], v[186:189], v[246:249]
	v_mfma_f32_16x16x32_bf16 v[52:55], v[24:27], v[190:193], v[32:35]
	v_mfma_f32_16x16x32_bf16 v[32:35], v[0:3], v[198:201], v[44:47]
	v_mfma_f32_16x16x32_bf16 v[40:43], v[8:11], v[202:205], v[32:35]
	v_mfma_f32_16x16x32_bf16 v[32:35], v[16:19], v[198:201], v[234:237]
	v_mfma_f32_16x16x32_bf16 v[0:3], v[0:3], v[206:209], v[36:39]
	v_mfma_f32_16x16x32_bf16 v[44:47], v[24:27], v[202:205], v[32:35]
	v_mfma_f32_16x16x32_bf16 v[32:35], v[8:11], v[148:151], v[0:3]
	v_mfma_f32_16x16x32_bf16 v[0:3], v[16:19], v[206:209], v[152:155]
	v_mfma_f32_16x16x32_bf16 v[36:39], v[24:27], v[148:151], v[0:3]
	s_setprio 0
	s_setprio 1
	v_mfma_f32_16x16x32_bf16 v[0:3], v[210:213], v[174:177], v[28:31]
	v_mfma_f32_16x16x32_bf16 v[24:27], v[214:217], v[182:185], v[0:3]
	v_mfma_f32_16x16x32_bf16 v[0:3], v[218:221], v[174:177], v[162:165]
	v_mfma_f32_16x16x32_bf16 v[28:31], v[230:233], v[182:185], v[0:3]
	v_mfma_f32_16x16x32_bf16 v[0:3], v[210:213], v[186:189], v[20:23]
	v_mfma_f32_16x16x32_bf16 v[16:19], v[214:217], v[190:193], v[0:3]
	v_mfma_f32_16x16x32_bf16 v[0:3], v[218:221], v[186:189], v[166:169]
	v_mfma_f32_16x16x32_bf16 v[20:23], v[230:233], v[190:193], v[0:3]
	v_mfma_f32_16x16x32_bf16 v[0:3], v[210:213], v[198:201], v[12:15]
	v_mfma_f32_16x16x32_bf16 v[8:11], v[214:217], v[202:205], v[0:3]
	v_mfma_f32_16x16x32_bf16 v[0:3], v[218:221], v[198:201], v[170:173]
	v_mfma_f32_16x16x32_bf16 v[12:15], v[230:233], v[202:205], v[0:3]
	v_mfma_f32_16x16x32_bf16 v[0:3], v[210:213], v[206:209], v[4:7]
	v_mfma_f32_16x16x32_bf16 v[4:7], v[218:221], v[206:209], v[194:197]
	s_setprio 2
	s_barrier
	v_mfma_f32_16x16x32_bf16 v[0:3], v[214:217], v[148:151], v[0:3]
	v_mfma_f32_16x16x32_bf16 v[4:7], v[230:233], v[148:151], v[4:7]
	s_setprio 0
	v_cmp_gt_u32_e32 vcc, s60, v144
	s_and_saveexec_b64 s[18:19], vcc
	s_cbranch_execz .LBB0_2569
	s_barrier

; #define STAGE_A(P, br, kt) do { const char* _base = (const char*)(((kt) < G.ksplit ? G.A1 : A2m) + (long)(br) * G.lda + (long)(kt) * BK); \
;     __builtin_amdgcn_global_load_lds((const unsigned*)(_base + aoff0), (unsigned*)((char*)(P) + sb0), 16, 0, 0); \
;     __builtin_amdgcn_global_load_lds((const unsigned*)(_base + aoff1), (unsigned*)((char*)(P) + sb1), 16, 0, 0); } while (0)
; #define STAGE_B(P, br, kt) do { const char* _base = (const char*)(G.Bt + (long)(br) * G.ldb + (long)(kt) * BK); \
;     __builtin_amdgcn_global_load_lds((const unsigned*)(_base + boff0), (unsigned*)((char*)(P) + sb0), 16, 0, 0); \
;     __builtin_amdgcn_global_load_lds((const unsigned*)(_base + boff1), (unsigned*)((char*)(P) + sb1), 16, 0, 0); } while (0)
;     ...
;   const int K = G.K;
;   const u16* A2m = G.A2 - (long)G.ksplit * BK;
;   int t1 = otid();
;   const int wid = t1 >> 6, lane = t1 & 63, wr = wid >> 2, wc = wid & 3, fr = lane & 15, fq = lane >> 4;
;   const int sb0 = t1 * 16, sb1 = sb0 + 8192;
;   const int swz_ = lds_byte(fr, fq * 8);
;   const char* a_rd = shmc + wr * 8192 + swz_;
;   const char* b_rd = shmc + 4 * (HT * 2) + wc * 4096 + swz_;
;   int r0_, c0_, r1_, c1_; stage_rc(sb0, r0_, c0_); stage_rc(sb1, r1_, c1_);
;   const unsigned aoff0 = (unsigned)(r0_ * G.lda + c0_) * 2u, aoff1 = (unsigned)(r1_ * G.lda + c1_) * 2u;
;   const unsigned boff0 = (unsigned)(r0_ * G.ldb + c0_) * 2u, boff1 = (unsigned)(r1_ * G.ldb + c1_) * 2u;
;   f32x4 acc[2][2][4][2] = {};
;   bf16x8 At[4][2], B0[2][2], B1[2][2];
;   const int nt = K / BK;
;   if (EPI == EPI_RESID || first) {
;     STAGE_B(SB(0, 0), bcol, 0); STAGE_A(SA(0, 0), brow, 0);
;     STAGE_B(SB(0, 1), bcol + HALF, 0); STAGE_A(SA(0, 1), brow + HALF, 0);
;   }
;   if (wr == 1) BAR;
;   WAIT_V(0); BAR;
;   STAGE_B(SB(1, 0), bcol, 1); STAGE_A(SA(1, 0), brow, 1); STAGE_B(SB(1, 1), bcol + HALF, 1);
;   WAIT_V(6); BAR;
;   for (int t = 0; t < nt - 2; t += 2) {
;     LDB(B0, 0, 0); SCHED; LDA(At, 0, 0); STAGE_A(SA(1, 1), brow + HALF, t + 1);
;     WAIT_L(8); BAR; WAIT_L(0); MMA(0, 0, At, B0); BAR; SCHED;
;     LDB(B1, 0, 1); STAGE_B(SB(0, 0), bcol, t + 2);
;     BAR; WAIT_L(0); MMA(0, 1, At, B1); BAR;
;     LDA(At, 0, 1); STAGE_A(SA(0, 0), brow, t + 2);
;     BAR; WAIT_L(0); MMA(1, 0, At, B0); BAR; SCHED;
;     STAGE_B(SB(0, 1), bcol + HALF, t + 2);
;     WAIT_V(6); BAR; MMA(1, 1, At, B1); BAR;
.LBB0_2621:
	s_or_b64 exec, exec, s[12:13]
	v_readlane_b32 s12, v253, 46
	v_and_b32_e32 v18, 15, v142
	s_waitcnt vmcnt(0)
	v_lshlrev_b32_e32 v20, 2, v142
	v_add_u32_e32 v151, s12, v9
	v_and_b32_e32 v19, 48, v142
	v_lshlrev_b32_e32 v18, 6, v18
	v_and_b32_e32 v20, 32, v20
	s_mov_b64 s[22:23], 0x80
	v_readfirstlane_b32 s12, v151
	v_add_u32_e32 v152, 0x2000, v151
	v_bitop3_b32 v18, v18, v20, v19 bitop3:0x36
	v_lshlrev_b32_e32 v19, 6, v142
	v_lshl_add_u64 v[0:1], v[0:1], 0, s[22:23]
	s_mov_b32 m0, s12
	v_readfirstlane_b32 s12, v152
	v_add_u32_e32 v153, 0x8000, v145
	v_and_b32_e32 v19, 0x3000, v19
	s_waitcnt vmcnt(0)
	s_barrier
	global_load_lds_dwordx4 v[0:1], off
	v_lshl_add_u64 v[0:1], v[2:3], 0, s[22:23]
	s_mov_b32 m0, s12
	v_readfirstlane_b32 s12, v153
	v_add_u32_e32 v154, 0xa000, v145
	v_add_u32_e32 v19, s16, v19
	global_load_lds_dwordx4 v[0:1], off
	v_lshl_add_u64 v[0:1], v[4:5], 0, s[22:23]
	s_mov_b32 m0, s12
	v_readfirstlane_b32 s12, v154
	v_readlane_b32 s16, v253, 47
	global_load_lds_dwordx4 v[0:1], off
	s_mov_b32 m0, s12
	s_add_u32 s12, s17, 0x160080
	v_add_u32_e32 v155, s16, v9
	v_lshl_add_u64 v[0:1], v[6:7], 0, s[22:23]
	s_addc_u32 s13, s38, 0
	v_readfirstlane_b32 s16, v155
	global_load_lds_dwordx4 v[0:1], off
	v_lshl_add_u64 v[0:1], s[12:13], 0, v[180:181]
	s_mov_b32 m0, s16
	v_add_u32_e32 v156, 0x2000, v155
	global_load_lds_dwordx4 v[0:1], off
	v_lshl_add_u64 v[0:1], s[12:13], 0, v[128:129]
	v_readfirstlane_b32 s12, v156
	s_mov_b32 m0, s12
	s_mov_b32 s16, 0x16000
	global_load_lds_dwordx4 v[0:1], off
	v_lshrrev_b32_e32 v1, 1, v8
	v_mul_lo_u32 v0, v11, s18
	v_lshrrev_b32_e32 v3, 1, v13
	v_mul_lo_u32 v2, v15, s18
	v_mad_u64_u32 v[0:1], s[12:13], v1, s16, v[0:1]
	v_mad_u64_u32 v[2:3], s[12:13], v3, s16, v[2:3]
	v_or_b32_e32 v0, v0, v10
	v_or_b32_e32 v2, v2, v14
	v_add_lshl_u32 v0, v0, v12, 1
	v_mov_b32_e32 v1, v181
	v_add_lshl_u32 v2, v2, v16, 1
	v_mov_b32_e32 v3, v181
	v_lshl_add_u64 v[130:131], s[8:9], 0, v[0:1]
	v_lshl_add_u64 v[132:133], s[8:9], 0, v[2:3]
	s_add_u32 s8, s48, s15
	s_waitcnt vmcnt(6)
	s_addc_u32 s9, s49, s14
	v_lshl_add_u32 v17, v17, 13, 32
	v_lshl_add_u64 v[134:135], s[8:9], 0, v[0:1]
	v_lshl_add_u64 v[138:139], s[10:11], 0, v[0:1]
	v_lshl_add_u64 v[136:137], s[8:9], 0, v[2:3]
	v_lshl_add_u64 v[140:141], s[10:11], 0, v[2:3]
	s_mov_b32 s8, -2
	v_add_u32_e32 v147, v19, v18
	v_add_u32_e32 v144, v17, v18
	s_barrier
	ds_read_b128 v[160:163], v147
	ds_read_b128 v[164:167], v147 offset:1024
	ds_read_b128 v[168:171], v147 offset:2048
	ds_read_b128 v[172:175], v147 offset:3072
	v_add_u32_e32 v157, 0xc000, v145
	v_lshl_add_u64 v[222:223], s[86:87], 0, v[134:135]
	v_readfirstlane_b32 s9, v157
	v_lshl_add_u64 v[158:159], v[222:223], 0, s[72:73]
	s_mov_b32 m0, s9
	ds_read_b128 v[176:179], v144
	ds_read_b128 v[182:185], v144 offset:1024
	ds_read_b128 v[186:189], v144 offset:2048
	ds_read_b128 v[190:193], v144 offset:3072
	ds_read_b128 v[194:197], v144 offset:4096
	ds_read_b128 v[198:201], v144 offset:5120
	ds_read_b128 v[202:205], v144 offset:6144
	ds_read_b128 v[206:209], v144 offset:7168
	global_load_lds_dwordx4 v[158:159], off
	v_add_u32_e32 v158, 0xe000, v145
	v_lshl_add_u64 v[226:227], s[86:87], 0, v[136:137]
	v_readfirstlane_b32 s9, v158
	v_lshl_add_u64 v[210:211], v[226:227], 0, s[72:73]
	s_mov_b32 m0, s9
	s_nop 0
	global_load_lds_dwordx4 v[210:211], off
	ds_read_b128 v[210:213], v147 offset:16384
	ds_read_b128 v[214:217], v147 offset:17408
	ds_read_b128 v[218:221], v147 offset:18432
	ds_read_b128 v[230:233], v147 offset:19456
	s_waitcnt lgkmcnt(0)
	s_waitcnt vmcnt(8)
	s_barrier
	s_setprio 1
	v_mfma_f32_16x16x32_bf16 v[124:127], v[160:163], v[176:179], 0
	v_mfma_f32_16x16x32_bf16 v[120:123], v[168:171], v[176:179], 0
	v_mfma_f32_16x16x32_bf16 v[116:119], v[160:163], v[186:189], 0
	v_mfma_f32_16x16x32_bf16 v[112:115], v[168:171], v[186:189], 0
	v_mfma_f32_16x16x32_bf16 v[108:111], v[160:163], v[194:197], 0
	v_mfma_f32_16x16x32_bf16 v[104:107], v[168:171], v[194:197], 0
	v_mfma_f32_16x16x32_bf16 v[100:103], v[160:163], v[202:205], 0
	v_mfma_f32_16x16x32_bf16 v[96:99], v[168:171], v[202:205], 0
	v_mfma_f32_16x16x32_bf16 v[124:127], v[164:167], v[182:185], v[124:127]
	v_mfma_f32_16x16x32_bf16 v[120:123], v[172:175], v[182:185], v[120:123]
	v_mfma_f32_16x16x32_bf16 v[116:119], v[164:167], v[190:193], v[116:119]
	v_mfma_f32_16x16x32_bf16 v[112:115], v[172:175], v[190:193], v[112:115]
	v_mfma_f32_16x16x32_bf16 v[108:111], v[164:167], v[198:201], v[108:111]
	v_mfma_f32_16x16x32_bf16 v[104:107], v[172:175], v[198:201], v[104:107]
	v_mfma_f32_16x16x32_bf16 v[100:103], v[164:167], v[206:209], v[100:103]
	v_mfma_f32_16x16x32_bf16 v[96:99], v[172:175], v[206:209], v[96:99]
	v_mfma_f32_16x16x32_bf16 v[92:95], v[210:213], v[176:179], 0
	v_mfma_f32_16x16x32_bf16 v[88:91], v[218:221], v[176:179], 0
	v_mfma_f32_16x16x32_bf16 v[84:87], v[210:213], v[186:189], 0
	v_mfma_f32_16x16x32_bf16 v[80:83], v[218:221], v[186:189], 0
	v_mfma_f32_16x16x32_bf16 v[76:79], v[210:213], v[194:197], 0
	v_mfma_f32_16x16x32_bf16 v[72:75], v[218:221], v[194:197], 0
	v_mfma_f32_16x16x32_bf16 v[68:71], v[210:213], v[202:205], 0
	v_mfma_f32_16x16x32_bf16 v[64:67], v[218:221], v[202:205], 0
	v_mfma_f32_16x16x32_bf16 v[92:95], v[214:217], v[182:185], v[92:95]
	v_mfma_f32_16x16x32_bf16 v[88:91], v[230:233], v[182:185], v[88:91]
	v_mfma_f32_16x16x32_bf16 v[84:87], v[214:217], v[190:193], v[84:87]
	v_mfma_f32_16x16x32_bf16 v[80:83], v[230:233], v[190:193], v[80:83]
	v_mfma_f32_16x16x32_bf16 v[76:79], v[214:217], v[198:201], v[76:79]
	v_mfma_f32_16x16x32_bf16 v[72:75], v[230:233], v[198:201], v[72:75]
	s_setprio 2
	s_barrier
; #define STAGE_A(P, br, kt) do { const char* _base = (const char*)(((kt) < G.ksplit ? G.A1 : A2m) + (long)(br) * G.lda + (long)(kt) * BK); \
;     __builtin_amdgcn_global_load_lds((const unsigned*)(_base + aoff0), (unsigned*)((char*)(P) + sb0), 16, 0, 0); \
;     __builtin_amdgcn_global_load_lds((const unsigned*)(_base + aoff1), (unsigned*)((char*)(P) + sb1), 16, 0, 0); } while (0)
; #define STAGE_B(P, br, kt) do { const char* _base = (const char*)(G.Bt + (long)(br) * G.ldb + (long)(kt) * BK); \
;     __builtin_amdgcn_global_load_lds((const unsigned*)(_base + boff0), (unsigned*)((char*)(P) + sb0), 16, 0, 0); \
;     __builtin_amdgcn_global_load_lds((const unsigned*)(_base + boff1), (unsigned*)((char*)(P) + sb1), 16, 0, 0); } while (0)
; #define LDA(dst, b, h) for (int m = 0; m < 4; ++m) for (int k = 0; k < 2; ++k) \
;     dst[m][k] = *reinterpret_cast<const bf16x8*>(a_rd + ((b) * 2 + (h)) * (HT * 2) + m * 2048 + k * 1024)
; #define LDB(dst, b, h) for (int n = 0; n < 2; ++n) for (int k = 0; k < 2; ++k) \
;     dst[n][k] = *reinterpret_cast<const bf16x8*>(b_rd + ((b) * 2 + (h)) * (HT * 2) + n * 2048 + k * 1024)
; #define MMA(ai, bj, At_, Bt_) do { __builtin_amdgcn_s_setprio(1); \
;     for (int m = 0; m < 4; ++m) for (int n = 0; n < 2; ++n) for (int k = 0; k < 2; ++k) \
;       acc[ai][bj][m][n] = __builtin_amdgcn_mfma_f32_16x16x32_bf16(Bt_[n][k], At_[m][k], acc[ai][bj][m][n], 0, 0, 0); \
;     __builtin_amdgcn_s_setprio(0); } while (0)
; #define WAIT_V(n) asm volatile("s_waitcnt vmcnt(" #n ")" ::: "memory")
; #define WAIT_L(n) asm volatile("s_waitcnt lgkmcnt(" #n ")" ::: "memory")
;     ...
;   for (int t = 0; t < nt - 2; t += 2) {
;     LDB(B0, 0, 0); SCHED; LDA(At, 0, 0); STAGE_A(SA(1, 1), brow + HALF, t + 1);
;     WAIT_L(8); BAR; WAIT_L(0); MMA(0, 0, At, B0); BAR; SCHED;
;     LDB(B1, 0, 1); STAGE_B(SB(0, 0), bcol, t + 2);
;     BAR; WAIT_L(0); MMA(0, 1, At, B1); BAR;
;     LDA(At, 0, 1); STAGE_A(SA(0, 0), brow, t + 2);
;     BAR; WAIT_L(0); MMA(1, 0, At, B0); BAR; SCHED;
;     STAGE_B(SB(0, 1), bcol + HALF, t + 2);
;     WAIT_V(6); BAR; MMA(1, 1, At, B1); BAR;
;     LDB(B0, 1, 0); SCHED; LDA(At, 1, 0); STAGE_A(SA(0, 1), brow + HALF, t + 2);
;     WAIT_L(8); BAR; WAIT_L(0); MMA(0, 0, At, B0); BAR; SCHED;
;     LDB(B1, 1, 1); STAGE_B(SB(1, 0), bcol, t + 3);
;     BAR; WAIT_L(0); MMA(0, 1, At, B1); BAR;
;     LDA(At, 1, 1); STAGE_A(SA(1, 0), brow, t + 3);
	v_mfma_f32_16x16x32_bf16 v[68:71], v[214:217], v[206:209], v[68:71]
	v_mfma_f32_16x16x32_bf16 v[64:67], v[230:233], v[206:209], v[64:67]
	s_setprio 0
	v_lshl_add_u64 v[234:235], s[86:87], 0, v[130:131]
	v_readfirstlane_b32 s9, v143
	v_lshl_add_u64 v[236:237], v[234:235], 0, s[74:75]
	s_mov_b32 m0, s9
	v_add_u32_e32 v159, 0x2000, v143
	global_load_lds_dwordx4 v[236:237], off
	v_lshl_add_u64 v[236:237], s[86:87], 0, v[132:133]
	v_readfirstlane_b32 s9, v159
	v_lshl_add_u64 v[238:239], v[236:237], 0, s[74:75]
	s_mov_b32 m0, s9
	s_nop 0
	global_load_lds_dwordx4 v[238:239], off
	v_readfirstlane_b32 s9, v145
	v_lshl_add_u64 v[238:239], v[222:223], 0, s[76:77]
	s_mov_b32 m0, s9
	v_readfirstlane_b32 s9, v146
	ds_read_b128 v[176:179], v144 offset:16384
	ds_read_b128 v[182:185], v144 offset:17408
	ds_read_b128 v[186:189], v144 offset:18432
	ds_read_b128 v[190:193], v144 offset:19456
	ds_read_b128 v[194:197], v144 offset:20480
	ds_read_b128 v[198:201], v144 offset:21504
	ds_read_b128 v[202:205], v144 offset:22528
	ds_read_b128 v[206:209], v144 offset:23552
	global_load_lds_dwordx4 v[238:239], off
	v_lshl_add_u64 v[238:239], v[226:227], 0, s[76:77]
	s_mov_b32 m0, s9
	s_nop 0
	global_load_lds_dwordx4 v[238:239], off
	v_lshl_add_u64 v[238:239], s[86:87], 0, v[138:139]
	v_readfirstlane_b32 s9, v148
	v_add_u32_e32 v159, 0x2000, v148
	v_lshl_add_u64 v[250:251], v[238:239], 0, s[78:79]
	s_mov_b32 m0, s9
	v_lshl_add_u64 v[240:241], s[86:87], 0, v[140:141]
	v_readfirstlane_b32 s9, v159
	global_load_lds_dwordx4 v[250:251], off
	v_lshl_add_u64 v[250:251], v[240:241], 0, s[78:79]
	s_mov_b32 m0, s9
	s_nop 0
	global_load_lds_dwordx4 v[250:251], off
	s_waitcnt lgkmcnt(0)
	s_waitcnt vmcnt(8)
	s_barrier
	s_setprio 1
	v_mfma_f32_16x16x32_bf16 v[60:63], v[160:163], v[176:179], 0
	v_mfma_f32_16x16x32_bf16 v[56:59], v[168:171], v[176:179], 0
	v_mfma_f32_16x16x32_bf16 v[52:55], v[160:163], v[186:189], 0
	v_mfma_f32_16x16x32_bf16 v[48:51], v[168:171], v[186:189], 0
	v_mfma_f32_16x16x32_bf16 v[44:47], v[160:163], v[194:197], 0
	v_mfma_f32_16x16x32_bf16 v[40:43], v[168:171], v[194:197], 0
	v_mfma_f32_16x16x32_bf16 v[36:39], v[160:163], v[202:205], 0
	v_mfma_f32_16x16x32_bf16 v[32:35], v[168:171], v[202:205], 0
	v_mfma_f32_16x16x32_bf16 v[60:63], v[164:167], v[182:185], v[60:63]
	v_mfma_f32_16x16x32_bf16 v[56:59], v[172:175], v[182:185], v[56:59]
	v_mfma_f32_16x16x32_bf16 v[52:55], v[164:167], v[190:193], v[52:55]
	v_mfma_f32_16x16x32_bf16 v[48:51], v[172:175], v[190:193], v[48:51]
	v_mfma_f32_16x16x32_bf16 v[44:47], v[164:167], v[198:201], v[44:47]
	v_mfma_f32_16x16x32_bf16 v[40:43], v[172:175], v[198:201], v[40:43]
	v_mfma_f32_16x16x32_bf16 v[36:39], v[164:167], v[206:209], v[36:39]
	v_mfma_f32_16x16x32_bf16 v[32:35], v[172:175], v[206:209], v[32:35]
	v_mfma_f32_16x16x32_bf16 v[28:31], v[210:213], v[176:179], 0
	v_mfma_f32_16x16x32_bf16 v[24:27], v[218:221], v[176:179], 0
	v_mfma_f32_16x16x32_bf16 v[20:23], v[210:213], v[186:189], 0
	v_mfma_f32_16x16x32_bf16 v[16:19], v[218:221], v[186:189], 0
	v_mfma_f32_16x16x32_bf16 v[12:15], v[210:213], v[194:197], 0
	v_mfma_f32_16x16x32_bf16 v[8:11], v[218:221], v[194:197], 0
	v_mfma_f32_16x16x32_bf16 v[4:7], v[210:213], v[202:205], 0
	v_mfma_f32_16x16x32_bf16 v[0:3], v[218:221], v[202:205], 0
	v_mfma_f32_16x16x32_bf16 v[28:31], v[214:217], v[182:185], v[28:31]
	v_mfma_f32_16x16x32_bf16 v[24:27], v[230:233], v[182:185], v[24:27]
	v_mfma_f32_16x16x32_bf16 v[20:23], v[214:217], v[190:193], v[20:23]
	v_mfma_f32_16x16x32_bf16 v[16:19], v[230:233], v[190:193], v[16:19]
	v_mfma_f32_16x16x32_bf16 v[12:15], v[214:217], v[198:201], v[12:15]
	v_mfma_f32_16x16x32_bf16 v[8:11], v[230:233], v[198:201], v[8:11]
	s_setprio 2
	s_barrier
	v_mfma_f32_16x16x32_bf16 v[4:7], v[214:217], v[206:209], v[4:7]
	v_mfma_f32_16x16x32_bf16 v[0:3], v[230:233], v[206:209], v[0:3]
	s_setprio 0
	ds_read_b128 v[160:163], v147 offset:32768
	ds_read_b128 v[164:167], v147 offset:33792
	ds_read_b128 v[168:171], v147 offset:34816
	ds_read_b128 v[172:175], v147 offset:35840
	v_readfirstlane_b32 s9, v149
	v_lshl_add_u64 v[210:211], v[222:223], 0, s[80:81]
	s_mov_b32 m0, s9
	v_readfirstlane_b32 s9, v150
	ds_read_b128 v[176:179], v144 offset:32768
	ds_read_b128 v[182:185], v144 offset:33792
	ds_read_b128 v[186:189], v144 offset:34816
	ds_read_b128 v[190:193], v144 offset:35840
	ds_read_b128 v[194:197], v144 offset:36864
	ds_read_b128 v[198:201], v144 offset:37888
	ds_read_b128 v[202:205], v144 offset:38912
	ds_read_b128 v[206:209], v144 offset:39936
	global_load_lds_dwordx4 v[210:211], off
	v_lshl_add_u64 v[210:211], v[226:227], 0, s[80:81]
	s_mov_b32 m0, s9
	s_nop 0
	global_load_lds_dwordx4 v[210:211], off
	ds_read_b128 v[210:213], v147 offset:49152
	ds_read_b128 v[214:217], v147 offset:50176
	ds_read_b128 v[218:221], v147 offset:51200
	ds_read_b128 v[230:233], v147 offset:52224
	s_waitcnt lgkmcnt(0)
	s_waitcnt vmcnt(8)
	s_barrier
; #define STAGE_A(P, br, kt) do { const char* _base = (const char*)(((kt) < G.ksplit ? G.A1 : A2m) + (long)(br) * G.lda + (long)(kt) * BK); \
;     __builtin_amdgcn_global_load_lds((const unsigned*)(_base + aoff0), (unsigned*)((char*)(P) + sb0), 16, 0, 0); \
;     __builtin_amdgcn_global_load_lds((const unsigned*)(_base + aoff1), (unsigned*)((char*)(P) + sb1), 16, 0, 0); } while (0)
; #define STAGE_B(P, br, kt) do { const char* _base = (const char*)(G.Bt + (long)(br) * G.ldb + (long)(kt) * BK); \
;     __builtin_amdgcn_global_load_lds((const unsigned*)(_base + boff0), (unsigned*)((char*)(P) + sb0), 16, 0, 0); \
;     __builtin_amdgcn_global_load_lds((const unsigned*)(_base + boff1), (unsigned*)((char*)(P) + sb1), 16, 0, 0); } while (0)
; #define LDA(dst, b, h) for (int m = 0; m < 4; ++m) for (int k = 0; k < 2; ++k) \
;     dst[m][k] = *reinterpret_cast<const bf16x8*>(a_rd + ((b) * 2 + (h)) * (HT * 2) + m * 2048 + k * 1024)
; #define LDB(dst, b, h) for (int n = 0; n < 2; ++n) for (int k = 0; k < 2; ++k) \
;     dst[n][k] = *reinterpret_cast<const bf16x8*>(b_rd + ((b) * 2 + (h)) * (HT * 2) + n * 2048 + k * 1024)
; #define MMA(ai, bj, At_, Bt_) do { __builtin_amdgcn_s_setprio(1); \
;     for (int m = 0; m < 4; ++m) for (int n = 0; n < 2; ++n) for (int k = 0; k < 2; ++k) \
;       acc[ai][bj][m][n] = __builtin_amdgcn_mfma_f32_16x16x32_bf16(Bt_[n][k], At_[m][k], acc[ai][bj][m][n], 0, 0, 0); \
;     __builtin_amdgcn_s_setprio(0); } while (0)
; #define WAIT_V(n) asm volatile("s_waitcnt vmcnt(" #n ")" ::: "memory")
; #define WAIT_L(n) asm volatile("s_waitcnt lgkmcnt(" #n ")" ::: "memory")
; #define BAR __builtin_amdgcn_s_barrier()
; #define SCHED __builtin_amdgcn_sched_barrier(0)
;     ...
;     LDB(B0, 1, 0); SCHED; LDA(At, 1, 0); STAGE_A(SA(0, 1), brow + HALF, t + 2);
;     WAIT_L(8); BAR; WAIT_L(0); MMA(0, 0, At, B0); BAR; SCHED;
;     LDB(B1, 1, 1); STAGE_B(SB(1, 0), bcol, t + 3);
;     BAR; WAIT_L(0); MMA(0, 1, At, B1); BAR;
;     LDA(At, 1, 1); STAGE_A(SA(1, 0), brow, t + 3);
;     BAR; WAIT_L(0); MMA(1, 0, At, B0); BAR; SCHED;
;     STAGE_B(SB(1, 1), bcol + HALF, t + 3);
;     WAIT_V(6); BAR; MMA(1, 1, At, B1); BAR;
;   }
	s_setprio 1
	v_mfma_f32_16x16x32_bf16 v[124:127], v[160:163], v[176:179], v[124:127]
	v_mfma_f32_16x16x32_bf16 v[120:123], v[168:171], v[176:179], v[120:123]
	v_mfma_f32_16x16x32_bf16 v[116:119], v[160:163], v[186:189], v[116:119]
	v_mfma_f32_16x16x32_bf16 v[112:115], v[168:171], v[186:189], v[112:115]
	v_mfma_f32_16x16x32_bf16 v[108:111], v[160:163], v[194:197], v[108:111]
	v_mfma_f32_16x16x32_bf16 v[104:107], v[168:171], v[194:197], v[104:107]
	v_mfma_f32_16x16x32_bf16 v[100:103], v[160:163], v[202:205], v[100:103]
	v_mfma_f32_16x16x32_bf16 v[96:99], v[168:171], v[202:205], v[96:99]
	v_mfma_f32_16x16x32_bf16 v[124:127], v[164:167], v[182:185], v[124:127]
	v_mfma_f32_16x16x32_bf16 v[120:123], v[172:175], v[182:185], v[120:123]
	v_mfma_f32_16x16x32_bf16 v[116:119], v[164:167], v[190:193], v[116:119]
	v_mfma_f32_16x16x32_bf16 v[112:115], v[172:175], v[190:193], v[112:115]
	v_mfma_f32_16x16x32_bf16 v[108:111], v[164:167], v[198:201], v[108:111]
	v_mfma_f32_16x16x32_bf16 v[104:107], v[172:175], v[198:201], v[104:107]
	v_mfma_f32_16x16x32_bf16 v[100:103], v[164:167], v[206:209], v[100:103]
	v_mfma_f32_16x16x32_bf16 v[96:99], v[172:175], v[206:209], v[96:99]
	v_mfma_f32_16x16x32_bf16 v[92:95], v[210:213], v[176:179], v[92:95]
	v_mfma_f32_16x16x32_bf16 v[88:91], v[218:221], v[176:179], v[88:91]
	v_mfma_f32_16x16x32_bf16 v[84:87], v[210:213], v[186:189], v[84:87]
	v_mfma_f32_16x16x32_bf16 v[80:83], v[218:221], v[186:189], v[80:83]
	v_mfma_f32_16x16x32_bf16 v[76:79], v[210:213], v[194:197], v[76:79]
	v_mfma_f32_16x16x32_bf16 v[72:75], v[218:221], v[194:197], v[72:75]
	v_mfma_f32_16x16x32_bf16 v[68:71], v[210:213], v[202:205], v[68:71]
	v_mfma_f32_16x16x32_bf16 v[64:67], v[218:221], v[202:205], v[64:67]
	v_mfma_f32_16x16x32_bf16 v[92:95], v[214:217], v[182:185], v[92:95]
	v_mfma_f32_16x16x32_bf16 v[88:91], v[230:233], v[182:185], v[88:91]
	v_mfma_f32_16x16x32_bf16 v[84:87], v[214:217], v[190:193], v[84:87]
	v_mfma_f32_16x16x32_bf16 v[80:83], v[230:233], v[190:193], v[80:83]
	v_mfma_f32_16x16x32_bf16 v[76:79], v[214:217], v[198:201], v[76:79]
	v_mfma_f32_16x16x32_bf16 v[72:75], v[230:233], v[198:201], v[72:75]
	s_setprio 2
	s_barrier
	v_mfma_f32_16x16x32_bf16 v[68:71], v[214:217], v[206:209], v[68:71]
	v_mfma_f32_16x16x32_bf16 v[64:67], v[230:233], v[206:209], v[64:67]
	s_setprio 0
	v_readfirstlane_b32 s9, v151
	v_lshl_add_u64 v[234:235], v[234:235], 0, s[82:83]
	s_mov_b32 m0, s9
	v_readfirstlane_b32 s9, v152
	global_load_lds_dwordx4 v[234:235], off
	v_lshl_add_u64 v[234:235], v[236:237], 0, s[82:83]
	s_mov_b32 m0, s9
	s_nop 0
	global_load_lds_dwordx4 v[234:235], off
	v_readfirstlane_b32 s9, v153
	v_lshl_add_u64 v[222:223], v[222:223], 0, s[54:55]
	s_mov_b32 m0, s9
	v_readfirstlane_b32 s9, v154
	ds_read_b128 v[176:179], v144 offset:49152
	ds_read_b128 v[182:185], v144 offset:50176
	ds_read_b128 v[186:189], v144 offset:51200
	ds_read_b128 v[190:193], v144 offset:52224
	ds_read_b128 v[194:197], v144 offset:53248
	ds_read_b128 v[198:201], v144 offset:54272
	ds_read_b128 v[202:205], v144 offset:55296
	ds_read_b128 v[206:209], v144 offset:56320
	global_load_lds_dwordx4 v[222:223], off
	v_lshl_add_u64 v[222:223], v[226:227], 0, s[54:55]
	s_mov_b32 m0, s9
	s_nop 0
	global_load_lds_dwordx4 v[222:223], off
	v_readfirstlane_b32 s9, v155
	v_lshl_add_u64 v[250:251], v[238:239], 0, s[92:93]
	s_mov_b32 m0, s9
	v_readfirstlane_b32 s9, v156
	global_load_lds_dwordx4 v[250:251], off
	v_lshl_add_u64 v[250:251], v[240:241], 0, s[92:93]
	s_mov_b32 m0, s9
	s_nop 0
	global_load_lds_dwordx4 v[250:251], off
	s_waitcnt lgkmcnt(0)
	s_waitcnt vmcnt(8)
	s_barrier
	s_setprio 1
	v_mfma_f32_16x16x32_bf16 v[60:63], v[160:163], v[176:179], v[60:63]
	v_mfma_f32_16x16x32_bf16 v[56:59], v[168:171], v[176:179], v[56:59]
	v_mfma_f32_16x16x32_bf16 v[52:55], v[160:163], v[186:189], v[52:55]
	v_mfma_f32_16x16x32_bf16 v[48:51], v[168:171], v[186:189], v[48:51]
	v_mfma_f32_16x16x32_bf16 v[44:47], v[160:163], v[194:197], v[44:47]
	v_mfma_f32_16x16x32_bf16 v[40:43], v[168:171], v[194:197], v[40:43]
	v_mfma_f32_16x16x32_bf16 v[36:39], v[160:163], v[202:205], v[36:39]
	v_mfma_f32_16x16x32_bf16 v[32:35], v[168:171], v[202:205], v[32:35]
	v_mfma_f32_16x16x32_bf16 v[60:63], v[164:167], v[182:185], v[60:63]
	v_mfma_f32_16x16x32_bf16 v[56:59], v[172:175], v[182:185], v[56:59]
	v_mfma_f32_16x16x32_bf16 v[52:55], v[164:167], v[190:193], v[52:55]
	v_mfma_f32_16x16x32_bf16 v[48:51], v[172:175], v[190:193], v[48:51]
	v_mfma_f32_16x16x32_bf16 v[44:47], v[164:167], v[198:201], v[44:47]
	v_mfma_f32_16x16x32_bf16 v[40:43], v[172:175], v[198:201], v[40:43]
	v_mfma_f32_16x16x32_bf16 v[36:39], v[164:167], v[206:209], v[36:39]
	v_mfma_f32_16x16x32_bf16 v[32:35], v[172:175], v[206:209], v[32:35]
	v_mfma_f32_16x16x32_bf16 v[28:31], v[210:213], v[176:179], v[28:31]
	v_mfma_f32_16x16x32_bf16 v[24:27], v[218:221], v[176:179], v[24:27]
	v_mfma_f32_16x16x32_bf16 v[20:23], v[210:213], v[186:189], v[20:23]
	v_mfma_f32_16x16x32_bf16 v[16:19], v[218:221], v[186:189], v[16:19]
	v_mfma_f32_16x16x32_bf16 v[12:15], v[210:213], v[194:197], v[12:15]
	v_mfma_f32_16x16x32_bf16 v[8:11], v[218:221], v[194:197], v[8:11]
	v_mfma_f32_16x16x32_bf16 v[4:7], v[210:213], v[202:205], v[4:7]
	v_mfma_f32_16x16x32_bf16 v[0:3], v[218:221], v[202:205], v[0:3]
	v_mfma_f32_16x16x32_bf16 v[28:31], v[214:217], v[182:185], v[28:31]
	v_mfma_f32_16x16x32_bf16 v[24:27], v[230:233], v[182:185], v[24:27]
	v_mfma_f32_16x16x32_bf16 v[20:23], v[214:217], v[190:193], v[20:23]
	v_mfma_f32_16x16x32_bf16 v[16:19], v[230:233], v[190:193], v[16:19]
	v_mfma_f32_16x16x32_bf16 v[12:15], v[214:217], v[198:201], v[12:15]
	v_mfma_f32_16x16x32_bf16 v[8:11], v[230:233], v[198:201], v[8:11]
	s_setprio 2
	s_barrier
	v_mfma_f32_16x16x32_bf16 v[4:7], v[214:217], v[206:209], v[4:7]
	v_mfma_f32_16x16x32_bf16 v[0:3], v[230:233], v[206:209], v[0:3]
	s_setprio 0
	s_add_i32 s8, s8, 2
	v_lshl_add_u64 v[130:131], v[130:131], 0, s[90:91]
	v_lshl_add_u64 v[132:133], v[132:133], 0, s[90:91]
	v_lshl_add_u64 v[134:135], v[134:135], 0, s[90:91]
	v_lshl_add_u64 v[136:137], v[136:137], 0, s[90:91]
	v_lshl_add_u64 v[138:139], v[138:139], 0, s[90:91]
	s_cmpk_lt_u32 s8, 0x54
	v_lshl_add_u64 v[140:141], v[140:141], 0, s[90:91]
	s_cbranch_scc0 .Lmy_kexit_5

; #define STAGE_A(P, br, kt) do { const char* _base = (const char*)(((kt) < G.ksplit ? G.A1 : A2m) + (long)(br) * G.lda + (long)(kt) * BK); \
;     __builtin_amdgcn_global_load_lds((const unsigned*)(_base + aoff0), (unsigned*)((char*)(P) + sb0), 16, 0, 0); \
;     __builtin_amdgcn_global_load_lds((const unsigned*)(_base + aoff1), (unsigned*)((char*)(P) + sb1), 16, 0, 0); } while (0)
; #define LDA(dst, b, h) for (int m = 0; m < 4; ++m) for (int k = 0; k < 2; ++k) \
;     dst[m][k] = *reinterpret_cast<const bf16x8*>(a_rd + ((b) * 2 + (h)) * (HT * 2) + m * 2048 + k * 1024)
; #define LDB(dst, b, h) for (int n = 0; n < 2; ++n) for (int k = 0; k < 2; ++k) \
;     dst[n][k] = *reinterpret_cast<const bf16x8*>(b_rd + ((b) * 2 + (h)) * (HT * 2) + n * 2048 + k * 1024)
; #define MMA(ai, bj, At_, Bt_) do { __builtin_amdgcn_s_setprio(1); \
;     for (int m = 0; m < 4; ++m) for (int n = 0; n < 2; ++n) for (int k = 0; k < 2; ++k) \
;       acc[ai][bj][m][n] = __builtin_amdgcn_mfma_f32_16x16x32_bf16(Bt_[n][k], At_[m][k], acc[ai][bj][m][n], 0, 0, 0); \
;     __builtin_amdgcn_s_setprio(0); } while (0)
; #define WAIT_V(n) asm volatile("s_waitcnt vmcnt(" #n ")" ::: "memory")
; #define WAIT_L(n) asm volatile("s_waitcnt lgkmcnt(" #n ")" ::: "memory")
; #define BAR __builtin_amdgcn_s_barrier()
;     ...
;   { LDB(B0, 0, 0); LDA(At, 0, 0); STAGE_A(SA(1, 1), brow + HALF, nt - 1);
;     BAR; WAIT_L(0); MMA(0, 0, At, B0); BAR;
;     LDB(B1, 0, 1); BAR; WAIT_L(0); MMA(0, 1, At, B1); BAR;
;     LDA(At, 0, 1); WAIT_V(4); BAR; WAIT_L(0); MMA(1, 0, At, B0); MMA(1, 1, At, B1); BAR; }
;   { LDB(B0, 1, 0); LDA(At, 1, 0); WAIT_V(2); BAR; WAIT_L(0); MMA(0, 0, At, B0); BAR;
.Lmy_kexit_5:
	s_waitcnt vmcnt(6)
	v_not_b32_e32 v250, 63
	v_mov_b32_e32 v251, 0x41b17218
	s_add_u32 s6, s6, 0x2b80
	s_addc_u32 s7, s7, 0
	v_readfirstlane_b32 s8, v157
	v_lshl_add_u64 v[190:191], s[6:7], 0, v[180:181]
	s_mov_b32 m0, s8
	v_lshl_add_u64 v[128:129], s[6:7], 0, v[128:129]
	v_readfirstlane_b32 s6, v158
	ds_read_b128 v[130:133], v147
	ds_read_b128 v[134:137], v147 offset:1024
	ds_read_b128 v[138:141], v147 offset:2048
	ds_read_b128 v[148:151], v147 offset:3072
	ds_read_b128 v[152:155], v144
	ds_read_b128 v[160:163], v144 offset:1024
	ds_read_b128 v[164:167], v144 offset:2048
	ds_read_b128 v[168:171], v144 offset:3072
	ds_read_b128 v[172:175], v144 offset:4096
	ds_read_b128 v[176:179], v144 offset:5120
	ds_read_b128 v[182:185], v144 offset:6144
	ds_read_b128 v[186:189], v144 offset:7168
	global_load_lds_dwordx4 v[190:191], off
	s_mov_b32 m0, s6
	s_nop 0
	global_load_lds_dwordx4 v[128:129], off
	s_barrier
	s_waitcnt lgkmcnt(0)
	s_setprio 1
	s_waitcnt lgkmcnt(0)
	v_mfma_f32_16x16x32_bf16 v[124:127], v[130:133], v[152:155], v[124:127]
	v_mfma_f32_16x16x32_bf16 v[120:123], v[138:141], v[152:155], v[120:123]
	v_mfma_f32_16x16x32_bf16 v[116:119], v[130:133], v[164:167], v[116:119]
	v_mfma_f32_16x16x32_bf16 v[112:115], v[138:141], v[164:167], v[112:115]
	v_mfma_f32_16x16x32_bf16 v[108:111], v[130:133], v[172:175], v[108:111]
	v_mfma_f32_16x16x32_bf16 v[104:107], v[138:141], v[172:175], v[104:107]
	v_mfma_f32_16x16x32_bf16 v[100:103], v[130:133], v[182:185], v[100:103]
	v_mfma_f32_16x16x32_bf16 v[96:99], v[138:141], v[182:185], v[96:99]
	v_mfma_f32_16x16x32_bf16 v[124:127], v[134:137], v[160:163], v[124:127]
	v_mfma_f32_16x16x32_bf16 v[120:123], v[148:151], v[160:163], v[120:123]
	v_mfma_f32_16x16x32_bf16 v[116:119], v[134:137], v[168:171], v[116:119]
	v_mfma_f32_16x16x32_bf16 v[112:115], v[148:151], v[168:171], v[112:115]
	v_mfma_f32_16x16x32_bf16 v[108:111], v[134:137], v[176:179], v[108:111]
	v_mfma_f32_16x16x32_bf16 v[104:107], v[148:151], v[176:179], v[104:107]
	s_setprio 2
	s_barrier
	v_mfma_f32_16x16x32_bf16 v[100:103], v[134:137], v[186:189], v[100:103]
	v_mfma_f32_16x16x32_bf16 v[96:99], v[148:151], v[186:189], v[96:99]
	s_setprio 0
	ds_read_b128 v[156:159], v147 offset:16384
	ds_read_b128 v[190:193], v147 offset:17408
	ds_read_b128 v[194:197], v147 offset:18432
	ds_read_b128 v[198:201], v147 offset:19456
	s_barrier
	s_waitcnt lgkmcnt(0)
	s_setprio 1
	s_waitcnt lgkmcnt(0)
	v_mfma_f32_16x16x32_bf16 v[92:95], v[156:159], v[152:155], v[92:95]
	v_mfma_f32_16x16x32_bf16 v[88:91], v[194:197], v[152:155], v[88:91]
	v_mfma_f32_16x16x32_bf16 v[84:87], v[156:159], v[164:167], v[84:87]
	v_mfma_f32_16x16x32_bf16 v[80:83], v[194:197], v[164:167], v[80:83]
	v_mfma_f32_16x16x32_bf16 v[76:79], v[156:159], v[172:175], v[76:79]
	v_mfma_f32_16x16x32_bf16 v[72:75], v[194:197], v[172:175], v[72:75]
	v_mfma_f32_16x16x32_bf16 v[68:71], v[156:159], v[182:185], v[68:71]
	v_mfma_f32_16x16x32_bf16 v[64:67], v[194:197], v[182:185], v[64:67]
	v_mfma_f32_16x16x32_bf16 v[202:205], v[190:193], v[160:163], v[92:95]
	v_mfma_f32_16x16x32_bf16 v[152:155], v[198:201], v[160:163], v[88:91]
	v_mfma_f32_16x16x32_bf16 v[160:163], v[190:193], v[168:171], v[84:87]
	v_mfma_f32_16x16x32_bf16 v[164:167], v[198:201], v[168:171], v[80:83]
	v_mfma_f32_16x16x32_bf16 v[168:171], v[190:193], v[176:179], v[76:79]
	v_mfma_f32_16x16x32_bf16 v[172:175], v[198:201], v[176:179], v[72:75]
	s_setprio 2
	s_barrier
	v_mfma_f32_16x16x32_bf16 v[176:179], v[190:193], v[186:189], v[68:71]
	v_mfma_f32_16x16x32_bf16 v[182:185], v[198:201], v[186:189], v[64:67]
	s_setprio 0
	s_nop 0
	ds_read_b128 v[64:67], v144 offset:16384
	ds_read_b128 v[68:71], v144 offset:17408
	ds_read_b128 v[72:75], v144 offset:18432
	ds_read_b128 v[76:79], v144 offset:19456
	ds_read_b128 v[80:83], v144 offset:20480
	ds_read_b128 v[84:87], v144 offset:21504
	ds_read_b128 v[88:91], v144 offset:22528
	ds_read_b128 v[92:95], v144 offset:23552
	s_waitcnt vmcnt(4)
	s_barrier
	s_waitcnt lgkmcnt(0)
	s_setprio 1
	s_waitcnt lgkmcnt(0)
	v_mfma_f32_16x16x32_bf16 v[60:63], v[130:133], v[64:67], v[60:63]
	v_mfma_f32_16x16x32_bf16 v[56:59], v[138:141], v[64:67], v[56:59]
	v_mfma_f32_16x16x32_bf16 v[52:55], v[130:133], v[72:75], v[52:55]
	v_mfma_f32_16x16x32_bf16 v[48:51], v[138:141], v[72:75], v[48:51]
	v_mfma_f32_16x16x32_bf16 v[44:47], v[130:133], v[80:83], v[44:47]
	v_mfma_f32_16x16x32_bf16 v[40:43], v[138:141], v[80:83], v[40:43]
	v_mfma_f32_16x16x32_bf16 v[36:39], v[130:133], v[88:91], v[36:39]
	v_mfma_f32_16x16x32_bf16 v[32:35], v[138:141], v[88:91], v[32:35]
	v_mfma_f32_16x16x32_bf16 v[60:63], v[134:137], v[68:71], v[60:63]
	v_mfma_f32_16x16x32_bf16 v[56:59], v[148:151], v[68:71], v[56:59]
	v_mfma_f32_16x16x32_bf16 v[52:55], v[134:137], v[76:79], v[52:55]
	v_mfma_f32_16x16x32_bf16 v[48:51], v[148:151], v[76:79], v[48:51]
	v_mfma_f32_16x16x32_bf16 v[44:47], v[134:137], v[84:87], v[44:47]
	v_mfma_f32_16x16x32_bf16 v[40:43], v[148:151], v[84:87], v[40:43]
	v_mfma_f32_16x16x32_bf16 v[36:39], v[134:137], v[92:95], v[36:39]
	v_mfma_f32_16x16x32_bf16 v[32:35], v[148:151], v[92:95], v[32:35]
	s_setprio 0
	s_setprio 1
	v_mfma_f32_16x16x32_bf16 v[28:31], v[156:159], v[64:67], v[28:31]
	v_mfma_f32_16x16x32_bf16 v[24:27], v[194:197], v[64:67], v[24:27]
	v_mfma_f32_16x16x32_bf16 v[20:23], v[156:159], v[72:75], v[20:23]
	v_mfma_f32_16x16x32_bf16 v[16:19], v[194:197], v[72:75], v[16:19]
	v_mfma_f32_16x16x32_bf16 v[12:15], v[156:159], v[80:83], v[12:15]
	v_mfma_f32_16x16x32_bf16 v[8:11], v[194:197], v[80:83], v[8:11]
	v_mfma_f32_16x16x32_bf16 v[4:7], v[156:159], v[88:91], v[4:7]
	v_mfma_f32_16x16x32_bf16 v[0:3], v[194:197], v[88:91], v[0:3]
	v_mfma_f32_16x16x32_bf16 v[128:131], v[190:193], v[68:71], v[28:31]
	v_mfma_f32_16x16x32_bf16 v[132:135], v[198:201], v[68:71], v[24:27]
	v_mfma_f32_16x16x32_bf16 v[136:139], v[190:193], v[76:79], v[20:23]
	v_mfma_f32_16x16x32_bf16 v[148:151], v[198:201], v[76:79], v[16:19]
	v_mfma_f32_16x16x32_bf16 v[186:189], v[190:193], v[84:87], v[12:15]
	v_mfma_f32_16x16x32_bf16 v[206:209], v[198:201], v[84:87], v[8:11]
	s_setprio 2
	s_barrier
; #define LDA(dst, b, h) for (int m = 0; m < 4; ++m) for (int k = 0; k < 2; ++k) \
;     dst[m][k] = *reinterpret_cast<const bf16x8*>(a_rd + ((b) * 2 + (h)) * (HT * 2) + m * 2048 + k * 1024)
; #define LDB(dst, b, h) for (int n = 0; n < 2; ++n) for (int k = 0; k < 2; ++k) \
;     dst[n][k] = *reinterpret_cast<const bf16x8*>(b_rd + ((b) * 2 + (h)) * (HT * 2) + n * 2048 + k * 1024)
; #define MMA(ai, bj, At_, Bt_) do { __builtin_amdgcn_s_setprio(1); \
;     for (int m = 0; m < 4; ++m) for (int n = 0; n < 2; ++n) for (int k = 0; k < 2; ++k) \
;       acc[ai][bj][m][n] = __builtin_amdgcn_mfma_f32_16x16x32_bf16(Bt_[n][k], At_[m][k], acc[ai][bj][m][n], 0, 0, 0); \
;     __builtin_amdgcn_s_setprio(0); } while (0)
; #define WAIT_V(n) asm volatile("s_waitcnt vmcnt(" #n ")" ::: "memory")
; #define WAIT_L(n) asm volatile("s_waitcnt lgkmcnt(" #n ")" ::: "memory")
; #define BAR __builtin_amdgcn_s_barrier()
;     ...
;   { LDB(B0, 1, 0); LDA(At, 1, 0); WAIT_V(2); BAR; WAIT_L(0); MMA(0, 0, At, B0); BAR;
;     LDB(B1, 1, 1); WAIT_V(0); BAR; WAIT_L(0); MMA(0, 1, At, B1); BAR;
;     LDA(At, 1, 1); BAR; WAIT_L(0); MMA(1, 0, At, B0); MMA(1, 1, At, B1); BAR; }
;   if (wr == 0) BAR;
	v_mfma_f32_16x16x32_bf16 v[156:159], v[190:193], v[92:95], v[4:7]
	v_mfma_f32_16x16x32_bf16 v[190:193], v[198:201], v[92:95], v[0:3]
	s_setprio 0
	ds_read_b128 v[24:27], v147 offset:32768
	ds_read_b128 v[28:31], v147 offset:33792
	ds_read_b128 v[194:197], v147 offset:34816
	ds_read_b128 v[198:201], v147 offset:35840
	ds_read_b128 v[0:3], v144 offset:32768
	ds_read_b128 v[4:7], v144 offset:33792
	ds_read_b128 v[8:11], v144 offset:34816
	ds_read_b128 v[12:15], v144 offset:35840
	ds_read_b128 v[16:19], v144 offset:36864
	ds_read_b128 v[20:23], v144 offset:37888
	ds_read_b128 v[210:213], v144 offset:38912
	ds_read_b128 v[214:217], v144 offset:39936
	s_waitcnt vmcnt(2)
	s_barrier
	s_waitcnt lgkmcnt(0)
	s_setprio 1
	s_waitcnt lgkmcnt(0)
	v_mfma_f32_16x16x32_bf16 v[64:67], v[24:27], v[0:3], v[124:127]
	v_mfma_f32_16x16x32_bf16 v[68:71], v[194:197], v[0:3], v[120:123]
	v_mfma_f32_16x16x32_bf16 v[72:75], v[24:27], v[8:11], v[116:119]
	v_mfma_f32_16x16x32_bf16 v[76:79], v[194:197], v[8:11], v[112:115]
	v_mfma_f32_16x16x32_bf16 v[80:83], v[24:27], v[16:19], v[108:111]
	v_mfma_f32_16x16x32_bf16 v[84:87], v[194:197], v[16:19], v[104:107]
	v_mfma_f32_16x16x32_bf16 v[88:91], v[24:27], v[210:213], v[100:103]
	v_mfma_f32_16x16x32_bf16 v[92:95], v[194:197], v[210:213], v[96:99]
	v_mfma_f32_16x16x32_bf16 v[64:67], v[28:31], v[4:7], v[64:67]
	v_mfma_f32_16x16x32_bf16 v[68:71], v[198:201], v[4:7], v[68:71]
	v_mfma_f32_16x16x32_bf16 v[72:75], v[28:31], v[12:15], v[72:75]
	v_mfma_f32_16x16x32_bf16 v[76:79], v[198:201], v[12:15], v[76:79]
	v_mfma_f32_16x16x32_bf16 v[80:83], v[28:31], v[20:23], v[80:83]
	v_mfma_f32_16x16x32_bf16 v[84:87], v[198:201], v[20:23], v[84:87]
	s_setprio 2
	s_barrier
	v_mfma_f32_16x16x32_bf16 v[88:91], v[28:31], v[214:217], v[88:91]
	v_mfma_f32_16x16x32_bf16 v[92:95], v[198:201], v[214:217], v[92:95]
	s_setprio 0
	ds_read_b128 v[218:221], v147 offset:49152
	ds_read_b128 v[230:233], v147 offset:50176
	ds_read_b128 v[234:237], v147 offset:51200
	ds_read_b128 v[238:241], v147 offset:52224
	s_waitcnt vmcnt(0)
	s_barrier
	s_waitcnt lgkmcnt(0)
	s_setprio 1
	s_waitcnt lgkmcnt(0)
	v_mfma_f32_16x16x32_bf16 v[96:99], v[218:221], v[0:3], v[202:205]
	v_mfma_f32_16x16x32_bf16 v[0:3], v[234:237], v[0:3], v[152:155]
	v_mfma_f32_16x16x32_bf16 v[100:103], v[238:241], v[4:7], v[0:3]
	v_mfma_f32_16x16x32_bf16 v[0:3], v[218:221], v[8:11], v[160:163]
	v_mfma_f32_16x16x32_bf16 v[104:107], v[230:233], v[12:15], v[0:3]
	v_mfma_f32_16x16x32_bf16 v[0:3], v[234:237], v[8:11], v[164:167]
	v_mfma_f32_16x16x32_bf16 v[108:111], v[238:241], v[12:15], v[0:3]
	v_mfma_f32_16x16x32_bf16 v[0:3], v[218:221], v[16:19], v[168:171]
	v_mfma_f32_16x16x32_bf16 v[112:115], v[230:233], v[20:23], v[0:3]
	v_mfma_f32_16x16x32_bf16 v[0:3], v[234:237], v[16:19], v[172:175]
	v_mfma_f32_16x16x32_bf16 v[116:119], v[238:241], v[20:23], v[0:3]
	v_mfma_f32_16x16x32_bf16 v[0:3], v[218:221], v[210:213], v[176:179]
	v_mfma_f32_16x16x32_bf16 v[120:123], v[230:233], v[214:217], v[0:3]
	v_mfma_f32_16x16x32_bf16 v[0:3], v[234:237], v[210:213], v[182:185]
	s_setprio 2
	s_barrier
	v_mfma_f32_16x16x32_bf16 v[96:99], v[230:233], v[4:7], v[96:99]
	v_mfma_f32_16x16x32_bf16 v[124:127], v[238:241], v[214:217], v[0:3]
	s_setprio 0
	ds_read_b128 v[152:155], v144 offset:49152
	ds_read_b128 v[160:163], v144 offset:50176
	ds_read_b128 v[164:167], v144 offset:51200
	ds_read_b128 v[168:171], v144 offset:52224
	ds_read_b128 v[172:175], v144 offset:53248
	ds_read_b128 v[176:179], v144 offset:54272
	ds_read_b128 v[182:185], v144 offset:55296
	ds_read_b128 v[144:147], v144 offset:56320
	s_barrier
	s_waitcnt lgkmcnt(0)
	s_setprio 1
	s_waitcnt lgkmcnt(0)
	v_mfma_f32_16x16x32_bf16 v[0:3], v[24:27], v[152:155], v[60:63]
	v_mfma_f32_16x16x32_bf16 v[8:11], v[24:27], v[164:167], v[52:55]
	v_mfma_f32_16x16x32_bf16 v[16:19], v[24:27], v[172:175], v[44:47]
	v_mfma_f32_16x16x32_bf16 v[24:27], v[24:27], v[182:185], v[36:39]
	v_mfma_f32_16x16x32_bf16 v[0:3], v[28:31], v[160:163], v[0:3]
	v_mfma_f32_16x16x32_bf16 v[4:7], v[194:197], v[152:155], v[56:59]
	v_mfma_f32_16x16x32_bf16 v[8:11], v[28:31], v[168:171], v[8:11]
	v_mfma_f32_16x16x32_bf16 v[12:15], v[194:197], v[164:167], v[48:51]
	v_mfma_f32_16x16x32_bf16 v[16:19], v[28:31], v[176:179], v[16:19]
	v_mfma_f32_16x16x32_bf16 v[20:23], v[194:197], v[172:175], v[40:43]
	v_mfma_f32_16x16x32_bf16 v[24:27], v[28:31], v[144:147], v[24:27]
	v_mfma_f32_16x16x32_bf16 v[28:31], v[194:197], v[182:185], v[32:35]
	v_mfma_f32_16x16x32_bf16 v[4:7], v[198:201], v[160:163], v[4:7]
	v_mfma_f32_16x16x32_bf16 v[12:15], v[198:201], v[168:171], v[12:15]
	v_mfma_f32_16x16x32_bf16 v[20:23], v[198:201], v[176:179], v[20:23]
	v_mfma_f32_16x16x32_bf16 v[28:31], v[198:201], v[144:147], v[28:31]
	s_setprio 0
	s_setprio 1
	v_mfma_f32_16x16x32_bf16 v[32:35], v[218:221], v[152:155], v[128:131]
	v_mfma_f32_16x16x32_bf16 v[36:39], v[234:237], v[152:155], v[132:135]
	v_mfma_f32_16x16x32_bf16 v[40:43], v[218:221], v[164:167], v[136:139]
	v_mfma_f32_16x16x32_bf16 v[44:47], v[234:237], v[164:167], v[148:151]
	v_mfma_f32_16x16x32_bf16 v[48:51], v[218:221], v[172:175], v[186:189]
	v_mfma_f32_16x16x32_bf16 v[52:55], v[234:237], v[172:175], v[206:209]
	v_mfma_f32_16x16x32_bf16 v[56:59], v[218:221], v[182:185], v[156:159]
	v_mfma_f32_16x16x32_bf16 v[60:63], v[234:237], v[182:185], v[190:193]
	v_mfma_f32_16x16x32_bf16 v[32:35], v[230:233], v[160:163], v[32:35]
	v_mfma_f32_16x16x32_bf16 v[36:39], v[238:241], v[160:163], v[36:39]
	v_mfma_f32_16x16x32_bf16 v[40:43], v[230:233], v[168:171], v[40:43]
	v_mfma_f32_16x16x32_bf16 v[44:47], v[238:241], v[168:171], v[44:47]
	v_mfma_f32_16x16x32_bf16 v[48:51], v[230:233], v[176:179], v[48:51]
	v_mfma_f32_16x16x32_bf16 v[52:55], v[238:241], v[176:179], v[52:55]
	s_setprio 2
	s_barrier
	v_mfma_f32_16x16x32_bf16 v[56:59], v[230:233], v[144:147], v[56:59]
	v_mfma_f32_16x16x32_bf16 v[60:63], v[238:241], v[144:147], v[60:63]
	s_setprio 0
	v_cmp_gt_u32_e32 vcc, s60, v142
	s_and_saveexec_b64 s[6:7], vcc
	s_cbranch_execz .LBB0_2625
	s_barrier
